# early acquire + sc1 write-through on plain dwordx4 global stores (less dirty L2 at the grid barrier release)
# baseline (speedup 1.0000x reference)
.LBB0_22:
	s_cmpk_gt_i32 s97, 0x17f
	s_mov_b64 s[14:15], -1
	s_barrier
	s_cbranch_scc0 .LBB0_114
	s_cmpk_gt_u32 s97, 0xb8f
	s_cbranch_scc0 .LBB0_48
	s_cmpk_lg_i32 s97, 0xe90
	s_cbranch_scc0 .LBB0_26
	s_cmpk_lt_u32 s97, 0xc10
	s_cselect_b64 s[0:1], -1, 0
	s_cmpk_lt_u32 s97, 0xc90
	s_cselect_b64 s[14:15], -1, 0
	s_and_b64 s[14:15], s[14:15], exec
	s_movk_i32 s2, 0xf3f0
	s_mov_b32 s14, 0xf882100
	s_cselect_b32 s2, s2, 0xfffff370
	s_cselect_b32 s16, 56, 32
	s_cselect_b32 s17, s14, 0xd440000
	s_and_b64 s[14:15], s[0:1], exec
	s_cselect_b32 s14, 16, s16
	v_readlane_b32 s18, v253, 0
	s_cselect_b32 s2, 0xfffff470, s2
	v_readlane_b32 s19, v253, 1
	s_add_u32 s14, s18, s14
	s_addc_u32 s15, s19, 0
	s_and_b64 s[0:1], s[0:1], exec
	s_cselect_b32 s0, 0xf682100, s17
	s_load_dwordx2 s[14:15], s[14:15], 0x0
	s_add_u32 s0, s40, s0
	s_addc_u32 s1, s41, 0
	s_add_i32 s16, s97, s2
	s_mov_b32 s17, s36
	s_lshl_b64 s[16:17], s[16:17], 12
	v_lshl_add_u64 v[8:9], s[16:17], 0, v[144:145]
	s_waitcnt lgkmcnt(0)
	v_lshl_add_u64 v[10:11], v[8:9], 2, s[14:15]
	global_load_dwordx4 v[0:3], v[10:11], off nt
	global_load_dwordx4 v[4:7], v[10:11], off offset:16 nt
	v_lshl_add_u64 v[8:9], v[8:9], 1, s[0:1]
	s_mov_b64 s[14:15], 0
	s_waitcnt vmcnt(1)
	v_cvt_pk_bf16_f32 v0, v0, v1
	v_cvt_pk_bf16_f32 v1, v2, v3
	s_waitcnt vmcnt(0)
	v_cvt_pk_bf16_f32 v2, v4, v5
	v_cvt_pk_bf16_f32 v3, v6, v7
	global_store_dwordx4 v[8:9], v[0:3], off sc1
	global_load_dwordx4 v[0:3], v[10:11], off offset:32 nt
	s_nop 0
	global_load_dwordx4 v[4:7], v[10:11], off offset:48 nt
	s_waitcnt vmcnt(1)
	v_cvt_pk_bf16_f32 v0, v0, v1
	v_cvt_pk_bf16_f32 v1, v2, v3
	s_waitcnt vmcnt(0)
	v_cvt_pk_bf16_f32 v2, v4, v5
	v_cvt_pk_bf16_f32 v3, v6, v7
	global_store_dwordx4 v[8:9], v[0:3], off offset:16 sc1

.LBB0_42:
	v_mov_b32_e32 v34, v0
	s_mov_b32 s37, s36
	v_add_u32_e32 v2, -2, v2
	s_mov_b32 s38, s36
	s_mov_b32 s39, s36
	v_lshl_add_u64 v[4:5], v[34:35], 4, s[54:55]
	v_mov_b32_e32 v34, v1
	v_mov_b64_e32 v[8:9], s[36:37]
	v_cmp_eq_u32_e32 vcc, 0, v2
	v_add_u32_e32 v0, 0x200, v0
	v_mov_b64_e32 v[10:11], s[38:39]
	v_add_u32_e32 v1, 0x200, v1
	v_lshl_add_u64 v[6:7], v[34:35], 4, s[54:55]
	s_or_b64 s[14:15], vcc, s[14:15]
	global_store_dwordx4 v[4:5], v[8:11], off sc1
	global_store_dwordx4 v[6:7], v[8:11], off sc1
	s_andn2_b64 exec, exec, s[14:15]
	s_cbranch_execnz .LBB0_42
	s_or_b64 exec, exec, s[14:15]
	s_and_saveexec_b64 s[14:15], s[6:7]
	s_cbranch_execz .LBB0_46
	s_mov_b64 s[16:17], 0
	v_mov_b64_e32 v[0:1], v[44:45]
	v_mov_b32_e32 v2, v60
.LBB0_45:
	v_add_u32_e32 v2, 0x100, v2
	s_movk_i32 s2, 0x1eff
	s_mov_b64 s[0:1], 0x1000
	v_cmp_lt_u32_e32 vcc, s2, v2
	global_store_dwordx4 v[0:1], v[72:75], off sc1
	s_or_b64 s[16:17], vcc, s[16:17]
	v_lshl_add_u64 v[0:1], v[0:1], 0, s[0:1]
	s_andn2_b64 exec, exec, s[16:17]
	s_cbranch_execnz .LBB0_45

.LBB0_97:
	s_or_b64 exec, exec, s[38:39]
	s_waitcnt vmcnt(0)
	ds_write2_b32 v65, v4, v5 offset1:1
	ds_write2_b32 v65, v6, v7 offset0:2 offset1:3
	v_add_u32_e32 v4, 0x1040, v65
	ds_write2_b32 v4, v0, v1 offset1:1
	v_add_u32_e32 v0, 0x1048, v65
	ds_write2_b32 v0, v2, v3 offset1:1
	v_add_u32_e32 v0, 0x2080, v65
	ds_write2_b32 v0, v12, v13 offset1:1
	v_add_u32_e32 v0, 0x2088, v65
	ds_write2_b32 v0, v14, v15 offset1:1
	v_add_u32_e32 v0, 0x30c0, v65
	ds_write2_b32 v0, v8, v9 offset1:1
	v_add_u32_e32 v0, 0x30c8, v65
	ds_write2_b32 v0, v10, v11 offset1:1
	v_add_u32_e32 v0, 0x4100, v65
	ds_write2_b32 v0, v20, v21 offset1:1
	v_add_u32_e32 v0, 0x4108, v65
	ds_write2_b32 v0, v22, v23 offset1:1
	v_add_u32_e32 v0, 0x5140, v65
	ds_write2_b32 v0, v16, v17 offset1:1
	v_add_u32_e32 v0, 0x5148, v65
	ds_write2_b32 v0, v18, v19 offset1:1
	v_add_u32_e32 v0, 0x6180, v65
	ds_write2_b32 v0, v28, v29 offset1:1
	v_add_u32_e32 v0, 0x6188, v65
	ds_write2_b32 v0, v30, v31 offset1:1
	v_add_u32_e32 v0, 0x71c0, v65
	ds_write2_b32 v0, v24, v25 offset1:1
	v_add_u32_e32 v0, 0x71c8, v65
	v_add_u32_e32 v8, 0x400, v55
	ds_write2_b32 v0, v26, v27 offset1:1
	s_waitcnt lgkmcnt(0)
	s_barrier
	ds_read2_b32 v[0:1], v55 offset1:65
	ds_read2_b32 v[2:3], v55 offset0:130 offset1:195
	ds_read2_b32 v[4:5], v8 offset0:4 offset1:69
	ds_read2_b32 v[6:7], v8 offset0:134 offset1:199
	s_xor_b64 s[38:39], s[18:19], -1
	s_lshl_b32 s0, s33, 1
	s_add_u32 s18, s14, s0
	s_waitcnt lgkmcnt(3)
	v_cvt_pk_bf16_f32 v0, v0, v1
	s_waitcnt lgkmcnt(2)
	v_cvt_pk_bf16_f32 v1, v2, v3
	s_waitcnt lgkmcnt(0)
	v_cvt_pk_bf16_f32 v3, v6, v7
	v_add_u32_e32 v7, s2, v149
	s_addc_u32 s19, s15, 0
	v_cvt_pk_bf16_f32 v2, v4, v5
	v_mad_u64_u32 v[4:5], s[14:15], s16, v7, 0
	v_mov_b32_e32 v6, v5
	v_mad_u64_u32 v[6:7], s[14:15], s17, v7, v[6:7]
	v_mov_b32_e32 v5, v6
	v_lshl_add_u64 v[6:7], v[4:5], 1, s[18:19]
	s_mov_b64 s[14:15], -1
	s_and_b64 vcc, exec, s[38:39]
	v_lshlrev_b32_e32 v4, 1, v36
	s_cbranch_vccz .LBB0_99
	v_mov_b32_e32 v5, v35
	v_lshl_add_u64 v[10:11], v[6:7], 0, v[4:5]
	global_store_dwordx4 v[10:11], v[0:3], off sc1
	s_mov_b64 s[14:15], 0

.LBB0_101:
	ds_read2_b32 v[0:1], v55 offset0:32 offset1:97
	ds_read2_b32 v[2:3], v55 offset0:162 offset1:227
	ds_read2_b32 v[6:7], v8 offset0:36 offset1:101
	ds_read2_b32 v[8:9], v8 offset0:166 offset1:231
	v_add_u32_e32 v5, s2, v56
	s_waitcnt lgkmcnt(3)
	v_cvt_pk_bf16_f32 v0, v0, v1
	s_waitcnt lgkmcnt(2)
	v_cvt_pk_bf16_f32 v1, v2, v3
	s_waitcnt lgkmcnt(1)
	v_cvt_pk_bf16_f32 v2, v6, v7
	v_mad_u64_u32 v[6:7], s[14:15], s16, v5, 0
	s_waitcnt lgkmcnt(0)
	v_cvt_pk_bf16_f32 v3, v8, v9
	v_mov_b32_e32 v8, v7
	v_mad_u64_u32 v[8:9], s[14:15], s17, v5, v[8:9]
	v_mov_b32_e32 v7, v8
	v_cndmask_b32_e64 v5, 0, 1, s[38:39]
	v_lshl_add_u64 v[6:7], v[6:7], 1, s[18:19]
	v_cmp_ne_u32_e64 s[14:15], 1, v5
	s_andn2_b64 vcc, exec, s[38:39]
	s_mov_b64 s[38:39], -1
	s_cbranch_vccnz .LBB0_103
	v_mov_b32_e32 v5, v35
	v_lshl_add_u64 v[8:9], v[6:7], 0, v[4:5]
	s_mov_b64 s[38:39], 0
	global_store_dwordx4 v[8:9], v[0:3], off sc1

.LBB0_105:
	v_add_u32_e32 v8, 0x4000, v55
	v_add_u32_e32 v9, 0x4200, v55
	v_add_u32_e32 v10, 0x4400, v55
	ds_read2_b32 v[0:1], v8 offset0:64 offset1:129
	ds_read2_b32 v[2:3], v9 offset0:66 offset1:131
	ds_read2_b32 v[6:7], v10 offset0:68 offset1:133
	v_add_u32_e32 v11, 0x4600, v55
	ds_read2_b32 v[12:13], v11 offset0:70 offset1:135
	v_add_u32_e32 v5, s1, v149
	s_waitcnt lgkmcnt(3)
	v_cvt_pk_bf16_f32 v0, v0, v1
	s_waitcnt lgkmcnt(2)
	v_cvt_pk_bf16_f32 v1, v2, v3
	s_waitcnt lgkmcnt(1)
	v_cvt_pk_bf16_f32 v2, v6, v7
	v_mad_u64_u32 v[6:7], s[38:39], s16, v5, 0
	s_waitcnt lgkmcnt(0)
	v_cvt_pk_bf16_f32 v3, v12, v13
	v_mov_b32_e32 v12, v7
	v_mad_u64_u32 v[12:13], s[38:39], s17, v5, v[12:13]
	v_mov_b32_e32 v7, v12
	v_lshl_add_u64 v[6:7], v[6:7], 1, s[18:19]
	s_and_b64 vcc, exec, s[14:15]
	s_mov_b64 s[38:39], -1
	s_cbranch_vccnz .LBB0_107
	v_mov_b32_e32 v5, v35
	v_lshl_add_u64 v[12:13], v[6:7], 0, v[4:5]
	s_mov_b64 s[38:39], 0
	global_store_dwordx4 v[12:13], v[0:3], off sc1

.LBB0_109:
	ds_read2_b32 v[0:1], v8 offset0:96 offset1:161
	ds_read2_b32 v[2:3], v9 offset0:98 offset1:163
	ds_read2_b32 v[6:7], v10 offset0:100 offset1:165
	ds_read2_b32 v[8:9], v11 offset0:102 offset1:167
	v_add_u32_e32 v5, s1, v56
	s_waitcnt lgkmcnt(3)
	v_cvt_pk_bf16_f32 v0, v0, v1
	s_waitcnt lgkmcnt(2)
	v_cvt_pk_bf16_f32 v1, v2, v3
	s_waitcnt lgkmcnt(1)
	v_cvt_pk_bf16_f32 v2, v6, v7
	v_mad_u64_u32 v[6:7], s[0:1], s16, v5, 0
	s_waitcnt lgkmcnt(0)
	v_cvt_pk_bf16_f32 v3, v8, v9
	v_mov_b32_e32 v8, v7
	v_mad_u64_u32 v[8:9], s[0:1], s17, v5, v[8:9]
	v_mov_b32_e32 v7, v8
	v_lshl_add_u64 v[6:7], v[6:7], 1, s[18:19]
	s_and_b64 vcc, exec, s[14:15]
	s_mov_b64 s[14:15], -1
	s_cbranch_vccnz .LBB0_111
	v_mov_b32_e32 v5, v35
	v_lshl_add_u64 v[4:5], v[6:7], 0, v[4:5]
	s_mov_b64 s[14:15], 0
	global_store_dwordx4 v[4:5], v[0:3], off sc1

.LBB0_298:
	s_and_b64 vcc, exec, s[6:7]
	s_cbranch_vccz .LBB0_300
	s_waitcnt vmcnt(7)
	v_cvt_pk_bf16_f32 v64, v0, s0
	ds_write_b16 v168, v64
	v_cvt_pk_bf16_f32 v64, v1, s0
	ds_write_b16 v168, v64 offset:144
	v_cvt_pk_bf16_f32 v64, v2, s0
	ds_write_b16 v168, v64 offset:288
	v_cvt_pk_bf16_f32 v64, v3, s0
	ds_write_b16 v168, v64 offset:432
	v_cvt_pk_bf16_f32 v64, v4, s0
	ds_write_b16 v168, v64 offset:2304
	v_cvt_pk_bf16_f32 v64, v5, s0
	ds_write_b16 v168, v64 offset:2448
	v_cvt_pk_bf16_f32 v64, v6, s0
	ds_write_b16 v168, v64 offset:2592
	v_cvt_pk_bf16_f32 v64, v7, s0
	ds_write_b16 v168, v64 offset:2736
	v_cvt_pk_bf16_f32 v64, v8, s0
	ds_write_b16 v168, v64 offset:4608
	v_cvt_pk_bf16_f32 v64, v9, s0
	ds_write_b16 v168, v64 offset:4752
	v_cvt_pk_bf16_f32 v64, v10, s0
	ds_write_b16 v168, v64 offset:4896
	v_cvt_pk_bf16_f32 v64, v11, s0
	ds_write_b16 v168, v64 offset:5040
	v_cvt_pk_bf16_f32 v64, v12, s0
	ds_write_b16 v168, v64 offset:6912
	v_cvt_pk_bf16_f32 v64, v13, s0
	ds_write_b16 v168, v64 offset:7056
	v_cvt_pk_bf16_f32 v64, v14, s0
	ds_write_b16 v168, v64 offset:7200
	v_cvt_pk_bf16_f32 v64, v15, s0
	ds_write_b16 v168, v64 offset:7344
	v_cvt_pk_bf16_f32 v64, v16, s0
	ds_write_b16 v168, v64 offset:8
	v_cvt_pk_bf16_f32 v64, v17, s0
	ds_write_b16 v168, v64 offset:152
	v_cvt_pk_bf16_f32 v64, v18, s0
	ds_write_b16 v168, v64 offset:296
	v_cvt_pk_bf16_f32 v64, v19, s0
	ds_write_b16 v168, v64 offset:440
	v_cvt_pk_bf16_f32 v64, v20, s0
	ds_write_b16 v168, v64 offset:2312
	v_cvt_pk_bf16_f32 v64, v21, s0
	ds_write_b16 v168, v64 offset:2456
	v_cvt_pk_bf16_f32 v64, v22, s0
	ds_write_b16 v168, v64 offset:2600
	v_cvt_pk_bf16_f32 v64, v23, s0
	ds_write_b16 v168, v64 offset:2744
	v_cvt_pk_bf16_f32 v64, v24, s0
	ds_write_b16 v168, v64 offset:4616
	v_cvt_pk_bf16_f32 v64, v25, s0
	ds_write_b16 v168, v64 offset:4760
	v_cvt_pk_bf16_f32 v64, v26, s0
	ds_write_b16 v168, v64 offset:4904
	v_cvt_pk_bf16_f32 v64, v27, s0
	ds_write_b16 v168, v64 offset:5048
	v_cvt_pk_bf16_f32 v64, v28, s0
	ds_write_b16 v168, v64 offset:6920
	v_cvt_pk_bf16_f32 v64, v29, s0
	ds_write_b16 v168, v64 offset:7064
	v_cvt_pk_bf16_f32 v64, v30, s0
	ds_write_b16 v168, v64 offset:7208
	v_cvt_pk_bf16_f32 v64, v31, s0
	ds_write_b16 v168, v64 offset:7352
	v_cvt_pk_bf16_f32 v64, v32, s0
	ds_write_b16 v168, v64 offset:64
	v_cvt_pk_bf16_f32 v64, v33, s0
	ds_write_b16 v168, v64 offset:208
	v_cvt_pk_bf16_f32 v64, v34, s0
	ds_write_b16 v168, v64 offset:352
	v_cvt_pk_bf16_f32 v64, v35, s0
	ds_write_b16 v168, v64 offset:496
	v_cvt_pk_bf16_f32 v64, v36, s0
	ds_write_b16 v168, v64 offset:2368
	v_cvt_pk_bf16_f32 v64, v37, s0
	ds_write_b16 v168, v64 offset:2512
	v_cvt_pk_bf16_f32 v64, v38, s0
	ds_write_b16 v168, v64 offset:2656
	v_cvt_pk_bf16_f32 v64, v39, s0
	ds_write_b16 v168, v64 offset:2800
	v_cvt_pk_bf16_f32 v64, v40, s0
	ds_write_b16 v168, v64 offset:4672
	v_cvt_pk_bf16_f32 v64, v41, s0
	ds_write_b16 v168, v64 offset:4816
	v_cvt_pk_bf16_f32 v64, v42, s0
	ds_write_b16 v168, v64 offset:4960
	v_cvt_pk_bf16_f32 v64, v43, s0
	ds_write_b16 v168, v64 offset:5104
	v_cvt_pk_bf16_f32 v64, v44, s0
	ds_write_b16 v168, v64 offset:6976
	v_cvt_pk_bf16_f32 v64, v45, s0
	ds_write_b16 v168, v64 offset:7120
	v_cvt_pk_bf16_f32 v64, v46, s0
	ds_write_b16 v168, v64 offset:7264
	v_cvt_pk_bf16_f32 v64, v47, s0
	ds_write_b16 v168, v64 offset:7408
	v_cvt_pk_bf16_f32 v64, v48, s0
	ds_write_b16 v168, v64 offset:72
	v_cvt_pk_bf16_f32 v64, v49, s0
	ds_write_b16 v168, v64 offset:216
	v_cvt_pk_bf16_f32 v64, v50, s0
	ds_write_b16 v168, v64 offset:360
	v_cvt_pk_bf16_f32 v64, v51, s0
	ds_write_b16 v168, v64 offset:504
	v_cvt_pk_bf16_f32 v64, v52, s0
	ds_write_b16 v168, v64 offset:2376
	v_cvt_pk_bf16_f32 v64, v53, s0
	ds_write_b16 v168, v64 offset:2520
	v_cvt_pk_bf16_f32 v64, v54, s0
	ds_write_b16 v168, v64 offset:2664
	v_cvt_pk_bf16_f32 v64, v55, s0
	ds_write_b16 v168, v64 offset:2808
	v_cvt_pk_bf16_f32 v64, v56, s0
	ds_write_b16 v168, v64 offset:4680
	v_cvt_pk_bf16_f32 v64, v57, s0
	ds_write_b16 v168, v64 offset:4824
	v_cvt_pk_bf16_f32 v64, v58, s0
	ds_write_b16 v168, v64 offset:4968
	v_cvt_pk_bf16_f32 v64, v59, s0
	ds_write_b16 v168, v64 offset:5112
	v_cvt_pk_bf16_f32 v64, v60, s0
	ds_write_b16 v168, v64 offset:6984
	v_cvt_pk_bf16_f32 v64, v61, s0
	ds_write_b16 v168, v64 offset:7128
	v_cvt_pk_bf16_f32 v64, v62, s0
	ds_write_b16 v168, v64 offset:7272
	v_cvt_pk_bf16_f32 v64, v63, s0
	ds_write_b16 v168, v64 offset:7416
	s_waitcnt lgkmcnt(0)
	ds_read_b128 v[64:67], v163
	s_waitcnt vmcnt(3)
	v_add_u32_e32 v76, 0xfffffb00, v138
	s_lshl_b32 s22, s34, 1
	v_or_b32_e32 v68, v76, v236
	v_lshl_add_u64 v[72:73], v[134:135], 0, s[22:23]
	v_lshlrev_b32_e32 v128, 14, v68
	ds_read_b128 v[68:71], v163 offset:1152
	v_lshl_add_u64 v[74:75], v[72:73], 0, v[128:129]
	s_waitcnt lgkmcnt(1)
	global_store_dwordx4 v[74:75], v[64:67], off sc1
	v_mov_b64_e32 v[82:83], v[18:19]
	s_waitcnt vmcnt(3)
	v_mov_b64_e32 v[86:87], v[22:23]
	v_or_b32_e32 v64, v76, v237
	v_lshlrev_b32_e32 v128, 14, v64
	v_lshl_add_u64 v[64:65], v[72:73], 0, v[128:129]
	s_waitcnt lgkmcnt(0)
	global_store_dwordx4 v[64:65], v[68:71], off sc1
	ds_read_b128 v[64:67], v163 offset:2304
	s_waitcnt vmcnt(3)
	v_mov_b64_e32 v[90:91], v[26:27]
	v_or_b32_e32 v68, v76, v238
	v_lshlrev_b32_e32 v128, 14, v68
	ds_read_b128 v[68:71], v163 offset:3456
	v_lshl_add_u64 v[74:75], v[72:73], 0, v[128:129]
	s_waitcnt lgkmcnt(1)
	global_store_dwordx4 v[74:75], v[64:67], off sc1
	s_waitcnt vmcnt(3)
	v_mov_b64_e32 v[94:95], v[30:31]
	v_mov_b64_e32 v[98:99], v[34:35]
	v_or_b32_e32 v64, v76, v239
	v_lshlrev_b32_e32 v128, 14, v64
	v_lshl_add_u64 v[64:65], v[72:73], 0, v[128:129]
	s_waitcnt lgkmcnt(0)
	global_store_dwordx4 v[64:65], v[68:71], off sc1
	ds_read_b128 v[64:67], v163 offset:4608
	v_mov_b64_e32 v[102:103], v[38:39]
	v_or_b32_e32 v68, v76, v240
	v_lshlrev_b32_e32 v128, 14, v68
	ds_read_b128 v[68:71], v163 offset:5760
	v_lshl_add_u64 v[74:75], v[72:73], 0, v[128:129]
	s_waitcnt lgkmcnt(1)
	global_store_dwordx4 v[74:75], v[64:67], off sc1
	v_mov_b64_e32 v[106:107], v[42:43]
	v_mov_b64_e32 v[110:111], v[46:47]
	v_or_b32_e32 v64, v76, v241
	v_lshlrev_b32_e32 v128, 14, v64
	v_lshl_add_u64 v[64:65], v[72:73], 0, v[128:129]
	s_waitcnt lgkmcnt(0)
	global_store_dwordx4 v[64:65], v[68:71], off sc1
	ds_read_b128 v[64:67], v163 offset:6912
	v_mov_b64_e32 v[114:115], v[50:51]
	v_or_b32_e32 v68, v76, v242
	v_lshlrev_b32_e32 v128, 14, v68
	ds_read_b128 v[68:71], v163 offset:8064
	v_lshl_add_u64 v[74:75], v[72:73], 0, v[128:129]
	s_waitcnt lgkmcnt(1)
	global_store_dwordx4 v[74:75], v[64:67], off sc1
	v_mov_b64_e32 v[118:119], v[54:55]
	v_mov_b64_e32 v[122:123], v[58:59]
	v_or_b32_e32 v64, v76, v243
	v_lshlrev_b32_e32 v128, 14, v64
	v_lshl_add_u64 v[64:65], v[72:73], 0, v[128:129]
	s_waitcnt lgkmcnt(0)
	global_store_dwordx4 v[64:65], v[68:71], off sc1
	v_mov_b64_e32 v[66:67], v[2:3]
	v_mov_b64_e32 v[74:75], v[10:11]
	v_mov_b64_e32 v[70:71], v[6:7]
	v_mov_b64_e32 v[78:79], v[14:15]
	v_mov_b64_e32 v[126:127], v[62:63]
	v_mov_b64_e32 v[64:65], v[0:1]
	v_mov_b64_e32 v[68:69], v[4:5]
	v_mov_b64_e32 v[72:73], v[8:9]
	v_mov_b64_e32 v[76:77], v[12:13]
	v_mov_b64_e32 v[80:81], v[16:17]
	v_mov_b64_e32 v[84:85], v[20:21]
	v_mov_b64_e32 v[88:89], v[24:25]
	v_mov_b64_e32 v[92:93], v[28:29]
	v_mov_b64_e32 v[96:97], v[32:33]
	v_mov_b64_e32 v[100:101], v[36:37]
	v_mov_b64_e32 v[104:105], v[40:41]
	v_mov_b64_e32 v[108:109], v[44:45]
	v_mov_b64_e32 v[112:113], v[48:49]
	v_mov_b64_e32 v[116:117], v[52:53]
	v_mov_b64_e32 v[120:121], v[56:57]
	v_mov_b64_e32 v[124:125], v[60:61]

.LBB0_463:
	s_add_i32 s42, s43, 2
	s_cmp_lt_u32 s43, 14
	s_cselect_b32 s44, s2, 0x700
	s_min_u32 s26, s43, 12
	s_lshl_b32 s26, s26, 7
	s_addk_i32 s2, 0x100
	s_ashr_i32 s45, s44, 31
	s_addk_i32 s26, 0x180
	s_cmp_gt_u32 s43, 13
	s_setprio 1
	ds_read_b128 v[126:129], v120 offset:32768
	ds_read_b128 v[134:137], v120 offset:34816
	ds_read_b128 v[130:133], v119
	ds_read_b128 v[138:141], v119 offset:2048
	ds_read_b128 v[164:167], v119 offset:4096
	ds_read_b128 v[168:171], v119 offset:6144
	v_add_u32_e32 v99, s44, v96
	v_add_u32_e32 v142, 0x10000, v99
	s_waitcnt lgkmcnt(3)
	v_mfma_f32_16x16x32_bf16 v[60:63], v[126:129], v[130:133], v[60:63]
	ds_read_b128 v[172:175], v120 offset:36864
	v_mfma_f32_16x16x32_bf16 v[40:43], v[134:137], v[130:133], v[40:43]
	ds_read_b128 v[176:179], v120 offset:38912
	s_waitcnt lgkmcnt(1)
	v_mfma_f32_16x16x32_bf16 v[28:31], v[172:175], v[130:133], v[28:31]
	s_waitcnt lgkmcnt(0)
	v_mfma_f32_16x16x32_bf16 v[12:15], v[176:179], v[130:133], v[12:15]
	v_lshl_add_u64 v[130:131], v[100:101], 0, s[44:45]
	global_load_dwordx4 v[130:133], v[130:131], off
	ds_read_b128 v[180:183], v121
	v_mfma_f32_16x16x32_bf16 v[56:59], v[126:129], v[138:141], v[56:59]
	v_mfma_f32_16x16x32_bf16 v[44:47], v[134:137], v[138:141], v[44:47]
	global_load_dwordx4 v[184:187], v142, s[16:17]
	ds_read_b128 v[188:191], v121 offset:2048
	v_mfma_f32_16x16x32_bf16 v[24:27], v[172:175], v[138:141], v[24:27]
	v_mfma_f32_16x16x32_bf16 v[8:11], v[176:179], v[138:141], v[8:11]
	v_add_u32_e32 v138, 0x20000, v99
	v_add_u32_e32 v99, 0x30000, v99
	global_load_dwordx4 v[138:141], v138, s[16:17]
	ds_read_b128 v[192:195], v121 offset:4096
	v_mfma_f32_16x16x32_bf16 v[52:55], v[126:129], v[164:167], v[52:55]
	v_mfma_f32_16x16x32_bf16 v[36:39], v[134:137], v[164:167], v[36:39]
	global_load_dwordx4 v[196:199], v99, s[16:17]
	v_add_u32_e32 v99, s44, v98
	ds_read_b128 v[200:203], v121 offset:6144
	v_mfma_f32_16x16x32_bf16 v[20:23], v[172:175], v[164:167], v[20:23]
	v_add_u32_e32 v142, 0x20000, v99
	v_mfma_f32_16x16x32_bf16 v[4:7], v[176:179], v[164:167], v[4:7]
	global_load_dwordx4 v[164:167], v99, s[14:15]
	ds_read_b128 v[204:207], v122 offset:32768
	v_mfma_f32_16x16x32_bf16 v[48:51], v[126:129], v[168:171], v[48:51]
	v_add_u32_e32 v126, 0x10000, v99
	v_add_u32_e32 v99, 0x30000, v99
	v_mfma_f32_16x16x32_bf16 v[32:35], v[134:137], v[168:171], v[32:35]
	global_load_dwordx4 v[126:129], v126, s[14:15]
	ds_read_b128 v[134:137], v122 offset:34816
	v_mfma_f32_16x16x32_bf16 v[16:19], v[172:175], v[168:171], v[16:19]
	v_mfma_f32_16x16x32_bf16 v[0:3], v[176:179], v[168:171], v[0:3]
	global_load_dwordx4 v[168:171], v142, s[14:15]
	ds_read_b128 v[172:175], v122 offset:36864
	s_waitcnt lgkmcnt(2)
	v_mfma_f32_16x16x32_bf16 v[60:63], v[204:207], v[180:183], v[60:63]
	s_waitcnt lgkmcnt(1)
	v_mfma_f32_16x16x32_bf16 v[40:43], v[134:137], v[180:183], v[40:43]
	global_load_dwordx4 v[176:179], v99, s[14:15]
	ds_read_b128 v[208:211], v122 offset:38912
	s_waitcnt lgkmcnt(1)
	v_mfma_f32_16x16x32_bf16 v[28:31], v[172:175], v[180:183], v[28:31]
	s_waitcnt lgkmcnt(0)
	v_mfma_f32_16x16x32_bf16 v[12:15], v[208:211], v[180:183], v[12:15]
	s_waitcnt vmcnt(14)
	ds_write_b128 v117, v[64:67] offset:16384
	v_mfma_f32_16x16x32_bf16 v[56:59], v[204:207], v[188:191], v[56:59]
	v_mfma_f32_16x16x32_bf16 v[44:47], v[134:137], v[188:191], v[44:47]
	s_waitcnt vmcnt(13)
	ds_write_b128 v117, v[68:71] offset:20480
	v_mfma_f32_16x16x32_bf16 v[24:27], v[172:175], v[188:191], v[24:27]
	v_mfma_f32_16x16x32_bf16 v[8:11], v[208:211], v[188:191], v[8:11]
	s_waitcnt vmcnt(12)
	ds_write_b128 v117, v[72:75] offset:24576
	v_mfma_f32_16x16x32_bf16 v[52:55], v[204:207], v[192:195], v[52:55]
	v_mfma_f32_16x16x32_bf16 v[36:39], v[134:137], v[192:195], v[36:39]
	s_waitcnt vmcnt(11)
	ds_write_b128 v117, v[80:83] offset:28672
	v_mfma_f32_16x16x32_bf16 v[20:23], v[172:175], v[192:195], v[20:23]
	v_mfma_f32_16x16x32_bf16 v[4:7], v[208:211], v[192:195], v[4:7]
	ds_write_b128 v117, v[76:79] offset:49152
	v_mfma_f32_16x16x32_bf16 v[48:51], v[204:207], v[200:203], v[48:51]
	v_mfma_f32_16x16x32_bf16 v[32:35], v[134:137], v[200:203], v[32:35]
	s_waitcnt vmcnt(10)
	ds_write_b128 v117, v[84:87] offset:53248
	v_mfma_f32_16x16x32_bf16 v[16:19], v[172:175], v[200:203], v[16:19]
	v_mfma_f32_16x16x32_bf16 v[0:3], v[208:211], v[200:203], v[0:3]
	s_waitcnt vmcnt(9)
	ds_write_b128 v117, v[88:91] offset:57344
	s_waitcnt vmcnt(8)
	ds_write_b128 v117, v[92:95] offset:61440
	s_setprio 0
	s_waitcnt lgkmcnt(0)
	s_barrier
	s_setprio 1
	ds_read_b128 v[84:87], v120 offset:49152
	ds_read_b128 v[88:91], v120 offset:51200
	ds_read_b128 v[64:67], v119 offset:16384
	ds_read_b128 v[72:75], v119 offset:18432
	ds_read_b128 v[76:79], v119 offset:20480
	ds_read_b128 v[92:95], v119 offset:22528
	v_lshl_add_u64 v[68:69], v[110:111], 0, s[26:27]
	v_lshl_add_u64 v[80:81], v[114:115], 0, s[26:27]
	s_waitcnt lgkmcnt(3)
	v_mfma_f32_16x16x32_bf16 v[60:63], v[84:87], v[64:67], v[60:63]
	ds_read_b128 v[134:137], v120 offset:53248
	v_mfma_f32_16x16x32_bf16 v[40:43], v[88:91], v[64:67], v[40:43]
	ds_read_b128 v[172:175], v120 offset:55296
	s_waitcnt lgkmcnt(1)
	v_mfma_f32_16x16x32_bf16 v[28:31], v[134:137], v[64:67], v[28:31]
	s_waitcnt lgkmcnt(0)
	v_mfma_f32_16x16x32_bf16 v[12:15], v[172:175], v[64:67], v[12:15]
	v_lshl_add_u64 v[64:65], v[100:101], 0, s[26:27]
	global_load_dwordx4 v[64:67], v[64:65], off
	ds_read_b128 v[180:183], v121 offset:16384
	v_mfma_f32_16x16x32_bf16 v[56:59], v[84:87], v[72:75], v[56:59]
	v_mfma_f32_16x16x32_bf16 v[44:47], v[88:91], v[72:75], v[44:47]
	global_load_dwordx4 v[68:71], v[68:69], off
	ds_read_b128 v[188:191], v121 offset:18432
	v_mfma_f32_16x16x32_bf16 v[24:27], v[134:137], v[72:75], v[24:27]
	v_mfma_f32_16x16x32_bf16 v[8:11], v[172:175], v[72:75], v[8:11]
	v_lshl_add_u64 v[72:73], v[112:113], 0, s[26:27]
	global_load_dwordx4 v[72:75], v[72:73], off
	ds_read_b128 v[192:195], v121 offset:20480
	v_mfma_f32_16x16x32_bf16 v[52:55], v[84:87], v[76:79], v[52:55]
	v_mfma_f32_16x16x32_bf16 v[36:39], v[88:91], v[76:79], v[36:39]
	global_load_dwordx4 v[80:83], v[80:81], off
	ds_read_b128 v[200:203], v121 offset:22528
	v_mfma_f32_16x16x32_bf16 v[20:23], v[134:137], v[76:79], v[20:23]
	v_mfma_f32_16x16x32_bf16 v[4:7], v[172:175], v[76:79], v[4:7]
	v_lshl_add_u64 v[76:77], v[102:103], 0, s[26:27]
	global_load_dwordx4 v[76:79], v[76:77], off
	ds_read_b128 v[204:207], v122 offset:49152
	v_mfma_f32_16x16x32_bf16 v[48:51], v[84:87], v[92:95], v[48:51]
	v_lshl_add_u64 v[84:85], v[104:105], 0, s[26:27]
	v_mfma_f32_16x16x32_bf16 v[32:35], v[88:91], v[92:95], v[32:35]
	global_load_dwordx4 v[84:87], v[84:85], off
	ds_read_b128 v[208:211], v122 offset:51200
	v_lshl_add_u64 v[88:89], v[106:107], 0, s[26:27]
	v_mfma_f32_16x16x32_bf16 v[16:19], v[134:137], v[92:95], v[16:19]
	v_mfma_f32_16x16x32_bf16 v[0:3], v[172:175], v[92:95], v[0:3]
	v_lshl_add_u64 v[92:93], v[108:109], 0, s[26:27]
	global_load_dwordx4 v[88:91], v[88:89], off
	ds_read_b128 v[134:137], v122 offset:53248
	s_waitcnt lgkmcnt(2)
	v_mfma_f32_16x16x32_bf16 v[60:63], v[204:207], v[180:183], v[60:63]
	s_waitcnt lgkmcnt(1)
	v_mfma_f32_16x16x32_bf16 v[40:43], v[208:211], v[180:183], v[40:43]
	global_load_dwordx4 v[92:95], v[92:93], off
	ds_read_b128 v[172:175], v122 offset:55296
	s_waitcnt lgkmcnt(1)
	v_mfma_f32_16x16x32_bf16 v[28:31], v[134:137], v[180:183], v[28:31]
	s_waitcnt lgkmcnt(0)
	v_mfma_f32_16x16x32_bf16 v[12:15], v[172:175], v[180:183], v[12:15]
	s_waitcnt vmcnt(15)
	ds_write_b128 v117, v[130:133]
	v_mfma_f32_16x16x32_bf16 v[56:59], v[204:207], v[188:191], v[56:59]
	v_mfma_f32_16x16x32_bf16 v[44:47], v[208:211], v[188:191], v[44:47]
	s_waitcnt vmcnt(14)
	ds_write_b128 v117, v[184:187] offset:4096
	v_mfma_f32_16x16x32_bf16 v[24:27], v[134:137], v[188:191], v[24:27]
	v_mfma_f32_16x16x32_bf16 v[8:11], v[172:175], v[188:191], v[8:11]
	s_waitcnt vmcnt(13)
	ds_write_b128 v117, v[138:141] offset:8192
	v_mfma_f32_16x16x32_bf16 v[52:55], v[204:207], v[192:195], v[52:55]
	v_mfma_f32_16x16x32_bf16 v[36:39], v[208:211], v[192:195], v[36:39]
	s_waitcnt vmcnt(12)
	ds_write_b128 v117, v[196:199] offset:12288
	v_mfma_f32_16x16x32_bf16 v[20:23], v[134:137], v[192:195], v[20:23]
	v_mfma_f32_16x16x32_bf16 v[4:7], v[172:175], v[192:195], v[4:7]
	s_waitcnt vmcnt(11)
	ds_write_b128 v117, v[164:167] offset:32768
	v_mfma_f32_16x16x32_bf16 v[48:51], v[204:207], v[200:203], v[48:51]
	v_mfma_f32_16x16x32_bf16 v[32:35], v[208:211], v[200:203], v[32:35]
	s_waitcnt vmcnt(10)
	ds_write_b128 v117, v[126:129] offset:36864
	v_mfma_f32_16x16x32_bf16 v[16:19], v[134:137], v[200:203], v[16:19]
	v_mfma_f32_16x16x32_bf16 v[0:3], v[172:175], v[200:203], v[0:3]
	s_waitcnt vmcnt(9)
	ds_write_b128 v117, v[168:171] offset:40960
	s_waitcnt vmcnt(8)
	ds_write_b128 v117, v[176:179] offset:45056
	s_setprio 0
	s_mov_b32 s43, s42
	s_waitcnt lgkmcnt(0)
	s_barrier
	s_cbranch_scc0 .LBB0_463
	s_waitcnt vmcnt(6)
	v_add_u32_e32 v70, s1, v118
	s_addk_i32 s1, 0xf000
	s_ashr_i32 s1, s1, 10
	s_add_i32 s1, s1, 1
	s_and_b64 s[42:43], s[20:21], exec
	s_cselect_b32 s1, 0, s1
	s_mul_i32 s26, s1, 0x3000
	s_mul_hi_i32 s2, s1, 0x3000
	s_add_u32 s42, s4, s26
	s_addc_u32 s2, s5, s2
	v_or_b32_e32 v98, v70, v148
	s_add_u32 s44, s42, 0x2000
	s_addc_u32 s45, s2, 0
	s_add_i32 s1, s1, 5
	s_add_i32 s26, s26, 0xf000
	v_add_u32_e32 v66, 0xfffff000, v98
	v_mov_b32_e32 v67, v97
	s_mul_hi_u32 s1, s1, 0x3000
	s_add_u32 s2, s4, s26
	s_waitcnt vmcnt(5)
	v_lshlrev_b32_e32 v72, 12, v98
	v_mov_b32_e32 v73, v97
	v_lshlrev_b64 v[66:67], 12, v[66:67]
	s_addc_u32 s1, s5, s1
	v_or_b32_e32 v96, s0, v123
	v_lshl_add_u64 v[64:65], s[8:9], 0, v[72:73]
	v_lshl_add_u64 v[66:67], s[10:11], 0, v[66:67]
	v_cmp_gt_u32_e32 vcc, s48, v70
	s_add_u32 s42, s2, 0x1000
	s_waitcnt vmcnt(0)
	v_lshlrev_b64 v[92:93], 2, v[96:97]
	v_cndmask_b32_e32 v65, v67, v65, vcc
	v_cndmask_b32_e32 v64, v66, v64, vcc
	v_lshl_add_u64 v[68:69], s[44:45], 0, v[92:93]
	v_lshl_add_u64 v[76:77], v[64:65], 0, v[92:93]
	s_addc_u32 s43, s1, 0
	global_load_dwordx4 v[64:67], v[76:77], off nt
	global_load_dwordx4 v[100:103], v[68:69], off
	v_lshl_add_u64 v[68:69], s[42:43], 0, v[92:93]
	global_load_dwordx4 v[82:85], v[68:69], off
	v_lshl_add_u64 v[68:69], s[28:29], 0, v[92:93]
	global_load_dwordx4 v[86:89], v[68:69], off
	v_lshlrev_b32_e32 v99, 10, v98
	v_mov_b32_e32 v91, v97
	v_mov_b32_e32 v81, v97
	v_lshl_add_u64 v[70:71], s[12:13], 0, v[92:93]
	v_add_u32_e32 v80, 0xfffff010, v98
	v_or_b32_e32 v90, 0x4000, v99
	v_lshl_add_u64 v[78:79], v[70:71], 0, v[72:73]
	v_lshlrev_b64 v[80:81], 12, v[80:81]
	v_lshlrev_b64 v[72:73], 2, v[90:91]
	v_lshl_add_u64 v[80:81], s[10:11], 0, v[80:81]
	v_lshl_add_u64 v[106:107], s[8:9], 0, v[72:73]
	v_mov_b32_e32 v75, v97
	v_lshlrev_b32_e32 v74, 1, v96
	v_cndmask_b32_e32 v81, v81, v107, vcc
	v_cndmask_b32_e32 v80, v80, v106, vcc
	v_mov_b32_e32 v95, v97
	v_lshl_add_u64 v[104:105], s[22:23], 0, v[74:75]
	v_lshlrev_b32_e32 v94, 11, v98
	v_lshl_add_u64 v[74:75], v[104:105], 0, v[94:95]
	v_lshl_add_u64 v[80:81], v[80:81], 0, v[92:93]
	v_lshl_add_u64 v[94:95], s[22:23], 0, v[94:95]
	s_waitcnt vmcnt(2)
	v_pk_fma_f32 v[60:61], v[60:61], v[100:101], v[64:65]
	v_pk_fma_f32 v[62:63], v[62:63], v[102:103], v[66:67]
	s_waitcnt vmcnt(1)
	v_pk_add_f32 v[64:65], v[82:83], 1.0 op_sel_hi:[1,0]
	v_pk_add_f32 v[66:67], v[84:85], 1.0 op_sel_hi:[1,0]
	s_waitcnt vmcnt(0)
	v_pk_mul_f32 v[106:107], v[86:87], v[64:65]
	v_pk_mul_f32 v[108:109], v[88:89], v[66:67]
	v_pk_mul_f32 v[64:65], v[106:107], v[60:61]
	v_pk_mul_f32 v[66:67], v[108:109], v[62:63]
	v_cvt_pk_bf16_f32 v64, v64, v65
	v_cvt_pk_bf16_f32 v65, v66, v67
	global_store_dwordx4 v[78:79], v[60:63], off sc1
	global_store_dwordx2 v[74:75], v[64:65], off
	global_load_dwordx4 v[64:67], v[80:81], off nt
	v_mov_b32_e32 v75, v97
	v_mov_b32_e32 v85, v97
	v_add_u32_e32 v84, 0xfffff020, v98
	v_or_b32_e32 v74, 0x8000, v99
	v_lshlrev_b64 v[86:87], 12, v[84:85]
	v_lshlrev_b64 v[84:85], 2, v[74:75]
	v_mov_b32_e32 v83, v97
	v_lshlrev_b32_e32 v82, 1, v90
	v_lshl_add_u64 v[86:87], s[10:11], 0, v[86:87]
	v_lshl_add_u64 v[110:111], s[8:9], 0, v[84:85]
	v_lshl_add_u64 v[88:89], v[70:71], 0, v[72:73]
	v_lshl_add_u64 v[90:91], v[104:105], 0, v[82:83]
	v_cndmask_b32_e32 v87, v87, v111, vcc
	v_cndmask_b32_e32 v86, v86, v110, vcc
	v_lshl_add_u64 v[86:87], v[86:87], 0, v[92:93]
	v_mov_b32_e32 v111, v97
	v_add_u32_e32 v110, 0xfffff030, v98
	v_lshlrev_b64 v[110:111], 12, v[110:111]
	v_lshl_add_u64 v[110:111], s[10:11], 0, v[110:111]
	v_lshl_add_u64 v[112:113], v[70:71], 0, v[84:85]
	v_pk_mul_f32 v[60:61], v[60:61], v[60:61]
	v_pk_mul_f32 v[62:63], v[62:63], v[62:63]
	v_add_f32_e32 v60, v61, v60
	v_add_f32_e32 v60, v62, v60
	s_waitcnt vmcnt(0)
	v_pk_fma_f32 v[56:57], v[56:57], v[100:101], v[64:65]
	v_pk_fma_f32 v[58:59], v[58:59], v[102:103], v[66:67]
	v_pk_mul_f32 v[64:65], v[106:107], v[56:57]
	v_pk_mul_f32 v[66:67], v[108:109], v[58:59]
	v_cvt_pk_bf16_f32 v64, v64, v65
	v_cvt_pk_bf16_f32 v65, v66, v67
	global_store_dwordx4 v[88:89], v[56:59], off sc1
	global_store_dwordx2 v[90:91], v[64:65], off
	global_load_dwordx4 v[64:67], v[86:87], off nt
	v_mov_b32_e32 v89, v97
	v_or_b32_e32 v88, 0xc000, v99
	v_lshlrev_b32_e32 v90, 1, v74
	v_lshlrev_b64 v[74:75], 2, v[88:89]
	v_mov_b32_e32 v91, v97
	v_lshl_add_u64 v[126:127], s[8:9], 0, v[74:75]
	v_lshl_add_u64 v[114:115], v[104:105], 0, v[90:91]
	v_cndmask_b32_e32 v111, v111, v127, vcc
	v_cndmask_b32_e32 v110, v110, v126, vcc
	v_lshl_add_u64 v[92:93], v[110:111], 0, v[92:93]
	v_lshlrev_b32_e32 v88, 1, v88
	v_lshl_add_u64 v[104:105], v[104:105], 0, v[88:89]
	s_waitcnt vmcnt(0)
	v_pk_fma_f32 v[52:53], v[52:53], v[100:101], v[64:65]
	v_pk_fma_f32 v[54:55], v[54:55], v[102:103], v[66:67]
	v_pk_mul_f32 v[64:65], v[106:107], v[52:53]
	v_pk_mul_f32 v[66:67], v[108:109], v[54:55]
	v_cvt_pk_bf16_f32 v64, v64, v65
	v_cvt_pk_bf16_f32 v65, v66, v67
	global_store_dwordx4 v[112:113], v[52:55], off sc1
	global_store_dwordx2 v[114:115], v[64:65], off
	global_load_dwordx4 v[64:67], v[92:93], off nt
	v_mov_b32_e32 v113, v97
	v_or_b32_e32 v112, 16, v96
	v_lshl_add_u64 v[114:115], v[70:71], 0, v[74:75]
	v_lshlrev_b64 v[110:111], 2, v[112:113]
	v_lshl_add_u64 v[126:127], s[44:45], 0, v[110:111]
	v_lshlrev_b32_e32 v112, 1, v112
	s_waitcnt vmcnt(0)
	v_pk_fma_f32 v[48:49], v[48:49], v[100:101], v[64:65]
	v_pk_fma_f32 v[50:51], v[50:51], v[102:103], v[66:67]
	v_pk_mul_f32 v[64:65], v[106:107], v[48:49]
	v_pk_mul_f32 v[66:67], v[108:109], v[50:51]
	v_cvt_pk_bf16_f32 v64, v64, v65
	v_cvt_pk_bf16_f32 v65, v66, v67
	global_store_dwordx4 v[114:115], v[48:51], off sc1
	global_store_dwordx2 v[104:105], v[64:65], off
	global_load_dwordx4 v[64:67], v[76:77], off offset:64 nt
	s_nop 0
	global_load_dwordx4 v[100:103], v[126:127], off
	v_lshl_add_u64 v[104:105], s[42:43], 0, v[110:111]
	global_load_dwordx4 v[104:107], v[104:105], off
	s_nop 0
	global_load_dwordx4 v[108:111], v[68:69], off offset:64
	v_lshl_add_u64 v[114:115], v[94:95], 0, v[112:113]
	s_waitcnt vmcnt(2)
	v_pk_fma_f32 v[64:65], v[40:41], v[100:101], v[64:65]
	v_pk_fma_f32 v[66:67], v[42:43], v[102:103], v[66:67]
	s_waitcnt vmcnt(1)
	v_pk_add_f32 v[40:41], v[104:105], 1.0 op_sel_hi:[1,0]
	v_pk_add_f32 v[42:43], v[106:107], 1.0 op_sel_hi:[1,0]
	s_waitcnt vmcnt(0)
	v_pk_mul_f32 v[104:105], v[108:109], v[40:41]
	v_pk_mul_f32 v[106:107], v[110:111], v[42:43]
	v_pk_mul_f32 v[40:41], v[104:105], v[64:65]
	v_pk_mul_f32 v[42:43], v[106:107], v[66:67]
	v_cvt_pk_bf16_f32 v40, v40, v41
	v_cvt_pk_bf16_f32 v41, v42, v43
	global_store_dwordx4 v[78:79], v[64:67], off offset:64 sc1
	global_store_dwordx2 v[114:115], v[40:41], off
	global_load_dwordx4 v[40:43], v[80:81], off offset:64 nt
	v_lshl_add_u64 v[108:109], v[70:71], 0, 64
	v_lshl_add_u64 v[110:111], s[22:23], 0, v[112:113]
	v_lshl_add_u64 v[112:113], v[108:109], 0, v[72:73]
	v_lshl_add_u64 v[114:115], v[110:111], 0, v[82:83]
	s_waitcnt vmcnt(0)
	v_pk_fma_f32 v[40:41], v[44:45], v[100:101], v[40:41]
	v_pk_fma_f32 v[42:43], v[46:47], v[102:103], v[42:43]
	v_pk_mul_f32 v[44:45], v[104:105], v[40:41]
	v_pk_mul_f32 v[46:47], v[106:107], v[42:43]
	v_cvt_pk_bf16_f32 v44, v44, v45
	v_cvt_pk_bf16_f32 v45, v46, v47
	global_store_dwordx4 v[112:113], v[40:43], off sc1
	global_store_dwordx2 v[114:115], v[44:45], off
	global_load_dwordx4 v[44:47], v[86:87], off offset:64 nt
	v_lshl_add_u64 v[112:113], v[108:109], 0, v[84:85]
	v_lshl_add_u64 v[114:115], v[110:111], 0, v[90:91]
	v_lshl_add_u64 v[108:109], v[108:109], 0, v[74:75]
	v_lshl_add_u64 v[110:111], v[110:111], 0, v[88:89]
	s_waitcnt vmcnt(0)
	v_pk_fma_f32 v[36:37], v[36:37], v[100:101], v[44:45]
	v_pk_fma_f32 v[38:39], v[38:39], v[102:103], v[46:47]
	v_pk_mul_f32 v[44:45], v[104:105], v[36:37]
	v_pk_mul_f32 v[46:47], v[106:107], v[38:39]
	v_cvt_pk_bf16_f32 v44, v44, v45
	v_cvt_pk_bf16_f32 v45, v46, v47
	global_store_dwordx4 v[112:113], v[36:39], off sc1
	global_store_dwordx2 v[114:115], v[44:45], off
	global_load_dwordx4 v[44:47], v[92:93], off offset:64 nt
	v_mov_b32_e32 v113, v97
	v_or_b32_e32 v112, 32, v96
	v_lshlrev_b64 v[114:115], 2, v[112:113]
	v_lshl_add_u64 v[126:127], s[44:45], 0, v[114:115]
	v_lshlrev_b32_e32 v112, 1, v112
	v_or_b32_e32 v96, 48, v96
	s_waitcnt vmcnt(0)
	v_pk_fma_f32 v[32:33], v[32:33], v[100:101], v[44:45]
	v_pk_fma_f32 v[34:35], v[34:35], v[102:103], v[46:47]
	v_pk_mul_f32 v[44:45], v[104:105], v[32:33]
	v_pk_mul_f32 v[46:47], v[106:107], v[34:35]
	v_cvt_pk_bf16_f32 v44, v44, v45
	v_cvt_pk_bf16_f32 v45, v46, v47
	global_store_dwordx4 v[108:109], v[32:35], off sc1
	global_store_dwordx2 v[110:111], v[44:45], off
	global_load_dwordx4 v[44:47], v[76:77], off offset:128 nt
	s_nop 0
	global_load_dwordx4 v[100:103], v[126:127], off
	v_lshl_add_u64 v[104:105], s[42:43], 0, v[114:115]
	global_load_dwordx4 v[104:107], v[104:105], off
	s_nop 0
	global_load_dwordx4 v[108:111], v[68:69], off offset:128
	v_lshl_add_u64 v[114:115], v[94:95], 0, v[112:113]
	s_waitcnt vmcnt(2)
	v_pk_fma_f32 v[28:29], v[28:29], v[100:101], v[44:45]
	v_pk_fma_f32 v[30:31], v[30:31], v[102:103], v[46:47]
	s_waitcnt vmcnt(1)
	v_pk_add_f32 v[44:45], v[104:105], 1.0 op_sel_hi:[1,0]
	v_pk_add_f32 v[46:47], v[106:107], 1.0 op_sel_hi:[1,0]
	s_waitcnt vmcnt(0)
	v_pk_mul_f32 v[104:105], v[108:109], v[44:45]
	v_pk_mul_f32 v[106:107], v[110:111], v[46:47]
	v_pk_mul_f32 v[44:45], v[104:105], v[28:29]
	v_pk_mul_f32 v[46:47], v[106:107], v[30:31]
	v_cvt_pk_bf16_f32 v44, v44, v45
	v_cvt_pk_bf16_f32 v45, v46, v47
	global_store_dwordx4 v[78:79], v[28:31], off offset:128 sc1
	global_store_dwordx2 v[114:115], v[44:45], off
	global_load_dwordx4 v[44:47], v[80:81], off offset:128 nt
	v_lshl_add_u64 v[108:109], v[70:71], 0, s[38:39]
	v_lshl_add_u64 v[110:111], s[22:23], 0, v[112:113]
	v_lshl_add_u64 v[112:113], v[108:109], 0, v[72:73]
	v_lshl_add_u64 v[114:115], v[110:111], 0, v[82:83]
	v_pk_mul_f32 v[28:29], v[28:29], v[28:29]
	v_pk_mul_f32 v[30:31], v[30:31], v[30:31]
	v_add_f32_e32 v28, v29, v28
	v_add_f32_e32 v28, v30, v28
	v_add_f32_e32 v28, v31, v28
	s_waitcnt vmcnt(0)
	v_pk_fma_f32 v[24:25], v[24:25], v[100:101], v[44:45]
	v_pk_fma_f32 v[26:27], v[26:27], v[102:103], v[46:47]
	v_pk_mul_f32 v[44:45], v[104:105], v[24:25]
	v_pk_mul_f32 v[46:47], v[106:107], v[26:27]
	v_cvt_pk_bf16_f32 v44, v44, v45
	v_cvt_pk_bf16_f32 v45, v46, v47
	global_store_dwordx4 v[112:113], v[24:27], off sc1
	global_store_dwordx2 v[114:115], v[44:45], off
	global_load_dwordx4 v[44:47], v[86:87], off offset:128 nt
	v_lshl_add_u64 v[112:113], v[108:109], 0, v[84:85]
	v_lshl_add_u64 v[114:115], v[110:111], 0, v[90:91]
	v_lshl_add_u64 v[108:109], v[108:109], 0, v[74:75]
	v_lshl_add_u64 v[110:111], v[110:111], 0, v[88:89]
	s_waitcnt vmcnt(0)
	v_pk_fma_f32 v[20:21], v[20:21], v[100:101], v[44:45]
	v_pk_fma_f32 v[22:23], v[22:23], v[102:103], v[46:47]
	v_pk_mul_f32 v[44:45], v[104:105], v[20:21]
	v_pk_mul_f32 v[46:47], v[106:107], v[22:23]
	v_cvt_pk_bf16_f32 v44, v44, v45
	v_cvt_pk_bf16_f32 v45, v46, v47
	global_store_dwordx4 v[112:113], v[20:23], off sc1
	global_store_dwordx2 v[114:115], v[44:45], off
	global_load_dwordx4 v[44:47], v[92:93], off offset:128 nt
	v_lshlrev_b64 v[112:113], 2, v[96:97]
	v_lshl_add_u64 v[114:115], s[44:45], 0, v[112:113]
	v_lshlrev_b32_e32 v96, 1, v96
	s_waitcnt vmcnt(0)
	v_pk_fma_f32 v[16:17], v[16:17], v[100:101], v[44:45]
	v_pk_fma_f32 v[18:19], v[18:19], v[102:103], v[46:47]
	v_pk_mul_f32 v[44:45], v[104:105], v[16:17]
	v_pk_mul_f32 v[46:47], v[106:107], v[18:19]
	v_cvt_pk_bf16_f32 v44, v44, v45
	v_cvt_pk_bf16_f32 v45, v46, v47
	global_store_dwordx4 v[108:109], v[16:19], off sc1
	global_store_dwordx2 v[110:111], v[44:45], off
	global_load_dwordx4 v[44:47], v[76:77], off offset:192 nt
	s_nop 0
	global_load_dwordx4 v[100:103], v[114:115], off
	v_lshl_add_u64 v[76:77], s[42:43], 0, v[112:113]
	global_load_dwordx4 v[104:107], v[76:77], off
	global_load_dwordx4 v[108:111], v[68:69], off offset:192
	v_lshl_add_u64 v[68:69], v[94:95], 0, v[96:97]
	s_waitcnt vmcnt(2)
	v_pk_fma_f32 v[12:13], v[12:13], v[100:101], v[44:45]
	v_pk_fma_f32 v[14:15], v[14:15], v[102:103], v[46:47]
	s_waitcnt vmcnt(1)
	v_pk_add_f32 v[44:45], v[104:105], 1.0 op_sel_hi:[1,0]
	v_pk_add_f32 v[46:47], v[106:107], 1.0 op_sel_hi:[1,0]
	s_waitcnt vmcnt(0)
	v_pk_mul_f32 v[76:77], v[108:109], v[44:45]
	v_pk_mul_f32 v[94:95], v[110:111], v[46:47]
	v_pk_mul_f32 v[44:45], v[76:77], v[12:13]
	v_pk_mul_f32 v[46:47], v[94:95], v[14:15]
	v_cvt_pk_bf16_f32 v44, v44, v45
	v_cvt_pk_bf16_f32 v45, v46, v47
	global_store_dwordx4 v[78:79], v[12:15], off offset:192 sc1
	global_store_dwordx2 v[68:69], v[44:45], off
	global_load_dwordx4 v[44:47], v[80:81], off offset:192 nt
	v_lshl_add_u64 v[68:69], v[70:71], 0, s[40:41]
	v_lshl_add_u64 v[70:71], s[22:23], 0, v[96:97]
	v_lshl_add_u64 v[72:73], v[68:69], 0, v[72:73]
	v_lshl_add_u64 v[78:79], v[70:71], 0, v[82:83]
	v_pk_mul_f32 v[12:13], v[12:13], v[12:13]
	v_pk_mul_f32 v[14:15], v[14:15], v[14:15]
	v_add_f32_e32 v12, v13, v12
	v_add_f32_e32 v12, v14, v12
	v_add_f32_e32 v12, v15, v12
	v_lshlrev_b32_e32 v96, 2, v98
	s_waitcnt vmcnt(0)
	v_pk_fma_f32 v[8:9], v[8:9], v[100:101], v[44:45]
	v_pk_fma_f32 v[10:11], v[10:11], v[102:103], v[46:47]
	v_pk_mul_f32 v[44:45], v[76:77], v[8:9]
	v_pk_mul_f32 v[46:47], v[94:95], v[10:11]
	v_cvt_pk_bf16_f32 v44, v44, v45
	v_cvt_pk_bf16_f32 v45, v46, v47
	global_store_dwordx4 v[72:73], v[8:11], off sc1
	global_store_dwordx2 v[78:79], v[44:45], off
	global_load_dwordx4 v[44:47], v[86:87], off offset:192 nt
	v_lshl_add_u64 v[72:73], v[68:69], 0, v[84:85]
	v_lshl_add_u64 v[78:79], v[70:71], 0, v[90:91]
	s_waitcnt vmcnt(0)
	v_pk_fma_f32 v[4:5], v[4:5], v[100:101], v[44:45]
	v_pk_fma_f32 v[6:7], v[6:7], v[102:103], v[46:47]
	v_pk_mul_f32 v[44:45], v[76:77], v[4:5]
	v_pk_mul_f32 v[46:47], v[94:95], v[6:7]
	v_cvt_pk_bf16_f32 v44, v44, v45
	v_cvt_pk_bf16_f32 v45, v46, v47
	global_store_dwordx4 v[72:73], v[4:7], off sc1
	global_store_dwordx2 v[78:79], v[44:45], off
	global_load_dwordx4 v[44:47], v[92:93], off offset:192 nt
	v_add_f32_e32 v72, v63, v60
	v_pk_mul_f32 v[60:61], v[64:65], v[64:65]
	v_pk_mul_f32 v[62:63], v[66:67], v[66:67]
	v_add_f32_e32 v60, v61, v60
	v_add_f32_e32 v60, v62, v60
	v_add_f32_e32 v60, v63, v60
	v_add_f32_e32 v60, v72, v60
	v_add_f32_e32 v28, v60, v28
	v_add_f32_e32 v14, v28, v12
	ds_bpermute_b32 v15, v124, v14
	v_lshl_add_u64 v[12:13], v[68:69], 0, v[74:75]
	v_lshl_add_u64 v[28:29], v[70:71], 0, v[88:89]
	s_waitcnt lgkmcnt(0)
	v_add_f32_e32 v14, v14, v15
	ds_bpermute_b32 v15, v125, v14
	s_waitcnt vmcnt(0)
	v_pk_fma_f32 v[0:1], v[0:1], v[100:101], v[44:45]
	v_pk_fma_f32 v[2:3], v[2:3], v[102:103], v[46:47]
	global_store_dwordx4 v[12:13], v[0:3], off sc1
	v_pk_mul_f32 v[12:13], v[76:77], v[0:1]
	v_pk_mul_f32 v[30:31], v[94:95], v[2:3]
	v_cvt_pk_bf16_f32 v12, v12, v13
	v_cvt_pk_bf16_f32 v13, v30, v31
	global_store_dwordx2 v[28:29], v[12:13], off
	v_lshl_add_u64 v[12:13], s[24:25], 0, v[96:97]
	s_and_saveexec_b64 s[42:43], s[6:7]
	s_cbranch_execz .LBB0_466
	s_waitcnt lgkmcnt(0)
	v_add_f32_e32 v14, v14, v15
	global_atomic_add_f32 v[12:13], v14, off

.LBB0_543:
	s_and_b64 vcc, exec, s[6:7]
	s_cbranch_vccz .LBB0_545
	v_cvt_pk_bf16_f32 v3, v8, s0
	ds_write_b16 v178, v3
	v_cvt_pk_bf16_f32 v3, v137, s0
	ds_write_b16 v178, v3 offset:144
	v_cvt_pk_bf16_f32 v3, v10, s0
	ds_write_b16 v178, v3 offset:288
	v_cvt_pk_bf16_f32 v3, v138, s0
	ds_write_b16 v178, v3 offset:432
	v_cvt_pk_bf16_f32 v3, v136, s0
	ds_write_b16 v178, v3 offset:2304
	v_cvt_pk_bf16_f32 v3, v9, s0
	ds_write_b16 v178, v3 offset:2448
	v_cvt_pk_bf16_f32 v3, v14, s0
	ds_write_b16 v178, v3 offset:2592
	v_cvt_pk_bf16_f32 v3, v139, s0
	ds_write_b16 v178, v3 offset:2736
	v_cvt_pk_bf16_f32 v3, v16, s0
	ds_write_b16 v178, v3 offset:4608
	v_cvt_pk_bf16_f32 v3, v143, s0
	ds_write_b16 v178, v3 offset:4752
	v_cvt_pk_bf16_f32 v3, v18, s0
	ds_write_b16 v178, v3 offset:4896
	v_cvt_pk_bf16_f32 v3, v12, s0
	ds_write_b16 v178, v3 offset:5040
	v_cvt_pk_bf16_f32 v3, v142, s0
	ds_write_b16 v178, v3 offset:6912
	v_cvt_pk_bf16_f32 v3, v17, s0
	ds_write_b16 v178, v3 offset:7056
	v_cvt_pk_bf16_f32 v3, v22, s0
	ds_write_b16 v178, v3 offset:7200
	v_cvt_pk_bf16_f32 v3, v13, s0
	ds_write_b16 v178, v3 offset:7344
	v_cvt_pk_bf16_f32 v3, v24, s0
	ds_write_b16 v178, v3 offset:8
	v_cvt_pk_bf16_f32 v3, v21, s0
	ds_write_b16 v178, v3 offset:152
	v_cvt_pk_bf16_f32 v3, v26, s0
	ds_write_b16 v178, v3 offset:296
	v_cvt_pk_bf16_f32 v3, v140, s0
	ds_write_b16 v178, v3 offset:440
	v_cvt_pk_bf16_f32 v3, v20, s0
	ds_write_b16 v178, v3 offset:2312
	v_cvt_pk_bf16_f32 v3, v25, s0
	ds_write_b16 v178, v3 offset:2456
	v_cvt_pk_bf16_f32 v3, v30, s0
	ds_write_b16 v178, v3 offset:2600
	v_cvt_pk_bf16_f32 v3, v141, s0
	ds_write_b16 v178, v3 offset:2744
	v_cvt_pk_bf16_f32 v3, v32, s0
	ds_write_b16 v178, v3 offset:4616
	v_cvt_pk_bf16_f32 v3, v165, s0
	ds_write_b16 v178, v3 offset:4760
	v_cvt_pk_bf16_f32 v3, v34, s0
	ds_write_b16 v178, v3 offset:4904
	v_cvt_pk_bf16_f32 v3, v28, s0
	ds_write_b16 v178, v3 offset:5048
	v_cvt_pk_bf16_f32 v3, v164, s0
	ds_write_b16 v178, v3 offset:6920
	v_cvt_pk_bf16_f32 v3, v33, s0
	ds_write_b16 v178, v3 offset:7064
	v_cvt_pk_bf16_f32 v3, v38, s0
	ds_write_b16 v178, v3 offset:7208
	v_cvt_pk_bf16_f32 v3, v29, s0
	ds_write_b16 v178, v3 offset:7352
	v_cvt_pk_bf16_f32 v3, v40, s0
	ds_write_b16 v178, v3 offset:64
	v_cvt_pk_bf16_f32 v3, v163, s0
	ds_write_b16 v178, v3 offset:208
	v_cvt_pk_bf16_f32 v3, v42, s0
	ds_write_b16 v178, v3 offset:352
	v_cvt_pk_bf16_f32 v3, v36, s0
	ds_write_b16 v178, v3 offset:496
	v_cvt_pk_bf16_f32 v3, v162, s0
	ds_write_b16 v178, v3 offset:2368
	v_cvt_pk_bf16_f32 v3, v41, s0
	ds_write_b16 v178, v3 offset:2512
	v_cvt_pk_bf16_f32 v3, v46, s0
	ds_write_b16 v178, v3 offset:2656
	v_cvt_pk_bf16_f32 v3, v37, s0
	ds_write_b16 v178, v3 offset:2800
	v_cvt_pk_bf16_f32 v3, v48, s0
	ds_write_b16 v178, v3 offset:4672
	v_cvt_pk_bf16_f32 v3, v169, s0
	ds_write_b16 v178, v3 offset:4816
	v_cvt_pk_bf16_f32 v3, v50, s0
	ds_write_b16 v178, v3 offset:4960
	v_cvt_pk_bf16_f32 v3, v44, s0
	ds_write_b16 v178, v3 offset:5104
	v_cvt_pk_bf16_f32 v3, v168, s0
	ds_write_b16 v178, v3 offset:6976
	v_cvt_pk_bf16_f32 v3, v49, s0
	ds_write_b16 v178, v3 offset:7120
	v_cvt_pk_bf16_f32 v3, v54, s0
	ds_write_b16 v178, v3 offset:7264
	v_cvt_pk_bf16_f32 v3, v45, s0
	ds_write_b16 v178, v3 offset:7408
	v_cvt_pk_bf16_f32 v3, v56, s0
	ds_write_b16 v178, v3 offset:72
	v_cvt_pk_bf16_f32 v3, v53, s0
	ds_write_b16 v178, v3 offset:216
	v_cvt_pk_bf16_f32 v3, v58, s0
	ds_write_b16 v178, v3 offset:360
	v_cvt_pk_bf16_f32 v3, v166, s0
	ds_write_b16 v178, v3 offset:504
	v_cvt_pk_bf16_f32 v3, v52, s0
	ds_write_b16 v178, v3 offset:2376
	v_cvt_pk_bf16_f32 v3, v57, s0
	ds_write_b16 v178, v3 offset:2520
	v_cvt_pk_bf16_f32 v3, v2, s0
	ds_write_b16 v178, v3 offset:2664
	v_cvt_pk_bf16_f32 v3, v167, s0
	ds_write_b16 v178, v3 offset:2808
	v_cvt_pk_bf16_f32 v3, v60, s0
	ds_write_b16 v178, v3 offset:4680
	v_cvt_pk_bf16_f32 v3, v1, s0
	ds_write_b16 v178, v3 offset:4824
	v_cvt_pk_bf16_f32 v3, v62, s0
	ds_write_b16 v178, v3 offset:4968
	v_cvt_pk_bf16_f32 v3, v170, s0
	ds_write_b16 v178, v3 offset:5112
	v_cvt_pk_bf16_f32 v3, v0, s0
	ds_write_b16 v178, v3 offset:6984
	v_cvt_pk_bf16_f32 v3, v61, s0
	ds_write_b16 v178, v3 offset:7128
	v_cvt_pk_bf16_f32 v3, v6, s0
	ds_write_b16 v178, v3 offset:7272
	v_cvt_pk_bf16_f32 v3, v171, s0
	ds_write_b16 v178, v3 offset:7416
	v_add_u32_e32 v3, 0xfffff800, v160
	s_waitcnt lgkmcnt(0)
	s_lshl_b32 s36, s44, 1
	ds_read_b128 v[64:67], v180
	v_or_b32_e32 v7, v3, v236
	v_lshl_add_u64 v[4:5], v[132:133], 0, s[36:37]
	v_lshlrev_b32_e32 v68, 14, v7
	v_mov_b32_e32 v69, v161
	v_lshl_add_u64 v[72:73], v[4:5], 0, v[68:69]
	ds_read_b128 v[68:71], v180 offset:1152
	v_or_b32_e32 v7, v3, v237
	s_waitcnt lgkmcnt(1)
	global_store_dwordx4 v[72:73], v[64:67], off sc1
	v_mov_b32_e32 v63, v170
	v_mov_b32_e32 v59, v166
	v_lshlrev_b32_e32 v64, 14, v7
	v_mov_b32_e32 v65, v161
	v_lshl_add_u64 v[64:65], v[4:5], 0, v[64:65]
	s_waitcnt lgkmcnt(0)
	global_store_dwordx4 v[64:65], v[68:71], off sc1
	ds_read_b128 v[64:67], v180 offset:2304
	v_or_b32_e32 v7, v3, v238
	v_lshlrev_b32_e32 v68, 14, v7
	v_mov_b32_e32 v69, v161
	v_lshl_add_u64 v[72:73], v[4:5], 0, v[68:69]
	ds_read_b128 v[68:71], v180 offset:3456
	v_or_b32_e32 v7, v3, v239
	s_waitcnt lgkmcnt(1)
	global_store_dwordx4 v[72:73], v[64:67], off sc1
	v_mov_b32_e32 v55, v45
	v_mov_b32_e32 v51, v44
	v_lshlrev_b32_e32 v64, 14, v7
	v_mov_b32_e32 v65, v161
	v_lshl_add_u64 v[64:65], v[4:5], 0, v[64:65]
	s_waitcnt lgkmcnt(0)
	global_store_dwordx4 v[64:65], v[68:71], off sc1
	ds_read_b128 v[64:67], v180 offset:4608
	v_or_b32_e32 v7, v3, v240
	v_lshlrev_b32_e32 v68, 14, v7
	v_mov_b32_e32 v69, v161
	v_lshl_add_u64 v[72:73], v[4:5], 0, v[68:69]
	ds_read_b128 v[68:71], v180 offset:5760
	v_or_b32_e32 v7, v3, v241
	s_waitcnt lgkmcnt(1)
	global_store_dwordx4 v[72:73], v[64:67], off sc1
	v_mov_b32_e32 v47, v37
	v_mov_b32_e32 v43, v36
	v_lshlrev_b32_e32 v64, 14, v7
	v_mov_b32_e32 v65, v161
	v_lshl_add_u64 v[64:65], v[4:5], 0, v[64:65]
	s_waitcnt lgkmcnt(0)
	global_store_dwordx4 v[64:65], v[68:71], off sc1
	ds_read_b128 v[64:67], v180 offset:6912
	v_or_b32_e32 v7, v3, v242
	v_lshlrev_b32_e32 v68, 14, v7
	v_mov_b32_e32 v69, v161
	v_lshl_add_u64 v[72:73], v[4:5], 0, v[68:69]
	ds_read_b128 v[68:71], v180 offset:8064
	v_or_b32_e32 v3, v3, v243
	s_waitcnt lgkmcnt(1)
	global_store_dwordx4 v[72:73], v[64:67], off sc1
	v_mov_b32_e32 v7, v171
	v_mov_b32_e32 v39, v29
	v_lshlrev_b32_e32 v64, 14, v3
	v_mov_b32_e32 v65, v161
	v_lshl_add_u64 v[4:5], v[4:5], 0, v[64:65]
	v_mov_b32_e32 v3, v167
	v_mov_b32_e32 v35, v28
	v_mov_b32_e32 v31, v141
	v_mov_b32_e32 v27, v140
	v_mov_b32_e32 v23, v13
	v_mov_b32_e32 v19, v12
	v_mov_b32_e32 v15, v139
	v_mov_b32_e32 v11, v138
	s_waitcnt lgkmcnt(0)
	global_store_dwordx4 v[4:5], v[68:71], off sc1
	v_mov_b32_e32 v4, v0
	v_mov_b32_e32 v5, v61
	v_mov_b32_e32 v61, v1
	v_mov_b32_e32 v0, v52
	v_mov_b32_e32 v1, v57
	v_mov_b32_e32 v57, v53
	v_mov_b32_e32 v52, v168
	v_mov_b32_e32 v53, v49
	v_mov_b32_e32 v49, v169
	v_mov_b32_e32 v44, v162
	v_mov_b32_e32 v45, v41
	v_mov_b32_e32 v41, v163
	v_mov_b32_e32 v36, v164
	v_mov_b32_e32 v37, v33
	v_mov_b32_e32 v33, v165
	v_mov_b32_e32 v28, v20
	v_mov_b32_e32 v29, v25
	v_mov_b32_e32 v25, v21
	v_mov_b32_e32 v20, v142
	v_mov_b32_e32 v21, v17
	v_mov_b32_e32 v17, v143
	v_mov_b32_e32 v12, v136
	v_mov_b32_e32 v13, v9
	v_mov_b32_e32 v9, v137
	v_mov_b64_e32 v[66:67], v[10:11]
	v_mov_b64_e32 v[70:71], v[14:15]
	v_mov_b64_e32 v[74:75], v[18:19]
	v_mov_b64_e32 v[78:79], v[22:23]
	v_mov_b64_e32 v[82:83], v[26:27]
	v_mov_b64_e32 v[86:87], v[30:31]
	v_mov_b64_e32 v[90:91], v[34:35]
	v_mov_b64_e32 v[94:95], v[38:39]
	v_mov_b64_e32 v[98:99], v[42:43]
	v_mov_b64_e32 v[102:103], v[46:47]
	v_mov_b64_e32 v[106:107], v[50:51]
	v_mov_b64_e32 v[110:111], v[54:55]
	v_mov_b64_e32 v[114:115], v[58:59]
	v_mov_b64_e32 v[118:119], v[2:3]
	v_mov_b64_e32 v[122:123], v[62:63]
	v_mov_b64_e32 v[126:127], v[6:7]
	v_mov_b64_e32 v[64:65], v[8:9]
	v_mov_b64_e32 v[68:69], v[12:13]
	v_mov_b64_e32 v[72:73], v[16:17]
	v_mov_b64_e32 v[76:77], v[20:21]
	v_mov_b64_e32 v[80:81], v[24:25]
	v_mov_b64_e32 v[84:85], v[28:29]
	v_mov_b64_e32 v[88:89], v[32:33]
	v_mov_b64_e32 v[92:93], v[36:37]
	v_mov_b64_e32 v[96:97], v[40:41]
	v_mov_b64_e32 v[100:101], v[44:45]
	v_mov_b64_e32 v[104:105], v[48:49]
	v_mov_b64_e32 v[108:109], v[52:53]
	v_mov_b64_e32 v[112:113], v[56:57]
	v_mov_b64_e32 v[116:117], v[0:1]
	v_mov_b64_e32 v[120:121], v[60:61]
	v_mov_b64_e32 v[124:125], v[4:5]

.LBB0_676:
	s_add_i32 s33, s42, 2
	s_cmp_lt_u32 s42, 14
	s_cselect_b32 s44, s2, 0x700
	s_min_u32 s28, s42, 12
	s_lshl_b32 s28, s28, 7
	s_addk_i32 s2, 0x100
	s_ashr_i32 s45, s44, 31
	s_addk_i32 s28, 0x180
	s_cmp_gt_u32 s42, 13
	s_setprio 1
	ds_read_b128 v[126:129], v119 offset:32768
	ds_read_b128 v[134:137], v119 offset:34816
	ds_read_b128 v[130:133], v118
	ds_read_b128 v[138:141], v118 offset:2048
	ds_read_b128 v[162:165], v118 offset:4096
	ds_read_b128 v[166:169], v118 offset:6144
	v_add_u32_e32 v99, s44, v96
	v_add_u32_e32 v142, 0x10000, v99
	s_waitcnt lgkmcnt(3)
	v_mfma_f32_16x16x32_bf16 v[64:67], v[126:129], v[130:133], v[64:67]
	ds_read_b128 v[170:173], v119 offset:36864
	v_mfma_f32_16x16x32_bf16 v[40:43], v[134:137], v[130:133], v[40:43]
	ds_read_b128 v[174:177], v119 offset:38912
	s_waitcnt lgkmcnt(1)
	v_mfma_f32_16x16x32_bf16 v[28:31], v[170:173], v[130:133], v[28:31]
	s_waitcnt lgkmcnt(0)
	v_mfma_f32_16x16x32_bf16 v[12:15], v[174:177], v[130:133], v[12:15]
	v_lshl_add_u64 v[130:131], v[100:101], 0, s[44:45]
	global_load_dwordx4 v[130:133], v[130:131], off
	ds_read_b128 v[178:181], v120
	v_mfma_f32_16x16x32_bf16 v[60:63], v[126:129], v[138:141], v[60:63]
	v_mfma_f32_16x16x32_bf16 v[44:47], v[134:137], v[138:141], v[44:47]
	global_load_dwordx4 v[182:185], v142, s[18:19]
	ds_read_b128 v[186:189], v120 offset:2048
	v_mfma_f32_16x16x32_bf16 v[24:27], v[170:173], v[138:141], v[24:27]
	v_mfma_f32_16x16x32_bf16 v[8:11], v[174:177], v[138:141], v[8:11]
	v_add_u32_e32 v138, 0x20000, v99
	v_add_u32_e32 v99, 0x30000, v99
	global_load_dwordx4 v[138:141], v138, s[18:19]
	ds_read_b128 v[190:193], v120 offset:4096
	v_mfma_f32_16x16x32_bf16 v[52:55], v[126:129], v[162:165], v[52:55]
	v_mfma_f32_16x16x32_bf16 v[36:39], v[134:137], v[162:165], v[36:39]
	global_load_dwordx4 v[194:197], v99, s[18:19]
	v_add_u32_e32 v99, s44, v98
	ds_read_b128 v[198:201], v120 offset:6144
	v_mfma_f32_16x16x32_bf16 v[20:23], v[170:173], v[162:165], v[20:23]
	v_add_u32_e32 v142, 0x20000, v99
	v_mfma_f32_16x16x32_bf16 v[4:7], v[174:177], v[162:165], v[4:7]
	global_load_dwordx4 v[162:165], v99, s[16:17]
	ds_read_b128 v[202:205], v121 offset:32768
	v_mfma_f32_16x16x32_bf16 v[48:51], v[126:129], v[166:169], v[48:51]
	v_add_u32_e32 v126, 0x10000, v99
	v_add_u32_e32 v99, 0x30000, v99
	v_mfma_f32_16x16x32_bf16 v[32:35], v[134:137], v[166:169], v[32:35]
	global_load_dwordx4 v[126:129], v126, s[16:17]
	ds_read_b128 v[134:137], v121 offset:34816
	v_mfma_f32_16x16x32_bf16 v[16:19], v[170:173], v[166:169], v[16:19]
	v_mfma_f32_16x16x32_bf16 v[0:3], v[174:177], v[166:169], v[0:3]
	global_load_dwordx4 v[166:169], v142, s[16:17]
	ds_read_b128 v[170:173], v121 offset:36864
	s_waitcnt lgkmcnt(2)
	v_mfma_f32_16x16x32_bf16 v[64:67], v[202:205], v[178:181], v[64:67]
	s_waitcnt lgkmcnt(1)
	v_mfma_f32_16x16x32_bf16 v[40:43], v[134:137], v[178:181], v[40:43]
	global_load_dwordx4 v[174:177], v99, s[16:17]
	ds_read_b128 v[206:209], v121 offset:38912
	s_waitcnt lgkmcnt(1)
	v_mfma_f32_16x16x32_bf16 v[28:31], v[170:173], v[178:181], v[28:31]
	s_waitcnt lgkmcnt(0)
	v_mfma_f32_16x16x32_bf16 v[12:15], v[206:209], v[178:181], v[12:15]
	s_waitcnt vmcnt(14)
	ds_write_b128 v117, v[56:59] offset:16384
	v_mfma_f32_16x16x32_bf16 v[60:63], v[202:205], v[186:189], v[60:63]
	v_mfma_f32_16x16x32_bf16 v[44:47], v[134:137], v[186:189], v[44:47]
	s_waitcnt vmcnt(13)
	ds_write_b128 v117, v[68:71] offset:20480
	v_mfma_f32_16x16x32_bf16 v[24:27], v[170:173], v[186:189], v[24:27]
	v_mfma_f32_16x16x32_bf16 v[8:11], v[206:209], v[186:189], v[8:11]
	s_waitcnt vmcnt(12)
	ds_write_b128 v117, v[72:75] offset:24576
	v_mfma_f32_16x16x32_bf16 v[52:55], v[202:205], v[190:193], v[52:55]
	v_mfma_f32_16x16x32_bf16 v[36:39], v[134:137], v[190:193], v[36:39]
	s_waitcnt vmcnt(11)
	ds_write_b128 v117, v[80:83] offset:28672
	v_mfma_f32_16x16x32_bf16 v[20:23], v[170:173], v[190:193], v[20:23]
	v_mfma_f32_16x16x32_bf16 v[4:7], v[206:209], v[190:193], v[4:7]
	ds_write_b128 v117, v[76:79] offset:49152
	v_mfma_f32_16x16x32_bf16 v[48:51], v[202:205], v[198:201], v[48:51]
	v_mfma_f32_16x16x32_bf16 v[32:35], v[134:137], v[198:201], v[32:35]
	s_waitcnt vmcnt(10)
	ds_write_b128 v117, v[84:87] offset:53248
	v_mfma_f32_16x16x32_bf16 v[16:19], v[170:173], v[198:201], v[16:19]
	v_mfma_f32_16x16x32_bf16 v[0:3], v[206:209], v[198:201], v[0:3]
	s_waitcnt vmcnt(9)
	ds_write_b128 v117, v[88:91] offset:57344
	s_waitcnt vmcnt(8)
	ds_write_b128 v117, v[92:95] offset:61440
	s_setprio 0
	s_waitcnt lgkmcnt(0)
	s_barrier
	s_setprio 1
	ds_read_b128 v[84:87], v119 offset:49152
	ds_read_b128 v[88:91], v119 offset:51200
	ds_read_b128 v[56:59], v118 offset:16384
	ds_read_b128 v[72:75], v118 offset:18432
	ds_read_b128 v[76:79], v118 offset:20480
	ds_read_b128 v[92:95], v118 offset:22528
	v_lshl_add_u64 v[68:69], v[110:111], 0, s[28:29]
	v_lshl_add_u64 v[80:81], v[114:115], 0, s[28:29]
	s_waitcnt lgkmcnt(3)
	v_mfma_f32_16x16x32_bf16 v[64:67], v[84:87], v[56:59], v[64:67]
	ds_read_b128 v[134:137], v119 offset:53248
	v_mfma_f32_16x16x32_bf16 v[40:43], v[88:91], v[56:59], v[40:43]
	ds_read_b128 v[170:173], v119 offset:55296
	s_waitcnt lgkmcnt(1)
	v_mfma_f32_16x16x32_bf16 v[28:31], v[134:137], v[56:59], v[28:31]
	s_waitcnt lgkmcnt(0)
	v_mfma_f32_16x16x32_bf16 v[12:15], v[170:173], v[56:59], v[12:15]
	v_lshl_add_u64 v[56:57], v[100:101], 0, s[28:29]
	global_load_dwordx4 v[56:59], v[56:57], off
	ds_read_b128 v[178:181], v120 offset:16384
	v_mfma_f32_16x16x32_bf16 v[60:63], v[84:87], v[72:75], v[60:63]
	v_mfma_f32_16x16x32_bf16 v[44:47], v[88:91], v[72:75], v[44:47]
	global_load_dwordx4 v[68:71], v[68:69], off
	ds_read_b128 v[186:189], v120 offset:18432
	v_mfma_f32_16x16x32_bf16 v[24:27], v[134:137], v[72:75], v[24:27]
	v_mfma_f32_16x16x32_bf16 v[8:11], v[170:173], v[72:75], v[8:11]
	v_lshl_add_u64 v[72:73], v[112:113], 0, s[28:29]
	global_load_dwordx4 v[72:75], v[72:73], off
	ds_read_b128 v[190:193], v120 offset:20480
	v_mfma_f32_16x16x32_bf16 v[52:55], v[84:87], v[76:79], v[52:55]
	v_mfma_f32_16x16x32_bf16 v[36:39], v[88:91], v[76:79], v[36:39]
	global_load_dwordx4 v[80:83], v[80:81], off
	ds_read_b128 v[198:201], v120 offset:22528
	v_mfma_f32_16x16x32_bf16 v[20:23], v[134:137], v[76:79], v[20:23]
	v_mfma_f32_16x16x32_bf16 v[4:7], v[170:173], v[76:79], v[4:7]
	v_lshl_add_u64 v[76:77], v[102:103], 0, s[28:29]
	global_load_dwordx4 v[76:79], v[76:77], off
	ds_read_b128 v[202:205], v121 offset:49152
	v_mfma_f32_16x16x32_bf16 v[48:51], v[84:87], v[92:95], v[48:51]
	v_lshl_add_u64 v[84:85], v[104:105], 0, s[28:29]
	v_mfma_f32_16x16x32_bf16 v[32:35], v[88:91], v[92:95], v[32:35]
	global_load_dwordx4 v[84:87], v[84:85], off
	ds_read_b128 v[206:209], v121 offset:51200
	v_lshl_add_u64 v[88:89], v[106:107], 0, s[28:29]
	v_mfma_f32_16x16x32_bf16 v[16:19], v[134:137], v[92:95], v[16:19]
	v_mfma_f32_16x16x32_bf16 v[0:3], v[170:173], v[92:95], v[0:3]
	v_lshl_add_u64 v[92:93], v[108:109], 0, s[28:29]
	global_load_dwordx4 v[88:91], v[88:89], off
	ds_read_b128 v[134:137], v121 offset:53248
	s_waitcnt lgkmcnt(2)
	v_mfma_f32_16x16x32_bf16 v[64:67], v[202:205], v[178:181], v[64:67]
	s_waitcnt lgkmcnt(1)
	v_mfma_f32_16x16x32_bf16 v[40:43], v[206:209], v[178:181], v[40:43]
	global_load_dwordx4 v[92:95], v[92:93], off
	ds_read_b128 v[170:173], v121 offset:55296
	s_waitcnt lgkmcnt(1)
	v_mfma_f32_16x16x32_bf16 v[28:31], v[134:137], v[178:181], v[28:31]
	s_waitcnt lgkmcnt(0)
	v_mfma_f32_16x16x32_bf16 v[12:15], v[170:173], v[178:181], v[12:15]
	s_waitcnt vmcnt(15)
	ds_write_b128 v117, v[130:133]
	v_mfma_f32_16x16x32_bf16 v[60:63], v[202:205], v[186:189], v[60:63]
	v_mfma_f32_16x16x32_bf16 v[44:47], v[206:209], v[186:189], v[44:47]
	s_waitcnt vmcnt(14)
	ds_write_b128 v117, v[182:185] offset:4096
	v_mfma_f32_16x16x32_bf16 v[24:27], v[134:137], v[186:189], v[24:27]
	v_mfma_f32_16x16x32_bf16 v[8:11], v[170:173], v[186:189], v[8:11]
	s_waitcnt vmcnt(13)
	ds_write_b128 v117, v[138:141] offset:8192
	v_mfma_f32_16x16x32_bf16 v[52:55], v[202:205], v[190:193], v[52:55]
	v_mfma_f32_16x16x32_bf16 v[36:39], v[206:209], v[190:193], v[36:39]
	s_waitcnt vmcnt(12)
	ds_write_b128 v117, v[194:197] offset:12288
	v_mfma_f32_16x16x32_bf16 v[20:23], v[134:137], v[190:193], v[20:23]
	v_mfma_f32_16x16x32_bf16 v[4:7], v[170:173], v[190:193], v[4:7]
	s_waitcnt vmcnt(11)
	ds_write_b128 v117, v[162:165] offset:32768
	v_mfma_f32_16x16x32_bf16 v[48:51], v[202:205], v[198:201], v[48:51]
	v_mfma_f32_16x16x32_bf16 v[32:35], v[206:209], v[198:201], v[32:35]
	s_waitcnt vmcnt(10)
	ds_write_b128 v117, v[126:129] offset:36864
	v_mfma_f32_16x16x32_bf16 v[16:19], v[134:137], v[198:201], v[16:19]
	v_mfma_f32_16x16x32_bf16 v[0:3], v[170:173], v[198:201], v[0:3]
	s_waitcnt vmcnt(9)
	ds_write_b128 v117, v[166:169] offset:40960
	s_waitcnt vmcnt(8)
	ds_write_b128 v117, v[174:177] offset:45056
	s_setprio 0
	s_mov_b32 s42, s33
	s_waitcnt lgkmcnt(0)
	s_barrier
	s_cbranch_scc0 .LBB0_676
	s_waitcnt vmcnt(1)
	v_add_u32_e32 v88, s1, v122
	s_addk_i32 s1, 0xf000
	s_ashr_i32 s1, s1, 10
	s_add_i32 s1, s1, 1
	s_and_b64 s[42:43], s[22:23], exec
	s_cselect_b32 s1, 0, s1
	s_mul_i32 s2, s1, 0x3000
	s_add_i32 s28, s1, 5
	s_add_i32 s33, s2, 0xf000
	s_mul_hi_u32 s28, s28, 0x3000
	s_add_u32 s33, s4, s33
	s_addc_u32 s28, s5, s28
	s_add_u32 s44, s33, 0x2000
	s_addc_u32 s45, s28, 0
	s_add_i32 s1, s1, 10
	s_add_i32 s2, s2, 0x1e000
	s_mul_hi_u32 s1, s1, 0x3000
	s_add_u32 s2, s4, s2
	s_addc_u32 s1, s5, s1
	s_add_u32 s42, s2, 0x1000
	v_or_b32_e32 v96, s0, v123
	v_lshlrev_b64 v[72:73], 2, v[96:97]
	s_addc_u32 s43, s1, 0
	v_lshl_add_u64 v[56:57], s[44:45], 0, v[72:73]
	v_lshl_add_u64 v[70:71], s[12:13], 0, v[72:73]
	v_lshlrev_b32_e32 v58, 12, v88
	v_mov_b32_e32 v59, v97
	v_lshl_add_u64 v[74:75], s[42:43], 0, v[72:73]
	v_lshl_add_u64 v[68:69], v[70:71], 0, v[58:59]
	global_load_dwordx4 v[90:93], v[56:57], off
	s_nop 0
	global_load_dwordx4 v[56:59], v[68:69], off
	global_load_dwordx4 v[78:81], v[74:75], off
	v_lshl_add_u64 v[72:73], s[14:15], 0, v[72:73]
	global_load_dwordx4 v[82:85], v[72:73], off
	v_mov_b32_e32 v75, v97
	v_lshlrev_b32_e32 v74, 1, v96
	v_lshlrev_b32_e32 v89, 10, v88
	v_mov_b32_e32 v87, v97
	v_lshlrev_b32_e32 v86, 11, v88
	s_waitcnt vmcnt(4)
	v_lshl_add_u64 v[94:95], s[24:25], 0, v[74:75]
	v_or_b32_e32 v104, 0x4000, v89
	v_mov_b32_e32 v77, v97
	v_lshl_add_u64 v[74:75], v[94:95], 0, v[86:87]
	v_lshlrev_b32_e32 v76, 2, v104
	v_lshl_add_u64 v[98:99], v[70:71], 0, v[76:77]
	v_mov_b32_e32 v107, v97
	v_or_b32_e32 v106, 16, v96
	v_lshl_add_u64 v[86:87], s[24:25], 0, v[86:87]
	s_waitcnt vmcnt(2)
	v_pk_fma_f32 v[64:65], v[64:65], v[90:91], v[56:57]
	v_pk_fma_f32 v[66:67], v[66:67], v[92:93], v[58:59]
	s_waitcnt vmcnt(1)
	v_pk_add_f32 v[56:57], v[78:79], 1.0 op_sel_hi:[1,0]
	v_pk_add_f32 v[58:59], v[80:81], 1.0 op_sel_hi:[1,0]
	s_waitcnt vmcnt(0)
	v_pk_mul_f32 v[100:101], v[82:83], v[56:57]
	v_pk_mul_f32 v[102:103], v[84:85], v[58:59]
	v_pk_mul_f32 v[56:57], v[100:101], v[64:65]
	v_pk_mul_f32 v[58:59], v[102:103], v[66:67]
	v_cvt_pk_bf16_f32 v56, v56, v57
	v_cvt_pk_bf16_f32 v57, v58, v59
	global_store_dwordx4 v[68:69], v[64:67], off sc1
	global_store_dwordx2 v[74:75], v[56:57], off
	global_load_dwordx4 v[56:59], v[98:99], off
	v_mov_b32_e32 v79, v97
	v_or_b32_e32 v82, 0x8000, v89
	v_lshlrev_b32_e32 v78, 1, v104
	v_mov_b32_e32 v81, v97
	v_lshlrev_b32_e32 v80, 2, v82
	v_lshl_add_u64 v[74:75], v[94:95], 0, v[78:79]
	v_lshl_add_u64 v[104:105], v[70:71], 0, v[80:81]
	v_mov_b32_e32 v83, v97
	v_or_b32_e32 v89, 0xc000, v89
	v_lshlrev_b32_e32 v82, 1, v82
	v_mov_b32_e32 v85, v97
	v_lshlrev_b32_e32 v84, 2, v89
	v_pk_mul_f32 v[64:65], v[64:65], v[64:65]
	v_pk_mul_f32 v[66:67], v[66:67], v[66:67]
	v_add_f32_e32 v64, v64, v65
	v_add_f32_e32 v64, v66, v64
	v_add_f32_e32 v64, v67, v64
	s_waitcnt vmcnt(0)
	v_pk_fma_f32 v[56:57], v[60:61], v[90:91], v[56:57]
	v_pk_fma_f32 v[58:59], v[62:63], v[92:93], v[58:59]
	v_pk_mul_f32 v[60:61], v[100:101], v[56:57]
	v_pk_mul_f32 v[62:63], v[102:103], v[58:59]
	v_cvt_pk_bf16_f32 v60, v60, v61
	v_cvt_pk_bf16_f32 v61, v62, v63
	global_store_dwordx4 v[98:99], v[56:59], off sc1
	global_store_dwordx2 v[74:75], v[60:61], off
	global_load_dwordx4 v[60:63], v[104:105], off
	v_lshl_add_u64 v[74:75], v[94:95], 0, v[82:83]
	v_lshl_add_u64 v[98:99], v[70:71], 0, v[84:85]
	s_waitcnt vmcnt(0)
	v_pk_fma_f32 v[52:53], v[52:53], v[90:91], v[60:61]
	v_pk_fma_f32 v[54:55], v[54:55], v[92:93], v[62:63]
	v_pk_mul_f32 v[60:61], v[100:101], v[52:53]
	v_pk_mul_f32 v[62:63], v[102:103], v[54:55]
	v_cvt_pk_bf16_f32 v60, v60, v61
	v_cvt_pk_bf16_f32 v61, v62, v63
	global_store_dwordx4 v[104:105], v[52:55], off sc1
	global_store_dwordx2 v[74:75], v[60:61], off
	global_load_dwordx4 v[60:63], v[98:99], off
	v_mov_b32_e32 v75, v97
	v_lshlrev_b32_e32 v74, 1, v89
	v_lshlrev_b64 v[104:105], 2, v[106:107]
	v_lshl_add_u64 v[94:95], v[94:95], 0, v[74:75]
	v_lshl_add_u64 v[108:109], s[44:45], 0, v[104:105]
	s_waitcnt vmcnt(0)
	v_pk_fma_f32 v[48:49], v[48:49], v[90:91], v[60:61]
	v_pk_fma_f32 v[50:51], v[50:51], v[92:93], v[62:63]
	v_pk_mul_f32 v[60:61], v[100:101], v[48:49]
	v_pk_mul_f32 v[62:63], v[102:103], v[50:51]
	v_cvt_pk_bf16_f32 v60, v60, v61
	v_cvt_pk_bf16_f32 v61, v62, v63
	global_store_dwordx4 v[98:99], v[48:51], off sc1
	global_store_dwordx2 v[94:95], v[60:61], off
	global_load_dwordx4 v[90:93], v[108:109], off
	s_nop 0
	global_load_dwordx4 v[60:63], v[68:69], off offset:64
	v_lshl_add_u64 v[94:95], s[42:43], 0, v[104:105]
	global_load_dwordx4 v[98:101], v[94:95], off
	global_load_dwordx4 v[102:105], v[72:73], off offset:64
	v_mov_b32_e32 v95, v97
	v_lshlrev_b32_e32 v94, 1, v106
	v_lshl_add_u64 v[106:107], v[70:71], 0, 64
	v_lshl_add_u64 v[108:109], v[86:87], 0, v[94:95]
	v_lshl_add_u64 v[110:111], v[106:107], 0, v[76:77]
	v_lshl_add_u64 v[94:95], s[24:25], 0, v[94:95]
	s_waitcnt vmcnt(2)
	v_pk_fma_f32 v[60:61], v[40:41], v[90:91], v[60:61]
	v_pk_fma_f32 v[62:63], v[42:43], v[92:93], v[62:63]
	s_waitcnt vmcnt(1)
	v_pk_add_f32 v[40:41], v[98:99], 1.0 op_sel_hi:[1,0]
	v_pk_add_f32 v[42:43], v[100:101], 1.0 op_sel_hi:[1,0]
	s_waitcnt vmcnt(0)
	v_pk_mul_f32 v[98:99], v[102:103], v[40:41]
	v_pk_mul_f32 v[100:101], v[104:105], v[42:43]
	v_pk_mul_f32 v[40:41], v[98:99], v[60:61]
	v_pk_mul_f32 v[42:43], v[100:101], v[62:63]
	v_cvt_pk_bf16_f32 v40, v40, v41
	v_cvt_pk_bf16_f32 v41, v42, v43
	global_store_dwordx4 v[68:69], v[60:63], off offset:64 sc1
	global_store_dwordx2 v[108:109], v[40:41], off
	global_load_dwordx4 v[40:43], v[110:111], off
	v_lshl_add_u64 v[102:103], v[94:95], 0, v[78:79]
	v_lshl_add_u64 v[104:105], v[106:107], 0, v[80:81]
	v_lshl_add_u64 v[106:107], v[106:107], 0, v[84:85]
	v_mov_b32_e32 v109, v97
	v_or_b32_e32 v108, 32, v96
	v_or_b32_e32 v96, 48, v96
	v_pk_mul_f32 v[60:61], v[60:61], v[60:61]
	v_pk_mul_f32 v[62:63], v[62:63], v[62:63]
	v_add_f32_e32 v60, v60, v61
	v_add_f32_e32 v60, v62, v60
	v_add_f32_e32 v60, v63, v60
	v_add_f32_e32 v60, v64, v60
	s_waitcnt vmcnt(0)
	v_pk_fma_f32 v[40:41], v[44:45], v[90:91], v[40:41]
	v_pk_fma_f32 v[42:43], v[46:47], v[92:93], v[42:43]
	v_pk_mul_f32 v[44:45], v[98:99], v[40:41]
	v_pk_mul_f32 v[46:47], v[100:101], v[42:43]
	v_cvt_pk_bf16_f32 v44, v44, v45
	v_cvt_pk_bf16_f32 v45, v46, v47
	global_store_dwordx4 v[110:111], v[40:43], off sc1
	global_store_dwordx2 v[102:103], v[44:45], off
	global_load_dwordx4 v[44:47], v[104:105], off
	v_lshl_add_u64 v[102:103], v[94:95], 0, v[82:83]
	v_lshl_add_u64 v[94:95], v[94:95], 0, v[74:75]
	s_waitcnt vmcnt(0)
	v_pk_fma_f32 v[36:37], v[36:37], v[90:91], v[44:45]
	v_pk_fma_f32 v[38:39], v[38:39], v[92:93], v[46:47]
	v_pk_mul_f32 v[44:45], v[98:99], v[36:37]
	v_pk_mul_f32 v[46:47], v[100:101], v[38:39]
	v_cvt_pk_bf16_f32 v44, v44, v45
	v_cvt_pk_bf16_f32 v45, v46, v47
	global_store_dwordx4 v[104:105], v[36:39], off sc1
	global_store_dwordx2 v[102:103], v[44:45], off
	global_load_dwordx4 v[44:47], v[106:107], off
	v_lshlrev_b64 v[102:103], 2, v[108:109]
	v_lshl_add_u64 v[104:105], s[44:45], 0, v[102:103]
	s_waitcnt vmcnt(0)
	v_pk_fma_f32 v[32:33], v[32:33], v[90:91], v[44:45]
	v_pk_fma_f32 v[34:35], v[34:35], v[92:93], v[46:47]
	v_pk_mul_f32 v[44:45], v[98:99], v[32:33]
	v_pk_mul_f32 v[46:47], v[100:101], v[34:35]
	v_cvt_pk_bf16_f32 v44, v44, v45
	v_cvt_pk_bf16_f32 v45, v46, v47
	global_store_dwordx4 v[106:107], v[32:35], off sc1
	global_store_dwordx2 v[94:95], v[44:45], off
	global_load_dwordx4 v[44:47], v[104:105], off
	s_nop 0
	global_load_dwordx4 v[90:93], v[68:69], off offset:128
	v_lshl_add_u64 v[94:95], s[42:43], 0, v[102:103]
	global_load_dwordx4 v[98:101], v[94:95], off
	global_load_dwordx4 v[102:105], v[72:73], off offset:128
	v_mov_b32_e32 v95, v97
	v_lshlrev_b32_e32 v94, 1, v108
	v_lshl_add_u64 v[106:107], v[70:71], 0, s[38:39]
	v_lshl_add_u64 v[108:109], v[86:87], 0, v[94:95]
	v_lshl_add_u64 v[110:111], v[106:107], 0, v[76:77]
	v_lshl_add_u64 v[94:95], s[24:25], 0, v[94:95]
	s_waitcnt vmcnt(2)
	v_pk_fma_f32 v[28:29], v[28:29], v[44:45], v[90:91]
	v_pk_fma_f32 v[30:31], v[30:31], v[46:47], v[92:93]
	s_waitcnt vmcnt(1)
	v_pk_add_f32 v[90:91], v[98:99], 1.0 op_sel_hi:[1,0]
	v_pk_add_f32 v[92:93], v[100:101], 1.0 op_sel_hi:[1,0]
	s_waitcnt vmcnt(0)
	v_pk_mul_f32 v[98:99], v[102:103], v[90:91]
	v_pk_mul_f32 v[100:101], v[104:105], v[92:93]
	v_pk_mul_f32 v[90:91], v[98:99], v[28:29]
	v_pk_mul_f32 v[92:93], v[100:101], v[30:31]
	v_cvt_pk_bf16_f32 v90, v90, v91
	v_cvt_pk_bf16_f32 v91, v92, v93
	global_store_dwordx4 v[68:69], v[28:31], off offset:128 sc1
	global_store_dwordx2 v[108:109], v[90:91], off
	global_load_dwordx4 v[90:93], v[110:111], off
	v_lshl_add_u64 v[102:103], v[94:95], 0, v[78:79]
	v_lshl_add_u64 v[104:105], v[106:107], 0, v[80:81]
	v_lshl_add_u64 v[106:107], v[106:107], 0, v[84:85]
	v_pk_mul_f32 v[28:29], v[28:29], v[28:29]
	v_pk_mul_f32 v[30:31], v[30:31], v[30:31]
	v_add_f32_e32 v28, v28, v29
	v_add_f32_e32 v28, v30, v28
	v_add_f32_e32 v28, v31, v28
	v_add_f32_e32 v28, v60, v28
	s_waitcnt vmcnt(0)
	v_pk_fma_f32 v[24:25], v[24:25], v[44:45], v[90:91]
	v_pk_fma_f32 v[26:27], v[26:27], v[46:47], v[92:93]
	v_pk_mul_f32 v[90:91], v[98:99], v[24:25]
	v_pk_mul_f32 v[92:93], v[100:101], v[26:27]
	v_cvt_pk_bf16_f32 v90, v90, v91
	v_cvt_pk_bf16_f32 v91, v92, v93
	global_store_dwordx4 v[110:111], v[24:27], off sc1
	global_store_dwordx2 v[102:103], v[90:91], off
	global_load_dwordx4 v[90:93], v[104:105], off
	v_lshl_add_u64 v[102:103], v[94:95], 0, v[82:83]
	v_lshl_add_u64 v[94:95], v[94:95], 0, v[74:75]
	s_waitcnt vmcnt(0)
	v_pk_fma_f32 v[20:21], v[20:21], v[44:45], v[90:91]
	v_pk_fma_f32 v[22:23], v[22:23], v[46:47], v[92:93]
	v_pk_mul_f32 v[90:91], v[98:99], v[20:21]
	v_pk_mul_f32 v[92:93], v[100:101], v[22:23]
	v_cvt_pk_bf16_f32 v90, v90, v91
	v_cvt_pk_bf16_f32 v91, v92, v93
	global_store_dwordx4 v[104:105], v[20:23], off sc1
	global_store_dwordx2 v[102:103], v[90:91], off
	global_load_dwordx4 v[90:93], v[106:107], off
	v_lshlrev_b64 v[102:103], 2, v[96:97]
	v_lshl_add_u64 v[104:105], s[44:45], 0, v[102:103]
	v_lshlrev_b32_e32 v96, 1, v96
	s_waitcnt vmcnt(0)
	v_pk_fma_f32 v[16:17], v[16:17], v[44:45], v[90:91]
	v_pk_fma_f32 v[18:19], v[18:19], v[46:47], v[92:93]
	v_pk_mul_f32 v[44:45], v[98:99], v[16:17]
	v_pk_mul_f32 v[46:47], v[100:101], v[18:19]
	v_cvt_pk_bf16_f32 v44, v44, v45
	v_cvt_pk_bf16_f32 v45, v46, v47
	global_store_dwordx4 v[106:107], v[16:19], off sc1
	global_store_dwordx2 v[94:95], v[44:45], off
	global_load_dwordx4 v[44:47], v[104:105], off
	s_nop 0
	global_load_dwordx4 v[90:93], v[68:69], off offset:192
	v_lshl_add_u64 v[94:95], s[42:43], 0, v[102:103]
	global_load_dwordx4 v[98:101], v[94:95], off
	global_load_dwordx4 v[102:105], v[72:73], off offset:192
	v_lshl_add_u64 v[72:73], v[70:71], 0, s[40:41]
	v_lshl_add_u64 v[70:71], v[86:87], 0, v[96:97]
	v_lshl_add_u64 v[76:77], v[72:73], 0, v[76:77]
	v_lshl_add_u64 v[80:81], v[72:73], 0, v[80:81]
	v_lshl_add_u64 v[72:73], v[72:73], 0, v[84:85]
	s_waitcnt vmcnt(2)
	v_pk_fma_f32 v[12:13], v[12:13], v[44:45], v[90:91]
	s_waitcnt vmcnt(1)
	v_pk_add_f32 v[86:87], v[98:99], 1.0 op_sel_hi:[1,0]
	v_pk_add_f32 v[90:91], v[100:101], 1.0 op_sel_hi:[1,0]
	v_pk_fma_f32 v[14:15], v[14:15], v[46:47], v[92:93]
	s_waitcnt vmcnt(0)
	v_pk_mul_f32 v[86:87], v[102:103], v[86:87]
	v_pk_mul_f32 v[90:91], v[104:105], v[90:91]
	global_store_dwordx4 v[68:69], v[12:15], off offset:192 sc1
	v_pk_mul_f32 v[68:69], v[86:87], v[12:13]
	v_pk_mul_f32 v[92:93], v[90:91], v[14:15]
	v_cvt_pk_bf16_f32 v68, v68, v69
	v_cvt_pk_bf16_f32 v69, v92, v93
	global_store_dwordx2 v[70:71], v[68:69], off
	global_load_dwordx4 v[68:71], v[76:77], off
	v_lshl_add_u64 v[92:93], s[24:25], 0, v[96:97]
	v_lshl_add_u64 v[78:79], v[92:93], 0, v[78:79]
	v_pk_mul_f32 v[12:13], v[12:13], v[12:13]
	v_pk_mul_f32 v[14:15], v[14:15], v[14:15]
	v_add_f32_e32 v12, v12, v13
	v_add_f32_e32 v12, v14, v12
	v_add_f32_e32 v12, v15, v12
	v_add_f32_e32 v14, v28, v12
	ds_bpermute_b32 v15, v124, v14
	v_lshlrev_b32_e32 v96, 2, v88
	v_lshl_add_u64 v[12:13], v[92:93], 0, v[74:75]
	s_waitcnt lgkmcnt(0)
	v_add_f32_e32 v14, v14, v15
	ds_bpermute_b32 v15, v125, v14
	s_waitcnt vmcnt(0)
	v_pk_fma_f32 v[8:9], v[8:9], v[44:45], v[68:69]
	v_pk_fma_f32 v[10:11], v[10:11], v[46:47], v[70:71]
	v_pk_mul_f32 v[68:69], v[86:87], v[8:9]
	v_pk_mul_f32 v[70:71], v[90:91], v[10:11]
	v_cvt_pk_bf16_f32 v68, v68, v69
	v_cvt_pk_bf16_f32 v69, v70, v71
	global_store_dwordx4 v[76:77], v[8:11], off sc1
	global_store_dwordx2 v[78:79], v[68:69], off
	global_load_dwordx4 v[68:71], v[80:81], off
	v_lshl_add_u64 v[76:77], v[92:93], 0, v[82:83]
	s_waitcnt vmcnt(0)
	v_pk_fma_f32 v[4:5], v[4:5], v[44:45], v[68:69]
	v_pk_fma_f32 v[6:7], v[6:7], v[46:47], v[70:71]
	v_pk_mul_f32 v[68:69], v[86:87], v[4:5]
	v_pk_mul_f32 v[70:71], v[90:91], v[6:7]
	v_cvt_pk_bf16_f32 v68, v68, v69
	v_cvt_pk_bf16_f32 v69, v70, v71
	global_store_dwordx4 v[80:81], v[4:7], off sc1
	global_store_dwordx2 v[76:77], v[68:69], off
	global_load_dwordx4 v[68:71], v[72:73], off
	s_waitcnt vmcnt(0)
	v_pk_fma_f32 v[0:1], v[0:1], v[44:45], v[68:69]
	v_pk_fma_f32 v[2:3], v[2:3], v[46:47], v[70:71]
	v_pk_mul_f32 v[28:29], v[86:87], v[0:1]
	v_pk_mul_f32 v[30:31], v[90:91], v[2:3]
	v_cvt_pk_bf16_f32 v28, v28, v29
	v_cvt_pk_bf16_f32 v29, v30, v31
	global_store_dwordx4 v[72:73], v[0:3], off sc1
	global_store_dwordx2 v[12:13], v[28:29], off
	v_lshl_add_u64 v[12:13], s[26:27], 0, v[96:97]
	s_and_saveexec_b64 s[42:43], s[10:11]
	s_cbranch_execz .LBB0_679
	s_waitcnt lgkmcnt(0)
	v_add_f32_e32 v14, v14, v15
	global_atomic_add_f32 v[12:13], v14, off

.LBB0_804:
	s_or_b64 exec, exec, s[14:15]
	v_cvt_pk_bf16_f32 v114, v58, v59
	v_pk_mul_f32 v[58:59], v[20:21], v[62:63]
	v_cvt_pk_bf16_f32 v115, v92, v93
	v_and_b32_e32 v93, 0xffff0000, v48
	v_lshlrev_b32_e32 v92, 16, v48
	v_pk_fma_f32 v[58:59], v[16:17], v[98:99], v[58:59]
	v_cvt_pk_bf16_f32 v116, v100, v101
	v_pk_fma_f32 v[98:99], v[24:25], v[92:93], v[58:59]
	v_cndmask_b32_e64 v52, v109, v110, s[12:13]
	v_mul_f32_e32 v48, 0xbfb8aa3b, v98
	v_exp_f32_e32 v100, v48
	v_mul_f32_e32 v48, 0xbfb8aa3b, v99
	v_exp_f32_e32 v101, v48
	v_ashrrev_i32_e32 v89, 31, v88
	v_cndmask_b32_e64 v66, v52, v111, s[10:11]
	v_lshl_add_u64 v[52:53], s[22:23], 0, v[66:67]
	v_lshlrev_b64 v[88:89], 11, v[88:89]
	v_and_b32_e32 v66, 0x380, v79
	v_lshl_add_u64 v[52:53], v[52:53], 0, v[88:89]
	v_lshlrev_b32_e32 v66, 1, v66
	v_lshl_add_u64 v[52:53], v[52:53], 0, v[66:67]
	v_lshlrev_b32_e32 v66, 1, v64
	v_pk_add_f32 v[100:101], v[100:101], 1.0 op_sel_hi:[1,0]
	v_lshl_add_u64 v[52:53], v[52:53], 0, v[66:67]
	v_div_scale_f32 v66, s[0:1], v101, v101, v99
	v_rcp_f32_e32 v79, v66
	v_and_b32_e32 v59, 0xffff0000, v50
	v_lshlrev_b32_e32 v58, 16, v50
	v_and_b32_e32 v89, 0xffff0000, v49
	v_fma_f32 v50, -v66, v79, 1.0
	v_fmac_f32_e32 v79, v50, v79
	v_div_scale_f32 v50, vcc, v99, v101, v99
	v_lshlrev_b32_e32 v88, 16, v49
	v_and_b32_e32 v49, 0xffff0000, v51
	v_lshlrev_b32_e32 v48, 16, v51
	v_mul_f32_e32 v51, v50, v79
	v_fma_f32 v83, -v66, v51, v50
	v_fmac_f32_e32 v51, v83, v79
	v_cvt_pk_bf16_f32 v117, v102, v103
	v_fma_f32 v50, -v66, v51, v50
	v_div_scale_f32 v66, s[0:1], v100, v100, v98
	v_pk_mul_f32 v[102:103], v[22:23], v[60:61]
	v_rcp_f32_e32 v83, v66
	v_pk_fma_f32 v[96:97], v[18:19], v[96:97], v[102:103]
	v_div_fmas_f32 v50, v50, v79, v51
	v_pk_fma_f32 v[96:97], v[26:27], v[88:89], v[96:97]
	v_div_fixup_f32 v51, v50, v101, v99
	v_mul_f32_e32 v85, 0xbfb8aa3b, v96
	v_exp_f32_e32 v102, v85
	v_mul_f32_e32 v85, 0xbfb8aa3b, v97
	v_fma_f32 v50, -v66, v83, 1.0
	v_exp_f32_e32 v103, v85
	v_fmac_f32_e32 v83, v50, v83
	v_div_scale_f32 v50, vcc, v98, v100, v98
	v_mul_f32_e32 v79, v50, v83
	v_fma_f32 v85, -v66, v79, v50
	v_fmac_f32_e32 v79, v85, v83
	v_pk_add_f32 v[102:103], v[102:103], 1.0 op_sel_hi:[1,0]
	v_fma_f32 v50, -v66, v79, v50
	v_div_scale_f32 v66, s[0:1], v103, v103, v97
	v_rcp_f32_e32 v85, v66
	v_div_fmas_f32 v50, v50, v83, v79
	v_div_fixup_f32 v50, v50, v100, v98
	global_store_dwordx4 v[52:53], v[114:117], off sc1
	v_fma_f32 v79, -v66, v85, 1.0
	v_fmac_f32_e32 v85, v79, v85
	v_div_scale_f32 v79, vcc, v97, v103, v97
	v_mul_f32_e32 v83, v79, v85
	v_fma_f32 v98, -v66, v83, v79
	v_fmac_f32_e32 v83, v98, v85
	v_fma_f32 v66, -v66, v83, v79
	v_div_scale_f32 v79, s[0:1], v102, v102, v96
	v_pk_mul_f32 v[98:99], v[4:5], v[56:57]
	v_rcp_f32_e32 v100, v79
	v_pk_fma_f32 v[94:95], v[0:1], v[94:95], v[98:99]
	v_div_fmas_f32 v66, v66, v85, v83
	v_pk_fma_f32 v[94:95], v[8:9], v[58:59], v[94:95]
	v_div_fixup_f32 v97, v66, v103, v97
	v_mul_f32_e32 v85, 0xbfb8aa3b, v94
	v_exp_f32_e32 v98, v85
	v_mul_f32_e32 v85, 0xbfb8aa3b, v95
	v_fma_f32 v66, -v79, v100, 1.0
	v_exp_f32_e32 v99, v85
	v_fmac_f32_e32 v100, v66, v100
	v_div_scale_f32 v66, vcc, v96, v102, v96
	v_mul_f32_e32 v83, v66, v100
	v_fma_f32 v85, -v79, v83, v66
	v_fmac_f32_e32 v83, v85, v100
	v_pk_add_f32 v[98:99], v[98:99], 1.0 op_sel_hi:[1,0]
	v_fma_f32 v66, -v79, v83, v66
	v_div_scale_f32 v79, s[0:1], v99, v99, v95
	v_rcp_f32_e32 v85, v79
	v_div_fmas_f32 v66, v66, v100, v83
	v_div_fixup_f32 v96, v66, v102, v96
	v_fma_f32 v66, -v79, v85, 1.0
	v_fmac_f32_e32 v85, v66, v85
	v_div_scale_f32 v66, vcc, v95, v99, v95
	v_mul_f32_e32 v83, v66, v85
	v_fma_f32 v100, -v79, v83, v66
	v_fmac_f32_e32 v83, v100, v85
	v_fma_f32 v66, -v79, v83, v66
	v_div_scale_f32 v79, s[0:1], v98, v98, v94
	v_pk_mul_f32 v[100:101], v[6:7], v[54:55]
	v_rcp_f32_e32 v102, v79
	v_pk_fma_f32 v[90:91], v[2:3], v[90:91], v[100:101]
	v_div_fmas_f32 v66, v66, v85, v83
	v_pk_fma_f32 v[90:91], v[10:11], v[48:49], v[90:91]
	v_div_fixup_f32 v95, v66, v99, v95
	v_mul_f32_e32 v85, 0xbfb8aa3b, v90
	v_exp_f32_e32 v100, v85
	v_mul_f32_e32 v85, 0xbfb8aa3b, v91
	v_fma_f32 v66, -v79, v102, 1.0
	v_exp_f32_e32 v101, v85
	v_fmac_f32_e32 v102, v66, v102
	v_div_scale_f32 v66, vcc, v94, v98, v94
	v_mul_f32_e32 v83, v66, v102
	v_fma_f32 v85, -v79, v83, v66
	v_fmac_f32_e32 v83, v85, v102
	v_pk_add_f32 v[100:101], v[100:101], 1.0 op_sel_hi:[1,0]
	v_fma_f32 v66, -v79, v83, v66
	v_div_scale_f32 v79, s[0:1], v101, v101, v91
	v_rcp_f32_e32 v85, v79
	v_div_fmas_f32 v66, v66, v102, v83
	v_div_fixup_f32 v94, v66, v98, v94
	v_fma_f32 v66, -v79, v85, 1.0
	v_fmac_f32_e32 v85, v66, v85
	v_div_scale_f32 v66, vcc, v91, v101, v91
	v_mul_f32_e32 v83, v66, v85
	v_fma_f32 v98, -v79, v83, v66
	v_fmac_f32_e32 v83, v98, v85
	v_fma_f32 v66, -v79, v83, v66
	v_div_scale_f32 v79, s[0:1], v100, v100, v90
	v_rcp_f32_e32 v98, v79
	v_div_fmas_f32 v66, v66, v85, v83
	v_div_fixup_f32 v91, v66, v101, v91
	v_fma_f32 v66, -v79, v98, 1.0
	v_fmac_f32_e32 v98, v66, v98
	v_div_scale_f32 v66, vcc, v90, v100, v90
	v_mul_f32_e32 v83, v66, v98
	v_fma_f32 v85, -v79, v83, v66
	v_fmac_f32_e32 v83, v85, v98
	v_fma_f32 v66, -v79, v83, v66
	v_div_fmas_f32 v66, v66, v98, v83
	v_div_fixup_f32 v90, v66, v100, v90
	s_and_saveexec_b64 s[14:15], s[12:13]
	s_cbranch_execz .LBB0_806
	v_pk_mul_f32 v[98:99], v[50:51], v[50:51]
	v_pk_mul_f32 v[100:101], v[96:97], v[96:97]
	v_add_f32_e32 v66, v98, v99
	v_add_f32_e32 v66, v66, v100
	v_pk_mul_f32 v[102:103], v[94:95], v[94:95]
	v_add_f32_e32 v66, v66, v101
	v_and_b32_e32 v83, 64, v108
	v_add_f32_e32 v66, v66, v102
	v_xor_b32_e32 v79, 1, v108
	v_add_u32_e32 v83, 64, v83
	v_pk_mul_f32 v[114:115], v[90:91], v[90:91]
	v_add_f32_e32 v66, v66, v103
	v_cmp_lt_i32_e32 vcc, v79, v83
	v_add_f32_e32 v66, v66, v114
	v_add_f32_e32 v66, v66, v115
	v_cndmask_b32_e32 v79, v108, v79, vcc
	v_lshlrev_b32_e32 v79, 2, v79
	ds_bpermute_b32 v79, v79, v66
	s_waitcnt lgkmcnt(0)
	v_add_f32_e32 v66, v66, v79
	v_xor_b32_e32 v79, 2, v108
	v_cmp_lt_i32_e32 vcc, v79, v83
	s_nop 1
	v_cndmask_b32_e32 v79, v108, v79, vcc
	v_lshlrev_b32_e32 v79, 2, v79
	ds_bpermute_b32 v79, v79, v66
	s_waitcnt lgkmcnt(0)
	v_add_f32_e32 v66, v66, v79
	v_xor_b32_e32 v79, 4, v108
	v_cmp_lt_i32_e32 vcc, v79, v83
	s_nop 1
	v_cndmask_b32_e32 v79, v108, v79, vcc
	v_lshlrev_b32_e32 v79, 2, v79
	ds_bpermute_b32 v79, v79, v66
	s_waitcnt lgkmcnt(0)
	v_add_f32_e32 v66, v66, v79
	v_xor_b32_e32 v79, 8, v108
	v_cmp_lt_i32_e32 vcc, v79, v83
	s_nop 1
	v_cndmask_b32_e32 v79, v108, v79, vcc
	v_lshlrev_b32_e32 v79, 2, v79
	ds_bpermute_b32 v79, v79, v66
	s_waitcnt lgkmcnt(0)
	v_add_f32_e32 v66, v66, v79
	v_add_f32_e32 v66, 0x358637bd, v66
	v_mul_f32_e32 v79, 0x4b800000, v66
	v_cmp_gt_f32_e32 vcc, s49, v66
	s_nop 1
	v_cndmask_b32_e32 v66, v66, v79, vcc
	v_rsq_f32_e32 v66, v66
	s_nop 0
	v_mul_f32_e32 v79, 0x45800000, v66
	v_cndmask_b32_e32 v66, v66, v79, vcc
	v_mul_f32_e32 v79, 0x3db504f3, v66
	v_cndmask_b32_e64 v66, v66, v79, s[10:11]
	v_pk_mul_f32 v[50:51], v[50:51], v[66:67] op_sel_hi:[1,0]
	v_pk_mul_f32 v[96:97], v[96:97], v[66:67] op_sel_hi:[1,0]
	v_pk_mul_f32 v[94:95], v[94:95], v[66:67] op_sel_hi:[1,0]
	v_pk_mul_f32 v[90:91], v[90:91], v[66:67] op_sel_hi:[1,0]
.LBB0_806:
	s_or_b64 exec, exec, s[14:15]
	v_cvt_pk_bf16_f32 v98, v50, v51
	v_pk_mul_f32 v[50:51], v[20:21], v[92:93]
	v_cvt_pk_bf16_f32 v101, v90, v91
	v_and_b32_e32 v91, 0xffff0000, v44
	v_lshlrev_b32_e32 v90, 16, v44
	v_pk_fma_f32 v[50:51], v[16:17], v[62:63], v[50:51]
	v_cvt_pk_bf16_f32 v100, v94, v95
	v_pk_fma_f32 v[94:95], v[24:25], v[90:91], v[50:51]
	v_cvt_pk_bf16_f32 v99, v96, v97
	v_mul_f32_e32 v44, 0xbfb8aa3b, v94
	v_exp_f32_e32 v96, v44
	v_mul_f32_e32 v44, 0xbfb8aa3b, v95
	v_exp_f32_e32 v97, v44
	v_and_b32_e32 v51, 0xffff0000, v46
	v_lshlrev_b32_e32 v50, 16, v46
	v_and_b32_e32 v63, 0xffff0000, v45
	v_pk_add_f32 v[96:97], v[96:97], 1.0 op_sel_hi:[1,0]
	v_lshlrev_b32_e32 v62, 16, v45
	v_div_scale_f32 v66, s[0:1], v97, v97, v95
	v_rcp_f32_e32 v79, v66
	v_and_b32_e32 v45, 0xffff0000, v47
	v_lshlrev_b32_e32 v44, 16, v47
	global_store_dwordx4 v[52:53], v[98:101], off offset:2048 sc1
	v_fma_f32 v46, -v66, v79, 1.0
	v_fmac_f32_e32 v79, v46, v79
	v_div_scale_f32 v46, vcc, v95, v97, v95
	v_mul_f32_e32 v47, v46, v79
	v_fma_f32 v83, -v66, v47, v46
	v_fmac_f32_e32 v47, v83, v79
	v_fma_f32 v46, -v66, v47, v46
	v_div_scale_f32 v66, s[0:1], v96, v96, v94
	v_pk_mul_f32 v[98:99], v[22:23], v[88:89]
	v_rcp_f32_e32 v83, v66
	v_pk_fma_f32 v[60:61], v[18:19], v[60:61], v[98:99]
	v_div_fmas_f32 v46, v46, v79, v47
	v_pk_fma_f32 v[60:61], v[26:27], v[62:63], v[60:61]
	v_div_fixup_f32 v47, v46, v97, v95
	v_mul_f32_e32 v85, 0xbfb8aa3b, v60
	v_exp_f32_e32 v98, v85
	v_mul_f32_e32 v85, 0xbfb8aa3b, v61
	v_fma_f32 v46, -v66, v83, 1.0
	v_exp_f32_e32 v99, v85
	v_fmac_f32_e32 v83, v46, v83
	v_div_scale_f32 v46, vcc, v94, v96, v94
	v_mul_f32_e32 v79, v46, v83
	v_fma_f32 v85, -v66, v79, v46
	v_fmac_f32_e32 v79, v85, v83
	v_pk_add_f32 v[98:99], v[98:99], 1.0 op_sel_hi:[1,0]
	v_fma_f32 v46, -v66, v79, v46
	v_div_scale_f32 v66, s[0:1], v99, v99, v61
	v_rcp_f32_e32 v85, v66
	v_div_fmas_f32 v46, v46, v83, v79
	v_div_fixup_f32 v46, v46, v96, v94
	v_fma_f32 v79, -v66, v85, 1.0
	v_fmac_f32_e32 v85, v79, v85
	v_div_scale_f32 v79, vcc, v61, v99, v61
	v_mul_f32_e32 v83, v79, v85
	v_fma_f32 v94, -v66, v83, v79
	v_fmac_f32_e32 v83, v94, v85
	v_fma_f32 v66, -v66, v83, v79
	v_div_scale_f32 v79, s[0:1], v98, v98, v60
	v_pk_mul_f32 v[94:95], v[4:5], v[58:59]
	v_rcp_f32_e32 v96, v79
	v_pk_fma_f32 v[56:57], v[0:1], v[56:57], v[94:95]
	v_div_fmas_f32 v66, v66, v85, v83
	v_pk_fma_f32 v[56:57], v[8:9], v[50:51], v[56:57]
	v_div_fixup_f32 v61, v66, v99, v61
	v_mul_f32_e32 v85, 0xbfb8aa3b, v56
	v_exp_f32_e32 v94, v85
	v_mul_f32_e32 v85, 0xbfb8aa3b, v57
	v_fma_f32 v66, -v79, v96, 1.0
	v_exp_f32_e32 v95, v85
	v_fmac_f32_e32 v96, v66, v96
	v_div_scale_f32 v66, vcc, v60, v98, v60
	v_mul_f32_e32 v83, v66, v96
	v_fma_f32 v85, -v79, v83, v66
	v_fmac_f32_e32 v83, v85, v96
	v_pk_add_f32 v[94:95], v[94:95], 1.0 op_sel_hi:[1,0]
	v_fma_f32 v66, -v79, v83, v66
	v_div_scale_f32 v79, s[0:1], v95, v95, v57
	v_rcp_f32_e32 v85, v79
	v_div_fmas_f32 v66, v66, v96, v83
	v_div_fixup_f32 v60, v66, v98, v60
	v_fma_f32 v66, -v79, v85, 1.0
	v_fmac_f32_e32 v85, v66, v85
	v_div_scale_f32 v66, vcc, v57, v95, v57
	v_mul_f32_e32 v83, v66, v85
	v_fma_f32 v96, -v79, v83, v66
	v_fmac_f32_e32 v83, v96, v85
	v_fma_f32 v66, -v79, v83, v66
	v_div_scale_f32 v79, s[0:1], v94, v94, v56
	v_pk_mul_f32 v[96:97], v[6:7], v[48:49]
	v_rcp_f32_e32 v98, v79
	v_pk_fma_f32 v[54:55], v[2:3], v[54:55], v[96:97]
	v_div_fmas_f32 v66, v66, v85, v83
	v_pk_fma_f32 v[54:55], v[10:11], v[44:45], v[54:55]
	v_div_fixup_f32 v57, v66, v95, v57
	v_mul_f32_e32 v85, 0xbfb8aa3b, v54
	v_exp_f32_e32 v96, v85
	v_mul_f32_e32 v85, 0xbfb8aa3b, v55
	v_fma_f32 v66, -v79, v98, 1.0
	v_exp_f32_e32 v97, v85
	v_fmac_f32_e32 v98, v66, v98
	v_div_scale_f32 v66, vcc, v56, v94, v56
	v_mul_f32_e32 v83, v66, v98
	v_fma_f32 v85, -v79, v83, v66
	v_fmac_f32_e32 v83, v85, v98
	v_pk_add_f32 v[96:97], v[96:97], 1.0 op_sel_hi:[1,0]
	v_fma_f32 v66, -v79, v83, v66
	v_div_scale_f32 v79, s[0:1], v97, v97, v55
	v_rcp_f32_e32 v85, v79
	v_div_fmas_f32 v66, v66, v98, v83
	v_div_fixup_f32 v56, v66, v94, v56
	v_fma_f32 v66, -v79, v85, 1.0
	v_fmac_f32_e32 v85, v66, v85
	v_div_scale_f32 v66, vcc, v55, v97, v55
	v_mul_f32_e32 v83, v66, v85
	v_fma_f32 v94, -v79, v83, v66
	v_fmac_f32_e32 v83, v94, v85
	v_fma_f32 v66, -v79, v83, v66
	v_div_scale_f32 v79, s[0:1], v96, v96, v54
	v_rcp_f32_e32 v94, v79
	v_div_fmas_f32 v66, v66, v85, v83
	v_div_fixup_f32 v55, v66, v97, v55
	v_fma_f32 v66, -v79, v94, 1.0
	v_fmac_f32_e32 v94, v66, v94
	v_div_scale_f32 v66, vcc, v54, v96, v54
	v_mul_f32_e32 v83, v66, v94
	v_fma_f32 v85, -v79, v83, v66
	v_fmac_f32_e32 v83, v85, v94
	v_fma_f32 v66, -v79, v83, v66
	v_div_fmas_f32 v66, v66, v94, v83
	v_div_fixup_f32 v54, v66, v96, v54
	s_and_saveexec_b64 s[14:15], s[12:13]
	s_cbranch_execz .LBB0_808
	v_pk_mul_f32 v[94:95], v[46:47], v[46:47]
	v_pk_mul_f32 v[96:97], v[60:61], v[60:61]
	v_add_f32_e32 v66, v94, v95
	v_add_f32_e32 v66, v66, v96
	v_pk_mul_f32 v[98:99], v[56:57], v[56:57]
	v_add_f32_e32 v66, v66, v97
	v_and_b32_e32 v83, 64, v108
	v_add_f32_e32 v66, v66, v98
	v_xor_b32_e32 v79, 1, v108
	v_add_u32_e32 v83, 64, v83
	v_pk_mul_f32 v[100:101], v[54:55], v[54:55]
	v_add_f32_e32 v66, v66, v99
	v_cmp_lt_i32_e32 vcc, v79, v83
	v_add_f32_e32 v66, v66, v100
	v_add_f32_e32 v66, v66, v101
	v_cndmask_b32_e32 v79, v108, v79, vcc
	v_lshlrev_b32_e32 v79, 2, v79
	ds_bpermute_b32 v79, v79, v66
	s_waitcnt lgkmcnt(0)
	v_add_f32_e32 v66, v66, v79
	v_xor_b32_e32 v79, 2, v108
	v_cmp_lt_i32_e32 vcc, v79, v83
	s_nop 1
	v_cndmask_b32_e32 v79, v108, v79, vcc
	v_lshlrev_b32_e32 v79, 2, v79
	ds_bpermute_b32 v79, v79, v66
	s_waitcnt lgkmcnt(0)
	v_add_f32_e32 v66, v66, v79
	v_xor_b32_e32 v79, 4, v108
	v_cmp_lt_i32_e32 vcc, v79, v83
	s_nop 1
	v_cndmask_b32_e32 v79, v108, v79, vcc
	v_lshlrev_b32_e32 v79, 2, v79
	ds_bpermute_b32 v79, v79, v66
	s_waitcnt lgkmcnt(0)
	v_add_f32_e32 v66, v66, v79
	v_xor_b32_e32 v79, 8, v108
	v_cmp_lt_i32_e32 vcc, v79, v83
	s_nop 1
	v_cndmask_b32_e32 v79, v108, v79, vcc
	v_lshlrev_b32_e32 v79, 2, v79
	ds_bpermute_b32 v79, v79, v66
	s_waitcnt lgkmcnt(0)
	v_add_f32_e32 v66, v66, v79
	v_add_f32_e32 v66, 0x358637bd, v66
	v_mul_f32_e32 v79, 0x4b800000, v66
	v_cmp_gt_f32_e32 vcc, s49, v66
	s_nop 1
	v_cndmask_b32_e32 v66, v66, v79, vcc
	v_rsq_f32_e32 v66, v66
	s_nop 0
	v_mul_f32_e32 v79, 0x45800000, v66
	v_cndmask_b32_e32 v66, v66, v79, vcc
	v_mul_f32_e32 v79, 0x3db504f3, v66
	v_cndmask_b32_e64 v66, v66, v79, s[10:11]
	v_pk_mul_f32 v[46:47], v[46:47], v[66:67] op_sel_hi:[1,0]
	v_pk_mul_f32 v[60:61], v[60:61], v[66:67] op_sel_hi:[1,0]
	v_pk_mul_f32 v[56:57], v[56:57], v[66:67] op_sel_hi:[1,0]
	v_pk_mul_f32 v[54:55], v[54:55], v[66:67] op_sel_hi:[1,0]
.LBB0_808:
	s_or_b64 exec, exec, s[14:15]
	v_cvt_pk_bf16_f32 v94, v46, v47
	v_pk_mul_f32 v[46:47], v[20:21], v[90:91]
	v_cvt_pk_bf16_f32 v95, v60, v61
	v_and_b32_e32 v61, 0xffff0000, v40
	v_lshlrev_b32_e32 v60, 16, v40
	v_pk_fma_f32 v[46:47], v[16:17], v[92:93], v[46:47]
	v_cvt_pk_bf16_f32 v96, v56, v57
	v_add_co_u32_e32 v56, vcc, s50, v52
	v_pk_fma_f32 v[92:93], v[24:25], v[60:61], v[46:47]
	v_cvt_pk_bf16_f32 v97, v54, v55
	v_addc_co_u32_e32 v57, vcc, 0, v53, vcc
	v_mul_f32_e32 v40, 0xbfb8aa3b, v92
	global_store_dwordx4 v[56:57], v[94:97], off sc1
	v_and_b32_e32 v47, 0xffff0000, v42
	v_lshlrev_b32_e32 v46, 16, v42
	v_exp_f32_e32 v94, v40
	v_mul_f32_e32 v40, 0xbfb8aa3b, v93
	v_exp_f32_e32 v95, v40
	v_and_b32_e32 v55, 0xffff0000, v41
	v_lshlrev_b32_e32 v54, 16, v41
	v_and_b32_e32 v41, 0xffff0000, v43
	v_pk_add_f32 v[94:95], v[94:95], 1.0 op_sel_hi:[1,0]
	v_lshlrev_b32_e32 v40, 16, v43
	v_div_scale_f32 v66, s[0:1], v95, v95, v93
	v_rcp_f32_e32 v79, v66
	v_pk_mul_f32 v[96:97], v[22:23], v[62:63]
	v_fma_f32 v42, -v66, v79, 1.0
	v_fmac_f32_e32 v79, v42, v79
	v_div_scale_f32 v42, vcc, v93, v95, v93
	v_mul_f32_e32 v43, v42, v79
	v_fma_f32 v83, -v66, v43, v42
	v_fmac_f32_e32 v43, v83, v79
	v_fma_f32 v42, -v66, v43, v42
	v_div_scale_f32 v66, s[0:1], v94, v94, v92
	v_rcp_f32_e32 v83, v66
	v_pk_fma_f32 v[88:89], v[18:19], v[88:89], v[96:97]
	v_div_fmas_f32 v42, v42, v79, v43
	v_pk_fma_f32 v[88:89], v[26:27], v[54:55], v[88:89]
	v_div_fixup_f32 v43, v42, v95, v93
	v_mul_f32_e32 v85, 0xbfb8aa3b, v88
	v_exp_f32_e32 v96, v85
	v_mul_f32_e32 v85, 0xbfb8aa3b, v89
	v_fma_f32 v42, -v66, v83, 1.0
	v_exp_f32_e32 v97, v85
	v_fmac_f32_e32 v83, v42, v83
	v_div_scale_f32 v42, vcc, v92, v94, v92
	v_mul_f32_e32 v79, v42, v83
	v_fma_f32 v85, -v66, v79, v42
	v_fmac_f32_e32 v79, v85, v83
	v_pk_add_f32 v[96:97], v[96:97], 1.0 op_sel_hi:[1,0]
	v_fma_f32 v42, -v66, v79, v42
	v_div_scale_f32 v66, s[0:1], v97, v97, v89
	v_rcp_f32_e32 v85, v66
	v_div_fmas_f32 v42, v42, v83, v79
	v_div_fixup_f32 v42, v42, v94, v92
	v_fma_f32 v79, -v66, v85, 1.0
	v_fmac_f32_e32 v85, v79, v85
	v_div_scale_f32 v79, vcc, v89, v97, v89
	v_mul_f32_e32 v83, v79, v85
	v_fma_f32 v92, -v66, v83, v79
	v_fmac_f32_e32 v83, v92, v85
	v_fma_f32 v66, -v66, v83, v79
	v_div_scale_f32 v79, s[0:1], v96, v96, v88
	v_pk_mul_f32 v[92:93], v[4:5], v[50:51]
	v_rcp_f32_e32 v94, v79
	v_pk_fma_f32 v[58:59], v[0:1], v[58:59], v[92:93]
	v_div_fmas_f32 v66, v66, v85, v83
	v_pk_fma_f32 v[58:59], v[8:9], v[46:47], v[58:59]
	v_div_fixup_f32 v89, v66, v97, v89
	v_mul_f32_e32 v85, 0xbfb8aa3b, v58
	v_exp_f32_e32 v92, v85
	v_mul_f32_e32 v85, 0xbfb8aa3b, v59
	v_fma_f32 v66, -v79, v94, 1.0
	v_exp_f32_e32 v93, v85
	v_fmac_f32_e32 v94, v66, v94
	v_div_scale_f32 v66, vcc, v88, v96, v88
	v_mul_f32_e32 v83, v66, v94
	v_fma_f32 v85, -v79, v83, v66
	v_fmac_f32_e32 v83, v85, v94
	v_pk_add_f32 v[92:93], v[92:93], 1.0 op_sel_hi:[1,0]
	v_fma_f32 v66, -v79, v83, v66
	v_div_scale_f32 v79, s[0:1], v93, v93, v59
	v_rcp_f32_e32 v85, v79
	v_div_fmas_f32 v66, v66, v94, v83
	v_div_fixup_f32 v88, v66, v96, v88
	v_fma_f32 v66, -v79, v85, 1.0
	v_fmac_f32_e32 v85, v66, v85
	v_div_scale_f32 v66, vcc, v59, v93, v59
	v_mul_f32_e32 v83, v66, v85
	v_fma_f32 v94, -v79, v83, v66
	v_fmac_f32_e32 v83, v94, v85
	v_fma_f32 v66, -v79, v83, v66
	v_div_scale_f32 v79, s[0:1], v92, v92, v58
	v_pk_mul_f32 v[94:95], v[6:7], v[44:45]
	v_rcp_f32_e32 v96, v79
	v_pk_fma_f32 v[48:49], v[2:3], v[48:49], v[94:95]
	v_div_fmas_f32 v66, v66, v85, v83
	v_pk_fma_f32 v[48:49], v[10:11], v[40:41], v[48:49]
	v_div_fixup_f32 v59, v66, v93, v59
	v_mul_f32_e32 v85, 0xbfb8aa3b, v48
	v_exp_f32_e32 v94, v85
	v_mul_f32_e32 v85, 0xbfb8aa3b, v49
	v_fma_f32 v66, -v79, v96, 1.0
	v_exp_f32_e32 v95, v85
	v_fmac_f32_e32 v96, v66, v96
	v_div_scale_f32 v66, vcc, v58, v92, v58
	v_mul_f32_e32 v83, v66, v96
	v_fma_f32 v85, -v79, v83, v66
	v_fmac_f32_e32 v83, v85, v96
	v_pk_add_f32 v[94:95], v[94:95], 1.0 op_sel_hi:[1,0]
	v_fma_f32 v66, -v79, v83, v66
	v_div_scale_f32 v79, s[0:1], v95, v95, v49
	v_rcp_f32_e32 v85, v79
	v_div_fmas_f32 v66, v66, v96, v83
	v_div_fixup_f32 v58, v66, v92, v58
	v_fma_f32 v66, -v79, v85, 1.0
	v_fmac_f32_e32 v85, v66, v85
	v_div_scale_f32 v66, vcc, v49, v95, v49
	v_mul_f32_e32 v83, v66, v85
	v_fma_f32 v92, -v79, v83, v66
	v_fmac_f32_e32 v83, v92, v85
	v_fma_f32 v66, -v79, v83, v66
	v_div_scale_f32 v79, s[0:1], v94, v94, v48
	v_rcp_f32_e32 v92, v79
	v_div_fmas_f32 v66, v66, v85, v83
	v_div_fixup_f32 v49, v66, v95, v49
	v_fma_f32 v66, -v79, v92, 1.0
	v_fmac_f32_e32 v92, v66, v92
	v_div_scale_f32 v66, vcc, v48, v94, v48
	v_mul_f32_e32 v83, v66, v92
	v_fma_f32 v85, -v79, v83, v66
	v_fmac_f32_e32 v83, v85, v92
	v_fma_f32 v66, -v79, v83, v66
	v_div_fmas_f32 v66, v66, v92, v83
	v_div_fixup_f32 v48, v66, v94, v48
	s_and_saveexec_b64 s[14:15], s[12:13]
	s_cbranch_execz .LBB0_810
	v_pk_mul_f32 v[92:93], v[42:43], v[42:43]
	v_pk_mul_f32 v[94:95], v[88:89], v[88:89]
	v_add_f32_e32 v66, v92, v93
	v_add_f32_e32 v66, v66, v94
	v_pk_mul_f32 v[96:97], v[58:59], v[58:59]
	v_add_f32_e32 v66, v66, v95
	v_and_b32_e32 v83, 64, v108
	v_add_f32_e32 v66, v66, v96
	v_xor_b32_e32 v79, 1, v108
	v_add_u32_e32 v83, 64, v83
	v_pk_mul_f32 v[98:99], v[48:49], v[48:49]
	v_add_f32_e32 v66, v66, v97
	v_cmp_lt_i32_e32 vcc, v79, v83
	v_add_f32_e32 v66, v66, v98
	v_add_f32_e32 v66, v66, v99
	v_cndmask_b32_e32 v79, v108, v79, vcc
	v_lshlrev_b32_e32 v79, 2, v79
	ds_bpermute_b32 v79, v79, v66
	s_waitcnt lgkmcnt(0)
	v_add_f32_e32 v66, v66, v79
	v_xor_b32_e32 v79, 2, v108
	v_cmp_lt_i32_e32 vcc, v79, v83
	s_nop 1
	v_cndmask_b32_e32 v79, v108, v79, vcc
	v_lshlrev_b32_e32 v79, 2, v79
	ds_bpermute_b32 v79, v79, v66
	s_waitcnt lgkmcnt(0)
	v_add_f32_e32 v66, v66, v79
	v_xor_b32_e32 v79, 4, v108
	v_cmp_lt_i32_e32 vcc, v79, v83
	s_nop 1
	v_cndmask_b32_e32 v79, v108, v79, vcc
	v_lshlrev_b32_e32 v79, 2, v79
	ds_bpermute_b32 v79, v79, v66
	s_waitcnt lgkmcnt(0)
	v_add_f32_e32 v66, v66, v79
	v_xor_b32_e32 v79, 8, v108
	v_cmp_lt_i32_e32 vcc, v79, v83
	s_nop 1
	v_cndmask_b32_e32 v79, v108, v79, vcc
	v_lshlrev_b32_e32 v79, 2, v79
	ds_bpermute_b32 v79, v79, v66
	s_waitcnt lgkmcnt(0)
	v_add_f32_e32 v66, v66, v79
	v_add_f32_e32 v66, 0x358637bd, v66
	v_mul_f32_e32 v79, 0x4b800000, v66
	v_cmp_gt_f32_e32 vcc, s49, v66
	s_nop 1
	v_cndmask_b32_e32 v66, v66, v79, vcc
	v_rsq_f32_e32 v66, v66
	s_nop 0
	v_mul_f32_e32 v79, 0x45800000, v66
	v_cndmask_b32_e32 v66, v66, v79, vcc
	v_mul_f32_e32 v79, 0x3db504f3, v66
	v_cndmask_b32_e64 v66, v66, v79, s[10:11]
	v_pk_mul_f32 v[42:43], v[42:43], v[66:67] op_sel_hi:[1,0]
	v_pk_mul_f32 v[88:89], v[88:89], v[66:67] op_sel_hi:[1,0]
	v_pk_mul_f32 v[58:59], v[58:59], v[66:67] op_sel_hi:[1,0]
	v_pk_mul_f32 v[48:49], v[48:49], v[66:67] op_sel_hi:[1,0]
.LBB0_810:
	s_or_b64 exec, exec, s[14:15]
	v_cvt_pk_bf16_f32 v92, v42, v43
	v_cvt_pk_bf16_f32 v93, v88, v89
	v_cvt_pk_bf16_f32 v94, v58, v59
	v_cvt_pk_bf16_f32 v95, v48, v49
	v_pk_mul_f32 v[42:43], v[20:21], v[60:61]
	global_store_dwordx4 v[56:57], v[92:95], off offset:2048 sc1
	v_and_b32_e32 v57, 0xffff0000, v36
	v_lshlrev_b32_e32 v56, 16, v36
	v_pk_fma_f32 v[42:43], v[16:17], v[90:91], v[42:43]
	v_and_b32_e32 v49, 0xffff0000, v37
	v_pk_fma_f32 v[58:59], v[24:25], v[56:57], v[42:43]
	v_and_b32_e32 v43, 0xffff0000, v38
	v_mul_f32_e32 v36, 0xbfb8aa3b, v58
	v_exp_f32_e32 v88, v36
	v_mul_f32_e32 v36, 0xbfb8aa3b, v59
	v_exp_f32_e32 v89, v36
	v_lshlrev_b32_e32 v42, 16, v38
	v_lshlrev_b32_e32 v48, 16, v37
	v_and_b32_e32 v37, 0xffff0000, v39
	v_pk_add_f32 v[88:89], v[88:89], 1.0 op_sel_hi:[1,0]
	v_lshlrev_b32_e32 v36, 16, v39
	v_div_scale_f32 v66, s[0:1], v89, v89, v59
	v_rcp_f32_e32 v79, v66
	v_pk_mul_f32 v[90:91], v[22:23], v[54:55]
	v_fma_f32 v38, -v66, v79, 1.0
	v_fmac_f32_e32 v79, v38, v79
	v_div_scale_f32 v38, vcc, v59, v89, v59
	v_mul_f32_e32 v39, v38, v79
	v_fma_f32 v83, -v66, v39, v38
	v_fmac_f32_e32 v39, v83, v79
	v_fma_f32 v38, -v66, v39, v38
	v_div_scale_f32 v66, s[0:1], v88, v88, v58
	v_rcp_f32_e32 v83, v66
	v_pk_fma_f32 v[62:63], v[18:19], v[62:63], v[90:91]
	v_div_fmas_f32 v38, v38, v79, v39
	v_pk_fma_f32 v[62:63], v[26:27], v[48:49], v[62:63]
	v_div_fixup_f32 v39, v38, v89, v59
	v_mul_f32_e32 v79, 0xbfb8aa3b, v62
	v_exp_f32_e32 v90, v79
	v_mul_f32_e32 v79, 0xbfb8aa3b, v63
	v_fma_f32 v38, -v66, v83, 1.0
	v_exp_f32_e32 v91, v79
	v_fmac_f32_e32 v83, v38, v83
	v_div_scale_f32 v38, vcc, v58, v88, v58
	v_mul_f32_e32 v59, v38, v83
	v_fma_f32 v79, -v66, v59, v38
	v_fmac_f32_e32 v59, v79, v83
	v_pk_add_f32 v[90:91], v[90:91], 1.0 op_sel_hi:[1,0]
	v_fma_f32 v38, -v66, v59, v38
	v_div_scale_f32 v66, s[0:1], v91, v91, v63
	v_rcp_f32_e32 v79, v66
	v_div_fmas_f32 v38, v38, v83, v59
	v_div_fixup_f32 v38, v38, v88, v58
	v_pk_mul_f32 v[88:89], v[4:5], v[46:47]
	v_fma_f32 v58, -v66, v79, 1.0
	v_fmac_f32_e32 v79, v58, v79
	v_div_scale_f32 v58, vcc, v63, v91, v63
	v_mul_f32_e32 v59, v58, v79
	v_fma_f32 v83, -v66, v59, v58
	v_fmac_f32_e32 v59, v83, v79
	v_fma_f32 v58, -v66, v59, v58
	v_div_scale_f32 v66, s[0:1], v90, v90, v62
	v_rcp_f32_e32 v83, v66
	v_pk_fma_f32 v[50:51], v[0:1], v[50:51], v[88:89]
	v_div_fmas_f32 v58, v58, v79, v59
	v_pk_fma_f32 v[50:51], v[8:9], v[42:43], v[50:51]
	v_div_fixup_f32 v59, v58, v91, v63
	v_mul_f32_e32 v79, 0xbfb8aa3b, v50
	v_exp_f32_e32 v88, v79
	v_mul_f32_e32 v79, 0xbfb8aa3b, v51
	v_fma_f32 v58, -v66, v83, 1.0
	v_exp_f32_e32 v89, v79
	v_fmac_f32_e32 v83, v58, v83
	v_div_scale_f32 v58, vcc, v62, v90, v62
	v_mul_f32_e32 v63, v58, v83
	v_fma_f32 v79, -v66, v63, v58
	v_fmac_f32_e32 v63, v79, v83
	v_pk_add_f32 v[88:89], v[88:89], 1.0 op_sel_hi:[1,0]
	v_fma_f32 v58, -v66, v63, v58
	v_div_scale_f32 v66, s[0:1], v89, v89, v51
	v_rcp_f32_e32 v79, v66
	v_div_fmas_f32 v58, v58, v83, v63
	v_div_fixup_f32 v58, v58, v90, v62
	v_fma_f32 v62, -v66, v79, 1.0
	v_fmac_f32_e32 v79, v62, v79
	v_div_scale_f32 v62, vcc, v51, v89, v51
	v_mul_f32_e32 v63, v62, v79
	v_fma_f32 v83, -v66, v63, v62
	v_fmac_f32_e32 v63, v83, v79
	v_fma_f32 v62, -v66, v63, v62
	v_div_scale_f32 v66, s[0:1], v88, v88, v50
	v_rcp_f32_e32 v83, v66
	v_div_fmas_f32 v62, v62, v79, v63
	v_div_fixup_f32 v51, v62, v89, v51
	v_div_scale_f32 v79, vcc, v50, v88, v50
	v_fma_f32 v62, -v66, v83, 1.0
	v_fmac_f32_e32 v83, v62, v83
	v_pk_mul_f32 v[62:63], v[6:7], v[40:41]
	v_mul_f32_e32 v85, v79, v83
	v_pk_fma_f32 v[44:45], v[2:3], v[44:45], v[62:63]
	v_fma_f32 v89, -v66, v85, v79
	v_pk_fma_f32 v[44:45], v[10:11], v[36:37], v[44:45]
	v_fmac_f32_e32 v85, v89, v83
	v_mul_f32_e32 v62, 0xbfb8aa3b, v44
	v_mul_f32_e32 v63, 0xbfb8aa3b, v45
	v_exp_f32_e32 v62, v62
	v_exp_f32_e32 v63, v63
	v_fma_f32 v66, -v66, v85, v79
	v_div_fmas_f32 v66, v66, v83, v85
	v_div_fixup_f32 v50, v66, v88, v50
	v_pk_add_f32 v[62:63], v[62:63], 1.0 op_sel_hi:[1,0]
	s_nop 0
	v_div_scale_f32 v79, s[0:1], v63, v63, v45
	v_rcp_f32_e32 v89, v79
	s_nop 0
	v_fma_f32 v66, -v79, v89, 1.0
	v_fmac_f32_e32 v89, v66, v89
	v_div_scale_f32 v66, vcc, v45, v63, v45
	v_mul_f32_e32 v83, v66, v89
	v_fma_f32 v85, -v79, v83, v66
	v_fmac_f32_e32 v83, v85, v89
	v_fma_f32 v66, -v79, v83, v66
	v_div_scale_f32 v79, s[0:1], v62, v62, v44
	v_rcp_f32_e32 v85, v79
	v_div_fmas_f32 v66, v66, v89, v83
	v_div_fixup_f32 v45, v66, v63, v45
	v_fma_f32 v63, -v79, v85, 1.0
	v_fmac_f32_e32 v85, v63, v85
	v_div_scale_f32 v63, vcc, v44, v62, v44
	v_mul_f32_e32 v66, v63, v85
	v_fma_f32 v83, -v79, v66, v63
	v_fmac_f32_e32 v66, v83, v85
	v_fma_f32 v63, -v79, v66, v63
	v_div_fmas_f32 v63, v63, v85, v66
	v_div_fixup_f32 v44, v63, v62, v44
	s_and_saveexec_b64 s[14:15], s[12:13]
	s_cbranch_execz .LBB0_812
	v_pk_mul_f32 v[62:63], v[38:39], v[38:39]
	v_pk_mul_f32 v[88:89], v[58:59], v[58:59]
	v_add_f32_e32 v62, v62, v63
	v_add_f32_e32 v62, v62, v88
	v_pk_mul_f32 v[90:91], v[50:51], v[50:51]
	v_add_f32_e32 v62, v62, v89
	v_and_b32_e32 v66, 64, v108
	v_add_f32_e32 v62, v62, v90
	v_xor_b32_e32 v63, 1, v108
	v_add_u32_e32 v66, 64, v66
	v_pk_mul_f32 v[92:93], v[44:45], v[44:45]
	v_add_f32_e32 v62, v62, v91
	v_cmp_lt_i32_e32 vcc, v63, v66
	v_add_f32_e32 v62, v62, v92
	v_add_f32_e32 v62, v62, v93
	v_cndmask_b32_e32 v63, v108, v63, vcc
	v_lshlrev_b32_e32 v63, 2, v63
	ds_bpermute_b32 v63, v63, v62
	s_waitcnt lgkmcnt(0)
	v_add_f32_e32 v62, v62, v63
	v_xor_b32_e32 v63, 2, v108
	v_cmp_lt_i32_e32 vcc, v63, v66
	s_nop 1
	v_cndmask_b32_e32 v63, v108, v63, vcc
	v_lshlrev_b32_e32 v63, 2, v63
	ds_bpermute_b32 v63, v63, v62
	s_waitcnt lgkmcnt(0)
	v_add_f32_e32 v62, v62, v63
	v_xor_b32_e32 v63, 4, v108
	v_cmp_lt_i32_e32 vcc, v63, v66
	s_nop 1
	v_cndmask_b32_e32 v63, v108, v63, vcc
	v_lshlrev_b32_e32 v63, 2, v63
	ds_bpermute_b32 v63, v63, v62
	s_waitcnt lgkmcnt(0)
	v_add_f32_e32 v62, v62, v63
	v_xor_b32_e32 v63, 8, v108
	v_cmp_lt_i32_e32 vcc, v63, v66
	s_nop 1
	v_cndmask_b32_e32 v63, v108, v63, vcc
	v_lshlrev_b32_e32 v63, 2, v63
	ds_bpermute_b32 v63, v63, v62
	s_waitcnt lgkmcnt(0)
	v_add_f32_e32 v62, v62, v63
	v_add_f32_e32 v62, 0x358637bd, v62
	v_mul_f32_e32 v63, 0x4b800000, v62
	v_cmp_gt_f32_e32 vcc, s49, v62
	s_nop 1
	v_cndmask_b32_e32 v62, v62, v63, vcc
	v_rsq_f32_e32 v62, v62
	s_nop 0
	v_mul_f32_e32 v63, 0x45800000, v62
	v_cndmask_b32_e32 v62, v62, v63, vcc
	v_mul_f32_e32 v63, 0x3db504f3, v62
	v_cndmask_b32_e64 v62, v62, v63, s[10:11]
	v_pk_mul_f32 v[38:39], v[38:39], v[62:63] op_sel_hi:[1,0]
	v_pk_mul_f32 v[58:59], v[58:59], v[62:63] op_sel_hi:[1,0]
	v_pk_mul_f32 v[50:51], v[50:51], v[62:63] op_sel_hi:[1,0]
	v_pk_mul_f32 v[44:45], v[44:45], v[62:63] op_sel_hi:[1,0]
.LBB0_812:
	s_or_b64 exec, exec, s[14:15]
	v_cvt_pk_bf16_f32 v88, v38, v39
	v_pk_mul_f32 v[38:39], v[20:21], v[56:57]
	v_cvt_pk_bf16_f32 v90, v50, v51
	v_and_b32_e32 v51, 0xffff0000, v32
	v_lshlrev_b32_e32 v50, 16, v32
	v_pk_fma_f32 v[38:39], v[16:17], v[60:61], v[38:39]
	v_cvt_pk_bf16_f32 v89, v58, v59
	v_pk_fma_f32 v[60:61], v[24:25], v[50:51], v[38:39]
	v_add_co_u32_e32 v58, vcc, s47, v52
	v_mul_f32_e32 v32, 0xbfb8aa3b, v60
	v_exp_f32_e32 v62, v32
	v_mul_f32_e32 v32, 0xbfb8aa3b, v61
	v_exp_f32_e32 v63, v32
	v_addc_co_u32_e32 v59, vcc, 0, v53, vcc
	v_and_b32_e32 v39, 0xffff0000, v34
	v_pk_add_f32 v[62:63], v[62:63], 1.0 op_sel_hi:[1,0]
	v_lshlrev_b32_e32 v38, 16, v34
	v_div_scale_f32 v66, s[0:1], v63, v63, v61
	v_rcp_f32_e32 v79, v66
	v_cvt_pk_bf16_f32 v91, v44, v45
	v_and_b32_e32 v45, 0xffff0000, v33
	v_lshlrev_b32_e32 v44, 16, v33
	v_fma_f32 v34, -v66, v79, 1.0
	v_fmac_f32_e32 v79, v34, v79
	v_div_scale_f32 v34, vcc, v61, v63, v61
	v_and_b32_e32 v33, 0xffff0000, v35
	v_lshlrev_b32_e32 v32, 16, v35
	v_mul_f32_e32 v35, v34, v79
	v_fma_f32 v83, -v66, v35, v34
	global_store_dwordx4 v[58:59], v[88:91], off sc1
	v_fmac_f32_e32 v35, v83, v79
	v_fma_f32 v34, -v66, v35, v34
	v_pk_mul_f32 v[88:89], v[22:23], v[48:49]
	v_div_scale_f32 v66, s[0:1], v62, v62, v60
	v_pk_fma_f32 v[54:55], v[18:19], v[54:55], v[88:89]
	v_rcp_f32_e32 v83, v66
	v_div_fmas_f32 v34, v34, v79, v35
	v_pk_fma_f32 v[54:55], v[26:27], v[44:45], v[54:55]
	v_div_fixup_f32 v35, v34, v63, v61
	v_mul_f32_e32 v63, 0xbfb8aa3b, v54
	v_exp_f32_e32 v88, v63
	v_mul_f32_e32 v63, 0xbfb8aa3b, v55
	v_exp_f32_e32 v89, v63
	v_fma_f32 v34, -v66, v83, 1.0
	v_fmac_f32_e32 v83, v34, v83
	v_div_scale_f32 v34, vcc, v60, v62, v60
	v_mul_f32_e32 v61, v34, v83
	v_fma_f32 v63, -v66, v61, v34
	v_pk_add_f32 v[88:89], v[88:89], 1.0 op_sel_hi:[1,0]
	v_fmac_f32_e32 v61, v63, v83
	v_div_scale_f32 v63, s[0:1], v89, v89, v55
	v_fma_f32 v34, -v66, v61, v34
	v_rcp_f32_e32 v66, v63
	v_div_fmas_f32 v34, v34, v83, v61
	v_div_fixup_f32 v34, v34, v62, v60
	v_fma_f32 v60, -v63, v66, 1.0
	v_fmac_f32_e32 v66, v60, v66
	v_div_scale_f32 v60, vcc, v55, v89, v55
	v_mul_f32_e32 v61, v60, v66
	v_fma_f32 v62, -v63, v61, v60
	v_fmac_f32_e32 v61, v62, v66
	v_div_scale_f32 v62, s[0:1], v88, v88, v54
	v_fma_f32 v60, -v63, v61, v60
	v_rcp_f32_e32 v63, v62
	v_div_fmas_f32 v60, v60, v66, v61
	v_div_fixup_f32 v55, v60, v89, v55
	v_div_scale_f32 v66, vcc, v54, v88, v54
	v_fma_f32 v60, -v62, v63, 1.0
	v_fmac_f32_e32 v63, v60, v63
	v_pk_mul_f32 v[60:61], v[4:5], v[42:43]
	v_mul_f32_e32 v79, v66, v63
	v_pk_fma_f32 v[46:47], v[0:1], v[46:47], v[60:61]
	v_fma_f32 v83, -v62, v79, v66
	v_pk_fma_f32 v[46:47], v[8:9], v[38:39], v[46:47]
	v_fmac_f32_e32 v79, v83, v63
	v_mul_f32_e32 v60, 0xbfb8aa3b, v46
	v_mul_f32_e32 v61, 0xbfb8aa3b, v47
	v_exp_f32_e32 v60, v60
	v_exp_f32_e32 v61, v61
	v_fma_f32 v62, -v62, v79, v66
	v_div_fmas_f32 v62, v62, v63, v79
	v_div_fixup_f32 v54, v62, v88, v54
	v_pk_add_f32 v[60:61], v[60:61], 1.0 op_sel_hi:[1,0]
	s_nop 0
	v_div_scale_f32 v66, s[0:1], v61, v61, v47
	v_rcp_f32_e32 v83, v66
	s_nop 0
	v_fma_f32 v62, -v66, v83, 1.0
	v_fmac_f32_e32 v83, v62, v83
	v_div_scale_f32 v62, vcc, v47, v61, v47
	v_mul_f32_e32 v63, v62, v83
	v_fma_f32 v79, -v66, v63, v62
	v_fmac_f32_e32 v63, v79, v83
	v_fma_f32 v62, -v66, v63, v62
	v_div_scale_f32 v66, s[0:1], v60, v60, v46
	v_div_fmas_f32 v62, v62, v83, v63
	v_rcp_f32_e32 v79, v66
	v_div_fixup_f32 v47, v62, v61, v47
	v_pk_mul_f32 v[62:63], v[6:7], v[36:37]
	v_fma_f32 v61, -v66, v79, 1.0
	v_pk_fma_f32 v[40:41], v[2:3], v[40:41], v[62:63]
	v_fmac_f32_e32 v79, v61, v79
	v_pk_fma_f32 v[40:41], v[10:11], v[32:33], v[40:41]
	v_div_scale_f32 v61, vcc, v46, v60, v46
	v_mul_f32_e32 v62, 0xbfb8aa3b, v40
	v_mul_f32_e32 v63, 0xbfb8aa3b, v41
	v_exp_f32_e32 v62, v62
	v_exp_f32_e32 v63, v63
	v_mul_f32_e32 v83, v61, v79
	v_fma_f32 v85, -v66, v83, v61
	v_fmac_f32_e32 v83, v85, v79
	v_pk_add_f32 v[62:63], v[62:63], 1.0 op_sel_hi:[1,0]
	v_fma_f32 v61, -v66, v83, v61
	v_div_scale_f32 v66, s[0:1], v63, v63, v41
	v_rcp_f32_e32 v85, v66
	v_div_fmas_f32 v61, v61, v79, v83
	v_div_fixup_f32 v46, v61, v60, v46
	v_fma_f32 v60, -v66, v85, 1.0
	v_fmac_f32_e32 v85, v60, v85
	v_div_scale_f32 v60, vcc, v41, v63, v41
	v_mul_f32_e32 v61, v60, v85
	v_fma_f32 v79, -v66, v61, v60
	v_fmac_f32_e32 v61, v79, v85
	v_fma_f32 v60, -v66, v61, v60
	v_div_scale_f32 v66, s[0:1], v62, v62, v40
	v_rcp_f32_e32 v79, v66
	v_div_fmas_f32 v60, v60, v85, v61
	v_div_fixup_f32 v41, v60, v63, v41
	v_fma_f32 v60, -v66, v79, 1.0
	v_fmac_f32_e32 v79, v60, v79
	v_div_scale_f32 v60, vcc, v40, v62, v40
	v_mul_f32_e32 v61, v60, v79
	v_fma_f32 v63, -v66, v61, v60
	v_fmac_f32_e32 v61, v63, v79
	v_fma_f32 v60, -v66, v61, v60
	v_div_fmas_f32 v60, v60, v79, v61
	v_div_fixup_f32 v40, v60, v62, v40
	s_and_saveexec_b64 s[14:15], s[12:13]
	s_cbranch_execz .LBB0_814
	v_pk_mul_f32 v[60:61], v[34:35], v[34:35]
	v_pk_mul_f32 v[62:63], v[54:55], v[54:55]
	v_add_f32_e32 v60, v60, v61
	v_add_f32_e32 v60, v60, v62
	v_pk_mul_f32 v[88:89], v[46:47], v[46:47]
	v_add_f32_e32 v60, v60, v63
	v_and_b32_e32 v62, 64, v108
	v_add_f32_e32 v60, v60, v88
	v_xor_b32_e32 v61, 1, v108
	v_add_u32_e32 v62, 64, v62
	v_pk_mul_f32 v[90:91], v[40:41], v[40:41]
	v_add_f32_e32 v60, v60, v89
	v_cmp_lt_i32_e32 vcc, v61, v62
	v_add_f32_e32 v60, v60, v90
	v_add_f32_e32 v60, v60, v91
	v_cndmask_b32_e32 v61, v108, v61, vcc
	v_lshlrev_b32_e32 v61, 2, v61
	ds_bpermute_b32 v61, v61, v60
	s_waitcnt lgkmcnt(0)
	v_add_f32_e32 v60, v60, v61
	v_xor_b32_e32 v61, 2, v108
	v_cmp_lt_i32_e32 vcc, v61, v62
	s_nop 1
	v_cndmask_b32_e32 v61, v108, v61, vcc
	v_lshlrev_b32_e32 v61, 2, v61
	ds_bpermute_b32 v61, v61, v60
	s_waitcnt lgkmcnt(0)
	v_add_f32_e32 v60, v60, v61
	v_xor_b32_e32 v61, 4, v108
	v_cmp_lt_i32_e32 vcc, v61, v62
	s_nop 1
	v_cndmask_b32_e32 v61, v108, v61, vcc
	v_lshlrev_b32_e32 v61, 2, v61
	ds_bpermute_b32 v61, v61, v60
	s_waitcnt lgkmcnt(0)
	v_add_f32_e32 v60, v60, v61
	v_xor_b32_e32 v61, 8, v108
	v_cmp_lt_i32_e32 vcc, v61, v62
	s_nop 1
	v_cndmask_b32_e32 v61, v108, v61, vcc
	v_lshlrev_b32_e32 v61, 2, v61
	ds_bpermute_b32 v61, v61, v60
	s_waitcnt lgkmcnt(0)
	v_add_f32_e32 v60, v60, v61
	v_add_f32_e32 v60, 0x358637bd, v60
	v_mul_f32_e32 v61, 0x4b800000, v60
	v_cmp_gt_f32_e32 vcc, s49, v60
	s_nop 1
	v_cndmask_b32_e32 v60, v60, v61, vcc
	v_rsq_f32_e32 v60, v60
	s_nop 0
	v_mul_f32_e32 v61, 0x45800000, v60
	v_cndmask_b32_e32 v60, v60, v61, vcc
	v_mul_f32_e32 v61, 0x3db504f3, v60
	v_cndmask_b32_e64 v60, v60, v61, s[10:11]
	v_pk_mul_f32 v[34:35], v[34:35], v[60:61] op_sel_hi:[1,0]
	v_pk_mul_f32 v[54:55], v[54:55], v[60:61] op_sel_hi:[1,0]
	v_pk_mul_f32 v[46:47], v[46:47], v[60:61] op_sel_hi:[1,0]
	v_pk_mul_f32 v[40:41], v[40:41], v[60:61] op_sel_hi:[1,0]
.LBB0_814:
	s_or_b64 exec, exec, s[14:15]
	v_cvt_pk_bf16_f32 v60, v34, v35
	v_pk_mul_f32 v[34:35], v[20:21], v[50:51]
	v_cvt_pk_bf16_f32 v62, v46, v47
	v_and_b32_e32 v47, 0xffff0000, v28
	v_lshlrev_b32_e32 v46, 16, v28
	v_pk_fma_f32 v[34:35], v[16:17], v[56:57], v[34:35]
	v_cvt_pk_bf16_f32 v61, v54, v55
	v_pk_fma_f32 v[54:55], v[24:25], v[46:47], v[34:35]
	v_cvt_pk_bf16_f32 v63, v40, v41
	v_mul_f32_e32 v28, 0xbfb8aa3b, v54
	v_exp_f32_e32 v56, v28
	v_mul_f32_e32 v28, 0xbfb8aa3b, v55
	v_exp_f32_e32 v57, v28
	global_store_dwordx4 v[58:59], v[60:63], off offset:2048 sc1
	v_and_b32_e32 v35, 0xffff0000, v30
	v_lshlrev_b32_e32 v34, 16, v30
	v_pk_add_f32 v[56:57], v[56:57], 1.0 op_sel_hi:[1,0]
	v_and_b32_e32 v41, 0xffff0000, v29
	v_div_scale_f32 v58, s[0:1], v57, v57, v55
	v_rcp_f32_e32 v59, v58
	v_lshlrev_b32_e32 v40, 16, v29
	v_and_b32_e32 v29, 0xffff0000, v31
	v_lshlrev_b32_e32 v28, 16, v31
	v_fma_f32 v30, -v58, v59, 1.0
	v_fmac_f32_e32 v59, v30, v59
	v_div_scale_f32 v30, vcc, v55, v57, v55
	v_mul_f32_e32 v31, v30, v59
	v_fma_f32 v60, -v58, v31, v30
	v_fmac_f32_e32 v31, v60, v59
	v_fma_f32 v30, -v58, v31, v30
	v_div_fmas_f32 v30, v30, v59, v31
	v_pk_mul_f32 v[58:59], v[22:23], v[44:45]
	v_div_scale_f32 v60, s[0:1], v56, v56, v54
	v_pk_fma_f32 v[48:49], v[18:19], v[48:49], v[58:59]
	v_rcp_f32_e32 v61, v60
	v_pk_fma_f32 v[48:49], v[26:27], v[40:41], v[48:49]
	v_div_fixup_f32 v31, v30, v57, v55
	v_mul_f32_e32 v57, 0xbfb8aa3b, v48
	v_exp_f32_e32 v58, v57
	v_mul_f32_e32 v57, 0xbfb8aa3b, v49
	v_exp_f32_e32 v59, v57
	v_fma_f32 v30, -v60, v61, 1.0
	v_fmac_f32_e32 v61, v30, v61
	v_div_scale_f32 v30, vcc, v54, v56, v54
	v_mul_f32_e32 v55, v30, v61
	v_fma_f32 v57, -v60, v55, v30
	v_pk_add_f32 v[58:59], v[58:59], 1.0 op_sel_hi:[1,0]
	v_fmac_f32_e32 v55, v57, v61
	v_div_scale_f32 v57, s[0:1], v59, v59, v49
	v_fma_f32 v30, -v60, v55, v30
	v_rcp_f32_e32 v60, v57
	v_div_fmas_f32 v30, v30, v61, v55
	v_div_fixup_f32 v30, v30, v56, v54
	v_fma_f32 v54, -v57, v60, 1.0
	v_fmac_f32_e32 v60, v54, v60
	v_div_scale_f32 v54, vcc, v49, v59, v49
	v_mul_f32_e32 v55, v54, v60
	v_fma_f32 v56, -v57, v55, v54
	v_fmac_f32_e32 v55, v56, v60
	v_div_scale_f32 v56, s[0:1], v58, v58, v48
	v_fma_f32 v54, -v57, v55, v54
	v_rcp_f32_e32 v57, v56
	v_div_fmas_f32 v54, v54, v60, v55
	v_div_fixup_f32 v49, v54, v59, v49
	v_div_scale_f32 v59, vcc, v48, v58, v48
	v_fma_f32 v54, -v56, v57, 1.0
	v_fmac_f32_e32 v57, v54, v57
	v_pk_mul_f32 v[54:55], v[4:5], v[38:39]
	v_mul_f32_e32 v60, v59, v57
	v_pk_fma_f32 v[42:43], v[0:1], v[42:43], v[54:55]
	v_fma_f32 v61, -v56, v60, v59
	v_pk_fma_f32 v[42:43], v[8:9], v[34:35], v[42:43]
	v_fmac_f32_e32 v60, v61, v57
	v_mul_f32_e32 v54, 0xbfb8aa3b, v42
	v_mul_f32_e32 v55, 0xbfb8aa3b, v43
	v_exp_f32_e32 v54, v54
	v_exp_f32_e32 v55, v55
	v_fma_f32 v56, -v56, v60, v59
	v_div_fmas_f32 v56, v56, v57, v60
	v_div_fixup_f32 v48, v56, v58, v48
	v_pk_add_f32 v[54:55], v[54:55], 1.0 op_sel_hi:[1,0]
	s_nop 0
	v_div_scale_f32 v59, s[0:1], v55, v55, v43
	v_rcp_f32_e32 v61, v59
	s_nop 0
	v_fma_f32 v56, -v59, v61, 1.0
	v_fmac_f32_e32 v61, v56, v61
	v_div_scale_f32 v56, vcc, v43, v55, v43
	v_mul_f32_e32 v57, v56, v61
	v_fma_f32 v58, -v59, v57, v56
	v_fmac_f32_e32 v57, v58, v61
	v_fma_f32 v56, -v59, v57, v56
	v_div_scale_f32 v58, s[0:1], v54, v54, v42
	v_div_fmas_f32 v56, v56, v61, v57
	v_rcp_f32_e32 v59, v58
	v_div_fixup_f32 v43, v56, v55, v43
	v_pk_mul_f32 v[56:57], v[6:7], v[32:33]
	v_fma_f32 v55, -v58, v59, 1.0
	v_pk_fma_f32 v[36:37], v[2:3], v[36:37], v[56:57]
	v_fmac_f32_e32 v59, v55, v59
	v_pk_fma_f32 v[36:37], v[10:11], v[28:29], v[36:37]
	v_div_scale_f32 v55, vcc, v42, v54, v42
	v_mul_f32_e32 v56, 0xbfb8aa3b, v36
	v_mul_f32_e32 v57, 0xbfb8aa3b, v37
	v_exp_f32_e32 v56, v56
	v_exp_f32_e32 v57, v57
	v_mul_f32_e32 v60, v55, v59
	v_fma_f32 v61, -v58, v60, v55
	v_fmac_f32_e32 v60, v61, v59
	v_pk_add_f32 v[56:57], v[56:57], 1.0 op_sel_hi:[1,0]
	v_fma_f32 v55, -v58, v60, v55
	v_div_scale_f32 v58, s[0:1], v57, v57, v37
	v_rcp_f32_e32 v61, v58
	v_div_fmas_f32 v55, v55, v59, v60
	v_div_fixup_f32 v42, v55, v54, v42
	v_fma_f32 v54, -v58, v61, 1.0
	v_fmac_f32_e32 v61, v54, v61
	v_div_scale_f32 v54, vcc, v37, v57, v37
	v_mul_f32_e32 v55, v54, v61
	v_fma_f32 v59, -v58, v55, v54
	v_fmac_f32_e32 v55, v59, v61
	v_fma_f32 v54, -v58, v55, v54
	v_div_scale_f32 v58, s[0:1], v56, v56, v36
	v_rcp_f32_e32 v59, v58
	v_div_fmas_f32 v54, v54, v61, v55
	v_div_fixup_f32 v37, v54, v57, v37
	v_fma_f32 v54, -v58, v59, 1.0
	v_fmac_f32_e32 v59, v54, v59
	v_div_scale_f32 v54, vcc, v36, v56, v36
	v_mul_f32_e32 v55, v54, v59
	v_fma_f32 v57, -v58, v55, v54
	v_fmac_f32_e32 v55, v57, v59
	v_fma_f32 v54, -v58, v55, v54
	v_div_fmas_f32 v54, v54, v59, v55
	v_div_fixup_f32 v36, v54, v56, v36
	s_and_saveexec_b64 s[14:15], s[12:13]
	s_cbranch_execz .LBB0_816
	v_pk_mul_f32 v[54:55], v[30:31], v[30:31]
	v_pk_mul_f32 v[56:57], v[48:49], v[48:49]
	v_add_f32_e32 v54, v54, v55
	v_add_f32_e32 v54, v54, v56
	v_pk_mul_f32 v[58:59], v[42:43], v[42:43]
	v_add_f32_e32 v54, v54, v57
	v_and_b32_e32 v56, 64, v108
	v_add_f32_e32 v54, v54, v58
	v_xor_b32_e32 v55, 1, v108
	v_add_u32_e32 v56, 64, v56
	v_pk_mul_f32 v[60:61], v[36:37], v[36:37]
	v_add_f32_e32 v54, v54, v59
	v_cmp_lt_i32_e32 vcc, v55, v56
	v_add_f32_e32 v54, v54, v60
	v_add_f32_e32 v54, v54, v61
	v_cndmask_b32_e32 v55, v108, v55, vcc
	v_lshlrev_b32_e32 v55, 2, v55
	ds_bpermute_b32 v55, v55, v54
	s_waitcnt lgkmcnt(0)
	v_add_f32_e32 v54, v54, v55
	v_xor_b32_e32 v55, 2, v108
	v_cmp_lt_i32_e32 vcc, v55, v56
	s_nop 1
	v_cndmask_b32_e32 v55, v108, v55, vcc
	v_lshlrev_b32_e32 v55, 2, v55
	ds_bpermute_b32 v55, v55, v54
	s_waitcnt lgkmcnt(0)
	v_add_f32_e32 v54, v54, v55
	v_xor_b32_e32 v55, 4, v108
	v_cmp_lt_i32_e32 vcc, v55, v56
	s_nop 1
	v_cndmask_b32_e32 v55, v108, v55, vcc
	v_lshlrev_b32_e32 v55, 2, v55
	ds_bpermute_b32 v55, v55, v54
	s_waitcnt lgkmcnt(0)
	v_add_f32_e32 v54, v54, v55
	v_xor_b32_e32 v55, 8, v108
	v_cmp_lt_i32_e32 vcc, v55, v56
	s_nop 1
	v_cndmask_b32_e32 v55, v108, v55, vcc
	v_lshlrev_b32_e32 v55, 2, v55
	ds_bpermute_b32 v55, v55, v54
	s_waitcnt lgkmcnt(0)
	v_add_f32_e32 v54, v54, v55
	v_add_f32_e32 v54, 0x358637bd, v54
	v_mul_f32_e32 v55, 0x4b800000, v54
	v_cmp_gt_f32_e32 vcc, s49, v54
	s_nop 1
	v_cndmask_b32_e32 v54, v54, v55, vcc
	v_rsq_f32_e32 v54, v54
	s_nop 0
	v_mul_f32_e32 v55, 0x45800000, v54
	v_cndmask_b32_e32 v54, v54, v55, vcc
	v_mul_f32_e32 v55, 0x3db504f3, v54
	v_cndmask_b32_e64 v54, v54, v55, s[10:11]
	v_pk_mul_f32 v[30:31], v[30:31], v[54:55] op_sel_hi:[1,0]
	v_pk_mul_f32 v[48:49], v[48:49], v[54:55] op_sel_hi:[1,0]
	v_pk_mul_f32 v[42:43], v[42:43], v[54:55] op_sel_hi:[1,0]
	v_pk_mul_f32 v[36:37], v[36:37], v[54:55] op_sel_hi:[1,0]
.LBB0_816:
	s_or_b64 exec, exec, s[14:15]
	v_cvt_pk_bf16_f32 v54, v30, v31
	v_add_co_u32_e32 v30, vcc, s51, v52
	v_cvt_pk_bf16_f32 v55, v48, v49
	v_cvt_pk_bf16_f32 v56, v42, v43
	v_cvt_pk_bf16_f32 v57, v36, v37
	v_addc_co_u32_e32 v31, vcc, 0, v53, vcc
	v_pk_mul_f32 v[20:21], v[20:21], v[46:47]
	global_store_dwordx4 v[30:31], v[54:57], off sc1
	v_lshlrev_b32_e32 v30, 16, v12
	v_and_b32_e32 v31, 0xffff0000, v12
	v_pk_fma_f32 v[16:17], v[16:17], v[50:51], v[20:21]
	v_pk_mul_f32 v[4:5], v[4:5], v[34:35]
	v_pk_fma_f32 v[16:17], v[24:25], v[30:31], v[16:17]
	v_lshlrev_b32_e32 v24, 16, v13
	v_mul_f32_e32 v12, 0xbfb8aa3b, v16
	v_exp_f32_e32 v20, v12
	v_mul_f32_e32 v12, 0xbfb8aa3b, v17
	v_exp_f32_e32 v21, v12
	v_and_b32_e32 v25, 0xffff0000, v13
	v_lshlrev_b32_e32 v30, 16, v14
	v_and_b32_e32 v31, 0xffff0000, v14
	v_pk_add_f32 v[12:13], v[20:21], 1.0 op_sel_hi:[1,0]
	v_lshlrev_b32_e32 v20, 16, v15
	v_div_scale_f32 v36, s[0:1], v13, v13, v17
	v_rcp_f32_e32 v37, v36
	v_and_b32_e32 v21, 0xffff0000, v15
	v_pk_fma_f32 v[0:1], v[0:1], v[38:39], v[4:5]
	v_pk_mul_f32 v[6:7], v[6:7], v[28:29]
	v_fma_f32 v14, -v36, v37, 1.0
	v_fmac_f32_e32 v37, v14, v37
	v_div_scale_f32 v14, vcc, v17, v13, v17
	v_mul_f32_e32 v15, v14, v37
	v_fma_f32 v42, -v36, v15, v14
	v_fmac_f32_e32 v15, v42, v37
	v_fma_f32 v14, -v36, v15, v14
	v_div_scale_f32 v36, s[0:1], v12, v12, v16
	v_rcp_f32_e32 v42, v36
	v_div_fmas_f32 v14, v14, v37, v15
	v_div_fixup_f32 v13, v14, v13, v17
	v_div_scale_f32 v17, vcc, v16, v12, v16
	v_fma_f32 v14, -v36, v42, 1.0
	v_fmac_f32_e32 v42, v14, v42
	v_pk_mul_f32 v[14:15], v[22:23], v[40:41]
	v_mul_f32_e32 v37, v17, v42
	v_pk_fma_f32 v[14:15], v[18:19], v[44:45], v[14:15]
	v_fma_f32 v22, -v36, v37, v17
	v_pk_fma_f32 v[14:15], v[26:27], v[24:25], v[14:15]
	v_fmac_f32_e32 v37, v22, v42
	v_mul_f32_e32 v18, 0xbfb8aa3b, v14
	v_mul_f32_e32 v19, 0xbfb8aa3b, v15
	v_exp_f32_e32 v18, v18
	v_exp_f32_e32 v19, v19
	v_fma_f32 v17, -v36, v37, v17
	v_div_fmas_f32 v17, v17, v42, v37
	v_div_fixup_f32 v12, v17, v12, v16
	v_pk_add_f32 v[18:19], v[18:19], 1.0 op_sel_hi:[1,0]
	v_pk_fma_f32 v[0:1], v[8:9], v[30:31], v[0:1]
	v_div_scale_f32 v22, s[0:1], v19, v19, v15
	v_rcp_f32_e32 v23, v22
	v_mul_f32_e32 v4, 0xbfb8aa3b, v0
	v_mul_f32_e32 v5, 0xbfb8aa3b, v1
	v_exp_f32_e32 v4, v4
	v_fma_f32 v16, -v22, v23, 1.0
	v_fmac_f32_e32 v23, v16, v23
	v_div_scale_f32 v16, vcc, v15, v19, v15
	v_mul_f32_e32 v17, v16, v23
	v_fma_f32 v24, -v22, v17, v16
	v_fmac_f32_e32 v17, v24, v23
	v_fma_f32 v16, -v22, v17, v16
	v_div_scale_f32 v22, s[0:1], v18, v18, v14
	v_rcp_f32_e32 v24, v22
	v_div_fmas_f32 v16, v16, v23, v17
	v_exp_f32_e32 v5, v5
	v_div_fixup_f32 v15, v16, v19, v15
	v_fma_f32 v16, -v22, v24, 1.0
	v_fmac_f32_e32 v24, v16, v24
	v_div_scale_f32 v16, vcc, v14, v18, v14
	v_mul_f32_e32 v17, v16, v24
	v_fma_f32 v8, -v22, v17, v16
	v_pk_add_f32 v[4:5], v[4:5], 1.0 op_sel_hi:[1,0]
	v_fmac_f32_e32 v17, v8, v24
	v_div_scale_f32 v9, s[0:1], v5, v5, v1
	v_fma_f32 v8, -v22, v17, v16
	v_rcp_f32_e32 v16, v9
	v_div_fmas_f32 v8, v8, v24, v17
	v_div_fixup_f32 v14, v8, v18, v14
	v_pk_fma_f32 v[2:3], v[2:3], v[32:33], v[6:7]
	v_fma_f32 v8, -v9, v16, 1.0
	v_fmac_f32_e32 v16, v8, v16
	v_div_scale_f32 v8, vcc, v1, v5, v1
	v_mul_f32_e32 v17, v8, v16
	v_fma_f32 v18, -v9, v17, v8
	v_fmac_f32_e32 v17, v18, v16
	v_fma_f32 v8, -v9, v17, v8
	v_div_scale_f32 v9, s[0:1], v4, v4, v0
	v_rcp_f32_e32 v18, v9
	v_pk_fma_f32 v[2:3], v[10:11], v[20:21], v[2:3]
	v_div_fmas_f32 v8, v8, v16, v17
	v_mul_f32_e32 v6, 0xbfb8aa3b, v2
	v_mul_f32_e32 v7, 0xbfb8aa3b, v3
	v_div_fixup_f32 v1, v8, v5, v1
	v_fma_f32 v5, -v9, v18, 1.0
	v_exp_f32_e32 v6, v6
	v_exp_f32_e32 v7, v7
	v_fmac_f32_e32 v18, v5, v18
	v_div_scale_f32 v5, vcc, v0, v4, v0
	v_mul_f32_e32 v8, v5, v18
	v_fma_f32 v10, -v9, v8, v5
	v_fmac_f32_e32 v8, v10, v18
	v_pk_add_f32 v[6:7], v[6:7], 1.0 op_sel_hi:[1,0]
	v_fma_f32 v5, -v9, v8, v5
	v_div_scale_f32 v9, s[0:1], v7, v7, v3
	v_rcp_f32_e32 v10, v9
	v_div_fmas_f32 v5, v5, v18, v8
	v_div_fixup_f32 v0, v5, v4, v0
	v_fma_f32 v4, -v9, v10, 1.0
	v_fmac_f32_e32 v10, v4, v10
	v_div_scale_f32 v4, vcc, v3, v7, v3
	v_mul_f32_e32 v5, v4, v10
	v_fma_f32 v8, -v9, v5, v4
	v_fmac_f32_e32 v5, v8, v10
	v_div_scale_f32 v8, s[0:1], v6, v6, v2
	v_fma_f32 v4, -v9, v5, v4
	v_rcp_f32_e32 v9, v8
	v_div_fmas_f32 v4, v4, v10, v5
	v_div_fixup_f32 v3, v4, v7, v3
	v_fma_f32 v4, -v8, v9, 1.0
	v_fmac_f32_e32 v9, v4, v9
	v_div_scale_f32 v4, vcc, v2, v6, v2
	v_mul_f32_e32 v5, v4, v9
	v_fma_f32 v7, -v8, v5, v4
	v_fmac_f32_e32 v5, v7, v9
	v_fma_f32 v4, -v8, v5, v4
	v_div_fmas_f32 v4, v4, v9, v5
	v_div_fixup_f32 v2, v4, v6, v2
	s_and_saveexec_b64 s[14:15], s[12:13]
	s_cbranch_execz .LBB0_818
	v_pk_mul_f32 v[4:5], v[12:13], v[12:13]
	v_pk_mul_f32 v[6:7], v[14:15], v[14:15]
	v_add_f32_e32 v4, v4, v5
	v_add_f32_e32 v4, v4, v6
	v_pk_mul_f32 v[8:9], v[0:1], v[0:1]
	v_add_f32_e32 v4, v4, v7
	v_and_b32_e32 v6, 64, v108
	v_add_f32_e32 v4, v4, v8
	v_xor_b32_e32 v5, 1, v108
	v_add_u32_e32 v6, 64, v6
	v_pk_mul_f32 v[10:11], v[2:3], v[2:3]
	v_add_f32_e32 v4, v4, v9
	v_cmp_lt_i32_e32 vcc, v5, v6
	v_add_f32_e32 v4, v4, v10
	v_add_f32_e32 v4, v4, v11
	v_cndmask_b32_e32 v5, v108, v5, vcc
	v_lshlrev_b32_e32 v5, 2, v5
	ds_bpermute_b32 v5, v5, v4
	s_waitcnt lgkmcnt(0)
	v_add_f32_e32 v4, v4, v5
	v_xor_b32_e32 v5, 2, v108
	v_cmp_lt_i32_e32 vcc, v5, v6
	s_nop 1
	v_cndmask_b32_e32 v5, v108, v5, vcc
	v_lshlrev_b32_e32 v5, 2, v5
	ds_bpermute_b32 v5, v5, v4
	s_waitcnt lgkmcnt(0)
	v_add_f32_e32 v4, v4, v5
	v_xor_b32_e32 v5, 4, v108
	v_cmp_lt_i32_e32 vcc, v5, v6
	s_nop 1
	v_cndmask_b32_e32 v5, v108, v5, vcc
	v_lshlrev_b32_e32 v5, 2, v5
	ds_bpermute_b32 v5, v5, v4
	s_waitcnt lgkmcnt(0)
	v_add_f32_e32 v4, v4, v5
	v_xor_b32_e32 v5, 8, v108
	v_cmp_lt_i32_e32 vcc, v5, v6
	s_nop 1
	v_cndmask_b32_e32 v5, v108, v5, vcc
	v_lshlrev_b32_e32 v5, 2, v5
	ds_bpermute_b32 v5, v5, v4
	s_waitcnt lgkmcnt(0)
	v_add_f32_e32 v4, v4, v5
	v_add_f32_e32 v4, 0x358637bd, v4
	v_mul_f32_e32 v5, 0x4b800000, v4
	v_cmp_gt_f32_e32 vcc, s49, v4
	s_nop 1
	v_cndmask_b32_e32 v4, v4, v5, vcc
	v_rsq_f32_e32 v4, v4
	s_nop 0
	v_mul_f32_e32 v5, 0x45800000, v4
	v_cndmask_b32_e32 v4, v4, v5, vcc
	v_mul_f32_e32 v5, 0x3db504f3, v4
	v_cndmask_b32_e64 v4, v4, v5, s[10:11]
	v_pk_mul_f32 v[12:13], v[12:13], v[4:5] op_sel_hi:[1,0]
	v_pk_mul_f32 v[14:15], v[14:15], v[4:5] op_sel_hi:[1,0]
	v_pk_mul_f32 v[0:1], v[0:1], v[4:5] op_sel_hi:[1,0]
	v_pk_mul_f32 v[2:3], v[2:3], v[4:5] op_sel_hi:[1,0]
.LBB0_818:
	s_or_b64 exec, exec, s[14:15]
	v_cvt_pk_bf16_f32 v6, v0, v1
	v_add_co_u32_e32 v0, vcc, 0x3000, v52
	v_cvt_pk_bf16_f32 v4, v12, v13
	v_cvt_pk_bf16_f32 v5, v14, v15
	v_cvt_pk_bf16_f32 v7, v2, v3
	v_addc_co_u32_e32 v1, vcc, 0, v53, vcc
	global_store_dwordx4 v[0:1], v[4:7], off offset:2048 sc1

.LBB0_1044:
	v_mad_i64_i32 v[8:9], s[6:7], v64, s2, v[66:67]
	v_lshl_add_u64 v[8:9], v[8:9], 0, s[20:21]
	v_lshl_add_u64 v[10:11], v[8:9], 0, v[56:57]
	v_ashrrev_i32_e32 v65, 31, v64
	v_lshl_add_u64 v[10:11], v[10:11], 0, v[68:69]
	global_load_dwordx4 v[52:55], v[10:11], off nt
	v_lshlrev_b64 v[10:11], 10, v[64:65]
	v_or_b32_e32 v12, v10, v58
	v_mov_b32_e32 v13, v11
	v_lshlrev_b64 v[12:13], 1, v[12:13]
	v_lshl_add_u64 v[14:15], s[14:15], 0, v[12:13]
	v_lshl_add_u64 v[12:13], s[16:17], 0, v[12:13]
	global_load_dwordx4 v[48:51], v[14:15], off nt
	global_load_dwordx4 v[44:47], v[12:13], off nt
	v_add_u32_e32 v74, 1, v64
	v_ashrrev_i32_e32 v75, 31, v74
	v_lshlrev_b64 v[14:15], 10, v[74:75]
	v_mad_i64_i32 v[12:13], s[6:7], v74, s2, v[66:67]
	v_or_b32_e32 v10, v10, v60
	v_or_b32_e32 v16, v14, v58
	v_mov_b32_e32 v17, v15
	v_or_b32_e32 v14, v14, v60
	v_lshl_add_u64 v[8:9], v[8:9], 0, v[68:69]
	v_lshl_add_u64 v[12:13], v[12:13], 0, s[20:21]
	v_lshlrev_b64 v[10:11], 1, v[10:11]
	v_lshlrev_b64 v[16:17], 1, v[16:17]
	v_lshlrev_b64 v[14:15], 1, v[14:15]
	v_lshl_add_u64 v[8:9], v[8:9], 0, v[70:71]
	v_lshl_add_u64 v[18:19], v[12:13], 0, v[56:57]
	v_lshl_add_u64 v[12:13], v[12:13], 0, v[68:69]
	v_lshl_add_u64 v[20:21], s[14:15], 0, v[10:11]
	v_lshl_add_u64 v[10:11], s[16:17], 0, v[10:11]
	v_lshl_add_u64 v[80:81], s[14:15], 0, v[16:17]
	v_lshl_add_u64 v[82:83], s[16:17], 0, v[16:17]
	v_lshl_add_u64 v[84:85], s[14:15], 0, v[14:15]
	v_lshl_add_u64 v[76:77], v[18:19], 0, v[68:69]
	v_lshl_add_u64 v[78:79], v[12:13], 0, v[70:71]
	global_load_dwordx4 v[36:39], v[20:21], off nt
	global_load_dwordx4 v[32:35], v[10:11], off nt
	global_load_dwordx4 v[40:43], v[8:9], off nt
	v_lshl_add_u64 v[86:87], s[16:17], 0, v[14:15]
	global_load_dwordx4 v[24:27], v[80:81], off nt
	global_load_dwordx4 v[20:23], v[82:83], off nt
	global_load_dwordx4 v[28:31], v[76:77], off nt
	global_load_dwordx4 v[12:15], v[84:85], off nt
	global_load_dwordx4 v[8:11], v[86:87], off nt
	global_load_dwordx4 v[16:19], v[78:79], off nt
	v_add_u32_e32 v92, s0, v92
	s_waitcnt vmcnt(11)
	v_lshlrev_b32_e32 v83, 16, v54
	v_and_b32_e32 v84, 0xffff0000, v54
	v_lshlrev_b32_e32 v88, 16, v55
	v_and_b32_e32 v89, 0xffff0000, v55
	v_mul_f32_e32 v80, 0xbfb8aa3b, v83
	v_mul_f32_e32 v81, 0xbfb8aa3b, v84
	v_lshlrev_b32_e32 v93, 16, v53
	s_waitcnt vmcnt(10)
	v_lshlrev_b32_e32 v54, 16, v51
	v_and_b32_e32 v55, 0xffff0000, v51
	s_waitcnt vmcnt(9)
	v_lshlrev_b32_e32 v76, 16, v47
	v_and_b32_e32 v77, 0xffff0000, v47
	v_lshlrev_b32_e32 v78, 16, v50
	v_and_b32_e32 v79, 0xffff0000, v50
	v_lshlrev_b32_e32 v50, 16, v46
	v_and_b32_e32 v51, 0xffff0000, v46
	v_pk_add_f32 v[46:47], v[54:55], v[76:77]
	v_exp_f32_e32 v54, v80
	v_exp_f32_e32 v55, v81
	v_mul_f32_e32 v85, 0xbfb8aa3b, v93
	v_exp_f32_e32 v76, v85
	v_and_b32_e32 v53, 0xffff0000, v53
	v_pk_add_f32 v[54:55], v[54:55], 1.0 op_sel_hi:[1,0]
	v_mul_f32_e32 v86, 0xbfb8aa3b, v53
	v_div_scale_f32 v85, s[6:7], v55, v55, v84
	v_div_scale_f32 v87, s[6:7], v54, v54, v83
	v_rcp_f32_e32 v94, v85
	v_rcp_f32_e32 v95, v87
	v_exp_f32_e32 v77, v86
	v_div_scale_f32 v86, vcc, v84, v55, v84
	v_fma_f32 v97, -v85, v94, 1.0
	v_fma_f32 v98, -v87, v95, 1.0
	v_fmac_f32_e32 v94, v97, v94
	v_div_scale_f32 v96, s[10:11], v83, v54, v83
	v_fmac_f32_e32 v95, v98, v95
	v_mul_f32_e32 v97, v86, v94
	v_mul_f32_e32 v98, v96, v95
	v_fma_f32 v99, -v85, v97, v86
	v_fma_f32 v100, -v87, v98, v96
	v_fmac_f32_e32 v97, v99, v94
	v_fmac_f32_e32 v98, v100, v95
	v_fma_f32 v85, -v85, v97, v86
	v_fma_f32 v86, -v87, v98, v96
	v_div_fmas_f32 v85, v85, v94, v97
	s_mov_b64 vcc, s[10:11]
	v_div_fixup_f32 v55, v85, v55, v84
	v_div_fmas_f32 v84, v86, v95, v98
	v_pk_add_f32 v[86:87], v[76:77], 1.0 op_sel_hi:[1,0]
	v_lshlrev_b32_e32 v82, 16, v49
	v_div_fixup_f32 v54, v84, v54, v83
	v_and_b32_e32 v83, 0xffff0000, v49
	v_div_scale_f32 v49, s[6:7], v87, v87, v53
	v_rcp_f32_e32 v94, v49
	v_lshlrev_b32_e32 v84, 16, v45
	v_and_b32_e32 v85, 0xffff0000, v45
	v_pk_add_f32 v[76:77], v[82:83], v[84:85]
	v_fma_f32 v45, -v49, v94, 1.0
	v_fmac_f32_e32 v94, v45, v94
	v_div_scale_f32 v45, vcc, v53, v87, v53
	v_mul_f32_e32 v84, v45, v94
	v_fma_f32 v85, -v49, v84, v45
	v_fmac_f32_e32 v84, v85, v94
	v_fma_f32 v45, -v49, v84, v45
	v_div_scale_f32 v49, s[6:7], v86, v86, v93
	v_rcp_f32_e32 v85, v49
	v_div_fmas_f32 v45, v45, v94, v84
	v_div_fixup_f32 v53, v45, v87, v53
	v_lshlrev_b32_e32 v94, 16, v52
	v_fma_f32 v45, -v49, v85, 1.0
	v_fmac_f32_e32 v85, v45, v85
	v_div_scale_f32 v45, vcc, v93, v86, v93
	v_mul_f32_e32 v84, v45, v85
	v_fma_f32 v87, -v49, v84, v45
	v_fmac_f32_e32 v84, v87, v85
	v_fma_f32 v45, -v49, v84, v45
	v_and_b32_e32 v95, 0xffff0000, v52
	v_mul_f32_e32 v49, 0xbfb8aa3b, v94
	v_div_fmas_f32 v45, v45, v85, v84
	v_exp_f32_e32 v84, v49
	v_mul_f32_e32 v49, 0xbfb8aa3b, v95
	v_exp_f32_e32 v85, v49
	v_div_fixup_f32 v52, v45, v86, v93
	v_lshlrev_b32_e32 v86, 16, v48
	v_and_b32_e32 v87, 0xffff0000, v48
	v_pk_add_f32 v[84:85], v[84:85], 1.0 op_sel_hi:[1,0]
	v_lshlrev_b32_e32 v48, 16, v44
	v_div_scale_f32 v45, s[6:7], v85, v85, v95
	v_rcp_f32_e32 v93, v45
	v_and_b32_e32 v49, 0xffff0000, v44
	v_pk_add_f32 v[48:49], v[86:87], v[48:49]
	s_waitcnt vmcnt(6)
	v_lshlrev_b32_e32 v98, 16, v42
	v_fma_f32 v44, -v45, v93, 1.0
	v_fmac_f32_e32 v93, v44, v93
	v_div_scale_f32 v44, vcc, v95, v85, v95
	v_mul_f32_e32 v86, v44, v93
	v_fma_f32 v87, -v45, v86, v44
	v_fmac_f32_e32 v86, v87, v93
	v_div_scale_f32 v87, s[6:7], v84, v84, v94
	v_rcp_f32_e32 v96, v87
	v_fma_f32 v44, -v45, v86, v44
	v_div_fmas_f32 v44, v44, v93, v86
	v_div_fixup_f32 v85, v44, v85, v95
	v_fma_f32 v44, -v87, v96, 1.0
	v_fmac_f32_e32 v96, v44, v96
	v_mul_f32_e32 v44, 0xbfb8aa3b, v88
	v_mul_f32_e32 v45, 0xbfb8aa3b, v89
	v_exp_f32_e32 v44, v44
	v_exp_f32_e32 v45, v45
	v_div_scale_f32 v86, vcc, v94, v84, v94
	v_mul_f32_e32 v93, v86, v96
	v_fma_f32 v95, -v87, v93, v86
	v_fmac_f32_e32 v93, v95, v96
	v_pk_add_f32 v[44:45], v[44:45], 1.0 op_sel_hi:[1,0]
	v_fma_f32 v86, -v87, v93, v86
	v_div_scale_f32 v87, s[6:7], v45, v45, v89
	v_rcp_f32_e32 v95, v87
	v_div_fmas_f32 v86, v86, v96, v93
	v_div_fixup_f32 v84, v86, v84, v94
	v_and_b32_e32 v99, 0xffff0000, v42
	v_fma_f32 v86, -v87, v95, 1.0
	v_fmac_f32_e32 v95, v86, v95
	v_div_scale_f32 v86, vcc, v89, v45, v89
	v_mul_f32_e32 v93, v86, v95
	v_fma_f32 v94, -v87, v93, v86
	v_fmac_f32_e32 v93, v94, v95
	v_fma_f32 v86, -v87, v93, v86
	v_div_scale_f32 v87, s[6:7], v44, v44, v88
	v_rcp_f32_e32 v94, v87
	v_div_fmas_f32 v86, v86, v95, v93
	v_div_fixup_f32 v89, v86, v45, v89
	v_and_b32_e32 v95, 0xffff0000, v35
	v_fma_f32 v45, -v87, v94, 1.0
	v_fmac_f32_e32 v94, v45, v94
	v_div_scale_f32 v45, vcc, v88, v44, v88
	v_mul_f32_e32 v86, v45, v94
	v_fma_f32 v93, -v87, v86, v45
	v_fmac_f32_e32 v86, v93, v94
	v_fma_f32 v45, -v87, v86, v45
	v_div_fmas_f32 v45, v45, v94, v86
	v_lshlrev_b32_e32 v94, 16, v35
	v_mul_f32_e32 v35, 0xbfb8aa3b, v98
	v_exp_f32_e32 v42, v35
	v_mul_f32_e32 v35, 0xbfb8aa3b, v99
	v_div_fixup_f32 v88, v45, v44, v88
	v_lshlrev_b64 v[44:45], 11, v[64:65]
	v_lshlrev_b32_e32 v65, 16, v43
	v_and_b32_e32 v93, 0xffff0000, v43
	v_exp_f32_e32 v43, v35
	v_lshlrev_b32_e32 v86, 16, v39
	v_and_b32_e32 v87, 0xffff0000, v39
	v_lshlrev_b32_e32 v96, 16, v38
	v_pk_add_f32 v[42:43], v[42:43], 1.0 op_sel_hi:[1,0]
	v_and_b32_e32 v97, 0xffff0000, v38
	v_div_scale_f32 v100, s[6:7], v43, v43, v99
	v_rcp_f32_e32 v101, v100
	v_lshlrev_b32_e32 v38, 16, v34
	v_and_b32_e32 v39, 0xffff0000, v34
	v_pk_add_f32 v[34:35], v[96:97], v[38:39]
	v_fma_f32 v38, -v100, v101, 1.0
	v_fmac_f32_e32 v101, v38, v101
	v_div_scale_f32 v38, vcc, v99, v43, v99
	v_mul_f32_e32 v39, v38, v101
	v_fma_f32 v102, -v100, v39, v38
	v_fmac_f32_e32 v39, v102, v101
	v_fma_f32 v38, -v100, v39, v38
	v_div_scale_f32 v100, s[6:7], v42, v42, v98
	v_rcp_f32_e32 v102, v100
	v_div_fmas_f32 v38, v38, v101, v39
	v_div_fixup_f32 v39, v38, v43, v99
	v_and_b32_e32 v101, 0xffff0000, v33
	v_fma_f32 v38, -v100, v102, 1.0
	v_fmac_f32_e32 v102, v38, v102
	v_div_scale_f32 v38, vcc, v98, v42, v98
	v_mul_f32_e32 v43, v38, v102
	v_fma_f32 v99, -v100, v43, v38
	v_fmac_f32_e32 v43, v99, v102
	v_fma_f32 v38, -v100, v43, v38
	v_div_fmas_f32 v38, v38, v102, v43
	v_lshlrev_b32_e32 v102, 16, v41
	v_and_b32_e32 v41, 0xffff0000, v41
	v_div_fixup_f32 v38, v38, v42, v98
	v_mul_f32_e32 v42, 0xbfb8aa3b, v102
	v_mul_f32_e32 v43, 0xbfb8aa3b, v41
	v_exp_f32_e32 v42, v42
	v_exp_f32_e32 v43, v43
	v_lshlrev_b32_e32 v98, 16, v37
	v_and_b32_e32 v99, 0xffff0000, v37
	v_lshlrev_b32_e32 v100, 16, v33
	v_pk_add_f32 v[42:43], v[42:43], 1.0 op_sel_hi:[1,0]
	v_pk_add_f32 v[98:99], v[98:99], v[100:101]
	v_div_scale_f32 v37, s[6:7], v43, v43, v41
	v_rcp_f32_e32 v103, v37
	v_pk_mul_f32 v[82:83], v[76:77], v[76:77]
	v_pk_mul_f32 v[100:101], v[98:99], v[98:99]
	v_pk_add_f32 v[50:51], v[78:79], v[50:51]
	v_fma_f32 v33, -v37, v103, 1.0
	v_fmac_f32_e32 v103, v33, v103
	v_div_scale_f32 v33, vcc, v41, v43, v41
	v_mul_f32_e32 v104, v33, v103
	v_fma_f32 v105, -v37, v104, v33
	v_fmac_f32_e32 v104, v105, v103
	v_fma_f32 v33, -v37, v104, v33
	v_div_scale_f32 v37, s[6:7], v42, v42, v102
	v_rcp_f32_e32 v105, v37
	v_div_fmas_f32 v33, v33, v103, v104
	v_div_fixup_f32 v103, v33, v43, v41
	v_lshlrev_b32_e32 v104, 16, v40
	v_fma_f32 v33, -v37, v105, 1.0
	v_fmac_f32_e32 v105, v33, v105
	v_div_scale_f32 v33, vcc, v102, v42, v102
	v_mul_f32_e32 v41, v33, v105
	v_fma_f32 v43, -v37, v41, v33
	v_fmac_f32_e32 v41, v43, v105
	v_fma_f32 v33, -v37, v41, v33
	v_div_fmas_f32 v33, v33, v105, v41
	v_and_b32_e32 v105, 0xffff0000, v40
	v_mul_f32_e32 v37, 0xbfb8aa3b, v104
	v_exp_f32_e32 v40, v37
	v_mul_f32_e32 v37, 0xbfb8aa3b, v105
	v_exp_f32_e32 v41, v37
	v_div_fixup_f32 v102, v33, v42, v102
	v_lshlrev_b32_e32 v42, 16, v36
	v_and_b32_e32 v43, 0xffff0000, v36
	v_pk_add_f32 v[36:37], v[40:41], 1.0 op_sel_hi:[1,0]
	v_lshlrev_b32_e32 v40, 16, v32
	v_div_scale_f32 v106, s[6:7], v37, v37, v105
	v_rcp_f32_e32 v107, v106
	v_and_b32_e32 v41, 0xffff0000, v32
	v_pk_add_f32 v[32:33], v[42:43], v[40:41]
	v_mov_b32_e32 v43, v49
	v_fma_f32 v40, -v106, v107, 1.0
	v_mov_b32_e32 v42, v33
	v_fmac_f32_e32 v107, v40, v107
	v_mov_b32_e32 v40, v32
	v_mov_b32_e32 v41, v48
	v_pk_mul_f32 v[42:43], v[42:43], v[42:43]
	v_pk_mul_f32 v[80:81], v[50:51], v[50:51]
	v_pk_fma_f32 v[40:41], v[40:41], v[40:41], v[42:43]
	v_mov_b32_e32 v42, v100
	v_mov_b32_e32 v43, v82
	v_pk_mul_f32 v[96:97], v[34:35], v[34:35]
	v_pk_add_f32 v[40:41], v[42:43], v[40:41]
	v_mov_b32_e32 v82, v101
	v_pk_add_f32 v[86:87], v[86:87], v[94:95]
	v_pk_add_f32 v[40:41], v[82:83], v[40:41]
	v_mov_b32_e32 v42, v96
	v_mov_b32_e32 v43, v80
	v_pk_mul_f32 v[78:79], v[46:47], v[46:47]
	v_pk_mul_f32 v[94:95], v[86:87], v[86:87]
	v_pk_add_f32 v[40:41], v[42:43], v[40:41]
	v_mov_b32_e32 v80, v97
	v_pk_add_f32 v[40:41], v[80:81], v[40:41]
	v_mov_b32_e32 v42, v94
	v_mov_b32_e32 v43, v78
	v_pk_add_f32 v[40:41], v[42:43], v[40:41]
	v_mov_b32_e32 v78, v95
	v_pk_add_f32 v[40:41], v[78:79], v[40:41]
	ds_bpermute_b32 v43, v59, v41
	ds_bpermute_b32 v42, v59, v40
	v_div_scale_f32 v108, vcc, v105, v37, v105
	v_mul_f32_e32 v109, v108, v107
	v_fma_f32 v110, -v106, v109, v108
	s_waitcnt lgkmcnt(0)
	v_pk_add_f32 v[40:41], v[40:41], v[42:43]
	ds_bpermute_b32 v43, v61, v41
	ds_bpermute_b32 v42, v61, v40
	v_fmac_f32_e32 v109, v110, v107
	v_fma_f32 v78, -v106, v109, v108
	v_div_fmas_f32 v78, v78, v107, v109
	v_div_fixup_f32 v37, v78, v37, v105
	s_waitcnt lgkmcnt(0)
	v_pk_add_f32 v[40:41], v[40:41], v[42:43]
	ds_bpermute_b32 v43, v90, v41
	ds_bpermute_b32 v42, v90, v40
	v_div_scale_f32 v78, s[6:7], v36, v36, v104
	v_rcp_f32_e32 v79, v78
	v_lshl_add_u64 v[44:45], v[62:63], 0, v[44:45]
	s_waitcnt lgkmcnt(0)
	v_pk_add_f32 v[40:41], v[40:41], v[42:43]
	ds_bpermute_b32 v43, v91, v41
	ds_bpermute_b32 v42, v91, v40
	v_fma_f32 v80, -v78, v79, 1.0
	v_fmac_f32_e32 v79, v80, v79
	v_div_scale_f32 v80, vcc, v104, v36, v104
	s_waitcnt lgkmcnt(0)
	v_pk_add_f32 v[40:41], v[40:41], v[42:43]
	v_mul_f32_e32 v81, v80, v79
	v_pk_fma_f32 v[42:43], v[40:41], s[22:23], v[72:73] op_sel_hi:[1,0,0]
	v_fma_f32 v82, -v78, v81, v80
	v_mul_f32_e32 v40, 0x4b800000, v43
	v_cmp_gt_f32_e64 s[10:11], s3, v43
	v_fmac_f32_e32 v81, v82, v79
	v_fma_f32 v78, -v78, v81, v80
	v_cndmask_b32_e64 v40, v43, v40, s[10:11]
	v_rsq_f32_e32 v40, v40
	v_div_fmas_f32 v41, v78, v79, v81
	v_div_fixup_f32 v36, v41, v36, v104
	v_mul_f32_e32 v43, 0x4b800000, v42
	v_mul_f32_e32 v41, 0x45800000, v40
	v_cndmask_b32_e64 v40, v40, v41, s[10:11]
	v_pk_mul_f32 v[48:49], v[48:49], v[40:41] op_sel_hi:[1,0]
	v_pk_mul_f32 v[76:77], v[76:77], v[40:41] op_sel_hi:[1,0]
	v_pk_mul_f32 v[48:49], v[4:5], v[48:49]
	v_pk_mul_f32 v[50:51], v[50:51], v[40:41] op_sel_hi:[1,0]
	v_pk_mul_f32 v[40:41], v[46:47], v[40:41] op_sel_hi:[1,0]
	v_cmp_gt_f32_e32 vcc, s3, v42
	v_pk_mul_f32 v[48:49], v[84:85], v[48:49]
	v_pk_mul_f32 v[40:41], v[2:3], v[40:41]
	v_cndmask_b32_e32 v42, v42, v43, vcc
	v_pk_mul_f32 v[46:47], v[88:89], v[40:41]
	v_cvt_pk_bf16_f32 v40, v48, v49
	v_rsq_f32_e32 v48, v42
	v_pk_mul_f32 v[76:77], v[6:7], v[76:77]
	v_pk_mul_f32 v[50:51], v[0:1], v[50:51]
	v_pk_mul_f32 v[52:53], v[52:53], v[76:77]
	v_pk_mul_f32 v[50:51], v[54:55], v[50:51]
	v_cvt_pk_bf16_f32 v41, v52, v53
	v_cvt_pk_bf16_f32 v42, v50, v51
	v_cvt_pk_bf16_f32 v43, v46, v47
	global_store_dwordx4 v[44:45], v[40:43], off sc1
	s_waitcnt vmcnt(1)
	v_lshlrev_b32_e32 v50, 16, v18
	v_and_b32_e32 v51, 0xffff0000, v18
	v_mul_f32_e32 v40, 0x45800000, v48
	v_cndmask_b32_e32 v40, v48, v40, vcc
	v_pk_mul_f32 v[32:33], v[32:33], v[40:41] op_sel_hi:[1,0]
	v_add_u32_e32 v64, s1, v64
	v_pk_mul_f32 v[32:33], v[4:5], v[32:33]
	s_nop 0
	v_pk_mul_f32 v[32:33], v[36:37], v[32:33]
	v_pk_mul_f32 v[36:37], v[98:99], v[40:41] op_sel_hi:[1,0]
	v_mul_f32_e32 v41, 0xbfb8aa3b, v65
	v_exp_f32_e32 v42, v41
	v_mul_f32_e32 v41, 0xbfb8aa3b, v93
	v_exp_f32_e32 v43, v41
	v_pk_mul_f32 v[34:35], v[34:35], v[40:41] op_sel_hi:[1,0]
	v_pk_mul_f32 v[36:37], v[6:7], v[36:37]
	v_pk_mul_f32 v[34:35], v[0:1], v[34:35]
	v_pk_add_f32 v[42:43], v[42:43], 1.0 op_sel_hi:[1,0]
	v_pk_mul_f32 v[34:35], v[38:39], v[34:35]
	v_div_scale_f32 v41, s[6:7], v43, v43, v93
	v_rcp_f32_e32 v46, v41
	v_pk_mul_f32 v[38:39], v[86:87], v[40:41] op_sel_hi:[1,0]
	v_pk_mul_f32 v[36:37], v[102:103], v[36:37]
	v_pk_mul_f32 v[38:39], v[2:3], v[38:39]
	v_fma_f32 v40, -v41, v46, 1.0
	v_fmac_f32_e32 v46, v40, v46
	v_div_scale_f32 v40, vcc, v93, v43, v93
	v_mul_f32_e32 v47, v40, v46
	v_fma_f32 v48, -v41, v47, v40
	v_fmac_f32_e32 v47, v48, v46
	v_div_scale_f32 v48, s[6:7], v42, v42, v65
	v_rcp_f32_e32 v49, v48
	v_fma_f32 v40, -v41, v47, v40
	v_div_fmas_f32 v40, v40, v46, v47
	v_div_fixup_f32 v41, v40, v43, v93
	v_fma_f32 v40, -v48, v49, 1.0
	v_fmac_f32_e32 v49, v40, v49
	v_div_scale_f32 v40, vcc, v65, v42, v65
	v_mul_f32_e32 v43, v40, v49
	v_fma_f32 v46, -v48, v43, v40
	v_fmac_f32_e32 v43, v46, v49
	v_fma_f32 v40, -v48, v43, v40
	v_div_fmas_f32 v40, v40, v49, v43
	v_div_fixup_f32 v40, v40, v42, v65
	v_pk_mul_f32 v[38:39], v[40:41], v[38:39]
	v_cvt_pk_bf16_f32 v32, v32, v33
	v_cvt_pk_bf16_f32 v33, v36, v37
	v_cvt_pk_bf16_f32 v34, v34, v35
	v_cvt_pk_bf16_f32 v35, v38, v39
	v_lshlrev_b32_e32 v38, 16, v30
	global_store_dwordx4 v[44:45], v[32:35], off offset:1024 sc1
	v_and_b32_e32 v39, 0xffff0000, v30
	v_lshlrev_b32_e32 v44, 16, v31
	v_lshlrev_b32_e32 v34, 16, v23
	v_and_b32_e32 v35, 0xffff0000, v23
	v_mul_f32_e32 v23, 0xbfb8aa3b, v38
	v_exp_f32_e32 v30, v23
	v_mul_f32_e32 v23, 0xbfb8aa3b, v39
	v_and_b32_e32 v45, 0xffff0000, v31
	v_exp_f32_e32 v31, v23
	v_lshlrev_b32_e32 v32, 16, v27
	v_and_b32_e32 v33, 0xffff0000, v27
	v_lshlrev_b32_e32 v36, 16, v26
	v_pk_add_f32 v[30:31], v[30:31], 1.0 op_sel_hi:[1,0]
	v_and_b32_e32 v37, 0xffff0000, v26
	v_div_scale_f32 v40, s[6:7], v31, v31, v39
	v_rcp_f32_e32 v41, v40
	v_lshlrev_b32_e32 v26, 16, v22
	v_and_b32_e32 v27, 0xffff0000, v22
	v_pk_add_f32 v[22:23], v[36:37], v[26:27]
	v_fma_f32 v26, -v40, v41, 1.0
	v_fmac_f32_e32 v41, v26, v41
	v_div_scale_f32 v26, vcc, v39, v31, v39
	v_mul_f32_e32 v27, v26, v41
	v_fma_f32 v42, -v40, v27, v26
	v_fmac_f32_e32 v27, v42, v41
	v_fma_f32 v26, -v40, v27, v26
	v_div_scale_f32 v40, s[6:7], v30, v30, v38
	v_rcp_f32_e32 v42, v40
	v_div_fmas_f32 v26, v26, v41, v27
	v_div_fixup_f32 v27, v26, v31, v39
	v_lshlrev_b32_e32 v46, 16, v29
	v_fma_f32 v26, -v40, v42, 1.0
	v_fmac_f32_e32 v42, v26, v42
	v_div_scale_f32 v26, vcc, v38, v30, v38
	v_mul_f32_e32 v31, v26, v42
	v_fma_f32 v39, -v40, v31, v26
	v_fmac_f32_e32 v31, v39, v42
	v_fma_f32 v26, -v40, v31, v26
	v_div_fmas_f32 v26, v26, v42, v31
	v_and_b32_e32 v29, 0xffff0000, v29
	v_div_fixup_f32 v26, v26, v30, v38
	v_mul_f32_e32 v30, 0xbfb8aa3b, v46
	v_mul_f32_e32 v31, 0xbfb8aa3b, v29
	v_exp_f32_e32 v30, v30
	v_exp_f32_e32 v31, v31
	v_lshlrev_b32_e32 v38, 16, v25
	v_and_b32_e32 v39, 0xffff0000, v25
	v_lshlrev_b32_e32 v40, 16, v21
	v_pk_add_f32 v[42:43], v[30:31], 1.0 op_sel_hi:[1,0]
	v_and_b32_e32 v41, 0xffff0000, v21
	v_div_scale_f32 v25, s[6:7], v43, v43, v29
	v_rcp_f32_e32 v47, v25
	v_pk_add_f32 v[30:31], v[38:39], v[40:41]
	v_and_b32_e32 v48, 0xffff0000, v28
	v_lshlrev_b32_e32 v65, 16, v19
	v_fma_f32 v21, -v25, v47, 1.0
	v_fmac_f32_e32 v47, v21, v47
	v_div_scale_f32 v21, vcc, v29, v43, v29
	v_mul_f32_e32 v40, v21, v47
	v_fma_f32 v41, -v25, v40, v21
	v_fmac_f32_e32 v40, v41, v47
	v_fma_f32 v21, -v25, v40, v21
	v_div_scale_f32 v25, s[6:7], v42, v42, v46
	v_rcp_f32_e32 v41, v25
	v_div_fmas_f32 v21, v21, v47, v40
	v_div_fixup_f32 v29, v21, v43, v29
	v_lshlrev_b32_e32 v47, 16, v28
	v_fma_f32 v21, -v25, v41, 1.0
	v_fmac_f32_e32 v41, v21, v41
	v_div_scale_f32 v21, vcc, v46, v42, v46
	v_mul_f32_e32 v40, v21, v41
	v_fma_f32 v43, -v25, v40, v21
	v_fmac_f32_e32 v40, v43, v41
	v_fma_f32 v21, -v25, v40, v21
	v_mul_f32_e32 v25, 0xbfb8aa3b, v47
	v_div_fmas_f32 v21, v21, v41, v40
	v_exp_f32_e32 v40, v25
	v_mul_f32_e32 v25, 0xbfb8aa3b, v48
	v_exp_f32_e32 v41, v25
	v_div_fixup_f32 v28, v21, v42, v46
	v_lshlrev_b32_e32 v42, 16, v24
	v_and_b32_e32 v43, 0xffff0000, v24
	v_pk_add_f32 v[40:41], v[40:41], 1.0 op_sel_hi:[1,0]
	v_lshlrev_b32_e32 v24, 16, v20
	v_div_scale_f32 v21, s[6:7], v41, v41, v48
	v_rcp_f32_e32 v46, v21
	v_and_b32_e32 v25, 0xffff0000, v20
	v_pk_add_f32 v[24:25], v[42:43], v[24:25]
	v_pk_mul_f32 v[38:39], v[30:31], v[30:31]
	v_fma_f32 v20, -v21, v46, 1.0
	v_fmac_f32_e32 v46, v20, v46
	v_div_scale_f32 v20, vcc, v48, v41, v48
	v_mul_f32_e32 v42, v20, v46
	v_fma_f32 v43, -v21, v42, v20
	v_fmac_f32_e32 v42, v43, v46
	v_div_scale_f32 v43, s[6:7], v40, v40, v47
	v_rcp_f32_e32 v49, v43
	v_fma_f32 v20, -v21, v42, v20
	v_div_fmas_f32 v20, v20, v46, v42
	v_div_fixup_f32 v41, v20, v41, v48
	v_fma_f32 v20, -v43, v49, 1.0
	v_fmac_f32_e32 v49, v20, v49
	v_mul_f32_e32 v20, 0xbfb8aa3b, v44
	v_mul_f32_e32 v21, 0xbfb8aa3b, v45
	v_exp_f32_e32 v20, v20
	v_exp_f32_e32 v21, v21
	v_div_scale_f32 v42, vcc, v47, v40, v47
	v_mul_f32_e32 v46, v42, v49
	v_fma_f32 v48, -v43, v46, v42
	v_fmac_f32_e32 v46, v48, v49
	v_pk_add_f32 v[20:21], v[20:21], 1.0 op_sel_hi:[1,0]
	v_fma_f32 v42, -v43, v46, v42
	v_div_scale_f32 v43, s[6:7], v21, v21, v45
	v_rcp_f32_e32 v48, v43
	v_div_fmas_f32 v42, v42, v49, v46
	v_div_fixup_f32 v40, v42, v40, v47
	v_and_b32_e32 v49, 0xffff0000, v14
	v_fma_f32 v42, -v43, v48, 1.0
	v_fmac_f32_e32 v48, v42, v48
	v_div_scale_f32 v42, vcc, v45, v21, v45
	v_mul_f32_e32 v46, v42, v48
	v_fma_f32 v47, -v43, v46, v42
	v_fmac_f32_e32 v46, v47, v48
	v_fma_f32 v42, -v43, v46, v42
	v_div_scale_f32 v43, s[6:7], v20, v20, v44
	v_rcp_f32_e32 v47, v43
	v_div_fmas_f32 v42, v42, v48, v46
	v_div_fixup_f32 v45, v42, v21, v45
	v_lshlrev_b32_e32 v48, 16, v14
	v_fma_f32 v21, -v43, v47, 1.0
	v_fmac_f32_e32 v47, v21, v47
	v_div_scale_f32 v21, vcc, v44, v20, v44
	v_mul_f32_e32 v42, v21, v47
	v_fma_f32 v46, -v43, v42, v21
	v_fmac_f32_e32 v42, v46, v47
	v_fma_f32 v21, -v43, v42, v21
	v_div_fmas_f32 v21, v21, v47, v42
	v_lshlrev_b32_e32 v46, 16, v11
	v_and_b32_e32 v47, 0xffff0000, v11
	v_mul_f32_e32 v11, 0xbfb8aa3b, v50
	v_exp_f32_e32 v18, v11
	v_mul_f32_e32 v11, 0xbfb8aa3b, v51
	v_div_fixup_f32 v44, v21, v20, v44
	v_lshlrev_b64 v[20:21], 11, v[74:75]
	v_and_b32_e32 v74, 0xffff0000, v19
	v_exp_f32_e32 v19, v11
	v_lshlrev_b32_e32 v42, 16, v15
	v_and_b32_e32 v43, 0xffff0000, v15
	v_lshlrev_b32_e32 v14, 16, v10
	v_pk_add_f32 v[18:19], v[18:19], 1.0 op_sel_hi:[1,0]
	v_and_b32_e32 v15, 0xffff0000, v10
	v_div_scale_f32 v52, s[6:7], v19, v19, v51
	v_rcp_f32_e32 v53, v52
	v_pk_add_f32 v[10:11], v[48:49], v[14:15]
	v_pk_mul_f32 v[36:37], v[22:23], v[22:23]
	v_pk_mul_f32 v[48:49], v[10:11], v[10:11]
	v_fma_f32 v14, -v52, v53, 1.0
	v_fmac_f32_e32 v53, v14, v53
	v_div_scale_f32 v14, vcc, v51, v19, v51
	v_mul_f32_e32 v15, v14, v53
	v_fma_f32 v54, -v52, v15, v14
	v_fmac_f32_e32 v15, v54, v53
	v_fma_f32 v14, -v52, v15, v14
	v_div_scale_f32 v52, s[6:7], v18, v18, v50
	v_rcp_f32_e32 v54, v52
	v_div_fmas_f32 v14, v14, v53, v15
	v_div_fixup_f32 v15, v14, v19, v51
	v_and_b32_e32 v53, 0xffff0000, v9
	v_fma_f32 v14, -v52, v54, 1.0
	v_fmac_f32_e32 v54, v14, v54
	v_div_scale_f32 v14, vcc, v50, v18, v50
	v_mul_f32_e32 v19, v14, v54
	v_fma_f32 v51, -v52, v19, v14
	v_fmac_f32_e32 v19, v51, v54
	v_fma_f32 v14, -v52, v19, v14
	v_div_fmas_f32 v14, v14, v54, v19
	v_lshlrev_b32_e32 v54, 16, v17
	v_and_b32_e32 v17, 0xffff0000, v17
	v_div_fixup_f32 v14, v14, v18, v50
	v_mul_f32_e32 v18, 0xbfb8aa3b, v54
	v_mul_f32_e32 v19, 0xbfb8aa3b, v17
	v_exp_f32_e32 v18, v18
	v_exp_f32_e32 v19, v19
	v_lshlrev_b32_e32 v50, 16, v13
	v_and_b32_e32 v51, 0xffff0000, v13
	v_lshlrev_b32_e32 v52, 16, v9
	v_pk_add_f32 v[18:19], v[18:19], 1.0 op_sel_hi:[1,0]
	v_pk_add_f32 v[50:51], v[50:51], v[52:53]
	v_div_scale_f32 v13, s[6:7], v19, v19, v17
	v_rcp_f32_e32 v55, v13
	v_pk_mul_f32 v[52:53], v[50:51], v[50:51]
	v_pk_add_f32 v[32:33], v[32:33], v[34:35]
	v_pk_add_f32 v[42:43], v[42:43], v[46:47]
	v_fma_f32 v9, -v13, v55, 1.0
	v_fmac_f32_e32 v55, v9, v55
	v_div_scale_f32 v9, vcc, v17, v19, v17
	v_mul_f32_e32 v75, v9, v55
	v_fma_f32 v76, -v13, v75, v9
	v_fmac_f32_e32 v75, v76, v55
	v_fma_f32 v9, -v13, v75, v9
	v_div_scale_f32 v13, s[6:7], v18, v18, v54
	v_rcp_f32_e32 v76, v13
	v_div_fmas_f32 v9, v9, v55, v75
	v_div_fixup_f32 v55, v9, v19, v17
	v_lshlrev_b32_e32 v75, 16, v16
	v_fma_f32 v9, -v13, v76, 1.0
	v_fmac_f32_e32 v76, v9, v76
	v_div_scale_f32 v9, vcc, v54, v18, v54
	v_mul_f32_e32 v17, v9, v76
	v_fma_f32 v19, -v13, v17, v9
	v_fmac_f32_e32 v17, v19, v76
	v_fma_f32 v9, -v13, v17, v9
	v_div_fmas_f32 v9, v9, v76, v17
	v_and_b32_e32 v76, 0xffff0000, v16
	v_mul_f32_e32 v13, 0xbfb8aa3b, v75
	v_exp_f32_e32 v16, v13
	v_mul_f32_e32 v13, 0xbfb8aa3b, v76
	v_exp_f32_e32 v17, v13
	v_div_fixup_f32 v54, v9, v18, v54
	v_lshlrev_b32_e32 v18, 16, v12
	v_and_b32_e32 v19, 0xffff0000, v12
	v_pk_add_f32 v[12:13], v[16:17], 1.0 op_sel_hi:[1,0]
	v_lshlrev_b32_e32 v16, 16, v8
	v_div_scale_f32 v77, s[6:7], v13, v13, v76
	v_rcp_f32_e32 v78, v77
	v_and_b32_e32 v17, 0xffff0000, v8
	v_pk_add_f32 v[8:9], v[18:19], v[16:17]
	v_mov_b32_e32 v19, v25
	v_fma_f32 v16, -v77, v78, 1.0
	v_mov_b32_e32 v18, v9
	v_fmac_f32_e32 v78, v16, v78
	v_mov_b32_e32 v16, v8
	v_mov_b32_e32 v17, v24
	v_pk_mul_f32 v[18:19], v[18:19], v[18:19]
	v_pk_mul_f32 v[34:35], v[32:33], v[32:33]
	v_pk_fma_f32 v[16:17], v[16:17], v[16:17], v[18:19]
	v_mov_b32_e32 v18, v52
	v_mov_b32_e32 v19, v38
	v_pk_add_f32 v[16:17], v[18:19], v[16:17]
	v_mov_b32_e32 v38, v53
	v_pk_add_f32 v[16:17], v[38:39], v[16:17]
	v_mov_b32_e32 v18, v48
	v_mov_b32_e32 v19, v36
	v_pk_mul_f32 v[46:47], v[42:43], v[42:43]
	v_pk_add_f32 v[16:17], v[18:19], v[16:17]
	v_mov_b32_e32 v36, v49
	v_pk_add_f32 v[16:17], v[36:37], v[16:17]
	v_mov_b32_e32 v18, v46
	v_mov_b32_e32 v19, v34
	v_pk_add_f32 v[16:17], v[18:19], v[16:17]
	v_mov_b32_e32 v34, v47
	v_pk_add_f32 v[16:17], v[34:35], v[16:17]
	ds_bpermute_b32 v19, v59, v17
	ds_bpermute_b32 v18, v59, v16
	v_div_scale_f32 v79, vcc, v76, v13, v76
	v_mul_f32_e32 v80, v79, v78
	v_fma_f32 v81, -v77, v80, v79
	s_waitcnt lgkmcnt(0)
	v_pk_add_f32 v[16:17], v[16:17], v[18:19]
	ds_bpermute_b32 v19, v61, v17
	ds_bpermute_b32 v18, v61, v16
	v_fmac_f32_e32 v80, v81, v78
	v_fma_f32 v34, -v77, v80, v79
	v_div_fmas_f32 v34, v34, v78, v80
	v_div_fixup_f32 v13, v34, v13, v76
	s_waitcnt lgkmcnt(0)
	v_pk_add_f32 v[16:17], v[16:17], v[18:19]
	ds_bpermute_b32 v19, v90, v17
	ds_bpermute_b32 v18, v90, v16
	v_div_scale_f32 v34, s[6:7], v12, v12, v75
	v_rcp_f32_e32 v35, v34
	v_lshl_add_u64 v[20:21], v[62:63], 0, v[20:21]
	s_waitcnt lgkmcnt(0)
	v_pk_add_f32 v[16:17], v[16:17], v[18:19]
	ds_bpermute_b32 v19, v91, v17
	ds_bpermute_b32 v18, v91, v16
	v_fma_f32 v36, -v34, v35, 1.0
	v_fmac_f32_e32 v35, v36, v35
	v_div_scale_f32 v36, vcc, v75, v12, v75
	s_waitcnt lgkmcnt(0)
	v_pk_add_f32 v[16:17], v[16:17], v[18:19]
	v_mul_f32_e32 v37, v36, v35
	v_pk_fma_f32 v[18:19], v[16:17], s[22:23], v[72:73] op_sel_hi:[1,0,0]
	v_fma_f32 v38, -v34, v37, v36
	v_mul_f32_e32 v16, 0x4b800000, v19
	v_cmp_gt_f32_e64 s[10:11], s3, v19
	v_fmac_f32_e32 v37, v38, v35
	v_fma_f32 v34, -v34, v37, v36
	v_cndmask_b32_e64 v16, v19, v16, s[10:11]
	v_rsq_f32_e32 v16, v16
	v_div_fmas_f32 v17, v34, v35, v37
	v_div_fixup_f32 v12, v17, v12, v75
	v_mul_f32_e32 v19, 0x4b800000, v18
	v_mul_f32_e32 v17, 0x45800000, v16
	v_cndmask_b32_e64 v16, v16, v17, s[10:11]
	v_pk_mul_f32 v[24:25], v[24:25], v[16:17] op_sel_hi:[1,0]
	v_pk_mul_f32 v[30:31], v[30:31], v[16:17] op_sel_hi:[1,0]
	v_pk_mul_f32 v[24:25], v[4:5], v[24:25]
	v_pk_mul_f32 v[22:23], v[22:23], v[16:17] op_sel_hi:[1,0]
	v_pk_mul_f32 v[16:17], v[32:33], v[16:17] op_sel_hi:[1,0]
	v_cmp_gt_f32_e32 vcc, s3, v18
	v_pk_mul_f32 v[24:25], v[40:41], v[24:25]
	v_pk_mul_f32 v[22:23], v[0:1], v[22:23]
	v_pk_mul_f32 v[16:17], v[2:3], v[16:17]
	v_cndmask_b32_e32 v18, v18, v19, vcc
	v_pk_mul_f32 v[22:23], v[26:27], v[22:23]
	v_pk_mul_f32 v[26:27], v[44:45], v[16:17]
	v_cvt_pk_bf16_f32 v16, v24, v25
	v_rsq_f32_e32 v24, v18
	v_pk_mul_f32 v[30:31], v[6:7], v[30:31]
	v_cvt_pk_bf16_f32 v18, v22, v23
	v_pk_mul_f32 v[28:29], v[28:29], v[30:31]
	v_cvt_pk_bf16_f32 v19, v26, v27
	v_cvt_pk_bf16_f32 v17, v28, v29
	global_store_dwordx4 v[20:21], v[16:19], off sc1
	s_nop 1
	v_mul_f32_e32 v16, 0x45800000, v24
	v_cndmask_b32_e32 v16, v24, v16, vcc
	v_pk_mul_f32 v[8:9], v[8:9], v[16:17] op_sel_hi:[1,0]
	s_nop 0
	v_pk_mul_f32 v[8:9], v[4:5], v[8:9]
	s_nop 0
	v_pk_mul_f32 v[8:9], v[12:13], v[8:9]
	v_pk_mul_f32 v[12:13], v[50:51], v[16:17] op_sel_hi:[1,0]
	v_mul_f32_e32 v17, 0xbfb8aa3b, v65
	v_exp_f32_e32 v18, v17
	v_mul_f32_e32 v17, 0xbfb8aa3b, v74
	v_exp_f32_e32 v19, v17
	v_pk_mul_f32 v[10:11], v[10:11], v[16:17] op_sel_hi:[1,0]
	v_pk_mul_f32 v[12:13], v[6:7], v[12:13]
	v_pk_mul_f32 v[10:11], v[0:1], v[10:11]
	v_pk_add_f32 v[18:19], v[18:19], 1.0 op_sel_hi:[1,0]
	v_pk_mul_f32 v[10:11], v[14:15], v[10:11]
	v_div_scale_f32 v17, s[6:7], v19, v19, v74
	v_rcp_f32_e32 v22, v17
	v_pk_mul_f32 v[14:15], v[42:43], v[16:17] op_sel_hi:[1,0]
	v_pk_mul_f32 v[12:13], v[54:55], v[12:13]
	v_pk_mul_f32 v[14:15], v[2:3], v[14:15]
	v_fma_f32 v16, -v17, v22, 1.0
	v_fmac_f32_e32 v22, v16, v22
	v_div_scale_f32 v16, vcc, v74, v19, v74
	v_mul_f32_e32 v23, v16, v22
	v_fma_f32 v24, -v17, v23, v16
	v_fmac_f32_e32 v23, v24, v22
	v_div_scale_f32 v24, s[6:7], v18, v18, v65
	v_rcp_f32_e32 v25, v24
	v_fma_f32 v16, -v17, v23, v16
	v_div_fmas_f32 v16, v16, v22, v23
	v_div_fixup_f32 v17, v16, v19, v74
	v_fma_f32 v16, -v24, v25, 1.0
	v_fmac_f32_e32 v25, v16, v25
	v_div_scale_f32 v16, vcc, v65, v18, v65
	v_mul_f32_e32 v19, v16, v25
	v_fma_f32 v22, -v24, v19, v16
	v_fmac_f32_e32 v19, v22, v25
	v_fma_f32 v16, -v24, v19, v16
	v_div_fmas_f32 v16, v16, v25, v19
	v_div_fixup_f32 v16, v16, v18, v65
	v_pk_mul_f32 v[14:15], v[16:17], v[14:15]
	v_cmp_lt_i32_e32 vcc, s4, v92
	v_cvt_pk_bf16_f32 v8, v8, v9
	v_cvt_pk_bf16_f32 v9, v12, v13
	v_cvt_pk_bf16_f32 v10, v10, v11
	v_cvt_pk_bf16_f32 v11, v14, v15
	s_or_b64 s[18:19], vcc, s[18:19]
	global_store_dwordx4 v[20:21], v[8:11], off offset:1024 sc1
	s_andn2_b64 exec, exec, s[18:19]
	s_cbranch_execnz .LBB0_1044

.LBB0_1101:
	s_add_i32 s33, s40, 2
	s_cmp_lt_u32 s40, 14
	s_cselect_b32 s42, s2, 0x700
	s_min_u32 s26, s40, 12
	s_lshl_b32 s26, s26, 7
	s_addk_i32 s2, 0x100
	s_ashr_i32 s43, s42, 31
	s_addk_i32 s26, 0x180
	s_cmp_gt_u32 s40, 13
	s_setprio 1
	ds_read_b128 v[126:129], v119 offset:32768
	ds_read_b128 v[134:137], v119 offset:34816
	ds_read_b128 v[130:133], v118
	ds_read_b128 v[138:141], v118 offset:2048
	ds_read_b128 v[160:163], v118 offset:4096
	ds_read_b128 v[164:167], v118 offset:6144
	v_add_u32_e32 v99, s42, v96
	v_add_u32_e32 v142, 0x10000, v99
	s_waitcnt lgkmcnt(3)
	v_mfma_f32_16x16x32_bf16 v[64:67], v[126:129], v[130:133], v[64:67]
	ds_read_b128 v[168:171], v119 offset:36864
	v_mfma_f32_16x16x32_bf16 v[40:43], v[134:137], v[130:133], v[40:43]
	ds_read_b128 v[172:175], v119 offset:38912
	s_waitcnt lgkmcnt(1)
	v_mfma_f32_16x16x32_bf16 v[28:31], v[168:171], v[130:133], v[28:31]
	s_waitcnt lgkmcnt(0)
	v_mfma_f32_16x16x32_bf16 v[12:15], v[172:175], v[130:133], v[12:15]
	v_lshl_add_u64 v[130:131], v[100:101], 0, s[42:43]
	global_load_dwordx4 v[130:133], v[130:131], off
	ds_read_b128 v[176:179], v120
	v_mfma_f32_16x16x32_bf16 v[60:63], v[126:129], v[138:141], v[60:63]
	v_mfma_f32_16x16x32_bf16 v[44:47], v[134:137], v[138:141], v[44:47]
	global_load_dwordx4 v[180:183], v142, s[18:19]
	ds_read_b128 v[184:187], v120 offset:2048
	v_mfma_f32_16x16x32_bf16 v[24:27], v[168:171], v[138:141], v[24:27]
	v_mfma_f32_16x16x32_bf16 v[8:11], v[172:175], v[138:141], v[8:11]
	v_add_u32_e32 v138, 0x20000, v99
	v_add_u32_e32 v99, 0x30000, v99
	global_load_dwordx4 v[138:141], v138, s[18:19]
	ds_read_b128 v[188:191], v120 offset:4096
	v_mfma_f32_16x16x32_bf16 v[52:55], v[126:129], v[160:163], v[52:55]
	v_mfma_f32_16x16x32_bf16 v[36:39], v[134:137], v[160:163], v[36:39]
	global_load_dwordx4 v[192:195], v99, s[18:19]
	v_add_u32_e32 v99, s42, v98
	ds_read_b128 v[196:199], v120 offset:6144
	v_mfma_f32_16x16x32_bf16 v[20:23], v[168:171], v[160:163], v[20:23]
	v_add_u32_e32 v142, 0x20000, v99
	v_mfma_f32_16x16x32_bf16 v[4:7], v[172:175], v[160:163], v[4:7]
	global_load_dwordx4 v[160:163], v99, s[16:17]
	ds_read_b128 v[200:203], v121 offset:32768
	v_mfma_f32_16x16x32_bf16 v[48:51], v[126:129], v[164:167], v[48:51]
	v_add_u32_e32 v126, 0x10000, v99
	v_add_u32_e32 v99, 0x30000, v99
	v_mfma_f32_16x16x32_bf16 v[32:35], v[134:137], v[164:167], v[32:35]
	global_load_dwordx4 v[126:129], v126, s[16:17]
	ds_read_b128 v[134:137], v121 offset:34816
	v_mfma_f32_16x16x32_bf16 v[16:19], v[168:171], v[164:167], v[16:19]
	v_mfma_f32_16x16x32_bf16 v[0:3], v[172:175], v[164:167], v[0:3]
	global_load_dwordx4 v[164:167], v142, s[16:17]
	ds_read_b128 v[168:171], v121 offset:36864
	s_waitcnt lgkmcnt(2)
	v_mfma_f32_16x16x32_bf16 v[64:67], v[200:203], v[176:179], v[64:67]
	s_waitcnt lgkmcnt(1)
	v_mfma_f32_16x16x32_bf16 v[40:43], v[134:137], v[176:179], v[40:43]
	global_load_dwordx4 v[172:175], v99, s[16:17]
	ds_read_b128 v[204:207], v121 offset:38912
	s_waitcnt lgkmcnt(1)
	v_mfma_f32_16x16x32_bf16 v[28:31], v[168:171], v[176:179], v[28:31]
	s_waitcnt lgkmcnt(0)
	v_mfma_f32_16x16x32_bf16 v[12:15], v[204:207], v[176:179], v[12:15]
	s_waitcnt vmcnt(14)
	ds_write_b128 v117, v[56:59] offset:16384
	v_mfma_f32_16x16x32_bf16 v[60:63], v[200:203], v[184:187], v[60:63]
	v_mfma_f32_16x16x32_bf16 v[44:47], v[134:137], v[184:187], v[44:47]
	s_waitcnt vmcnt(13)
	ds_write_b128 v117, v[68:71] offset:20480
	v_mfma_f32_16x16x32_bf16 v[24:27], v[168:171], v[184:187], v[24:27]
	v_mfma_f32_16x16x32_bf16 v[8:11], v[204:207], v[184:187], v[8:11]
	s_waitcnt vmcnt(12)
	ds_write_b128 v117, v[72:75] offset:24576
	v_mfma_f32_16x16x32_bf16 v[52:55], v[200:203], v[188:191], v[52:55]
	v_mfma_f32_16x16x32_bf16 v[36:39], v[134:137], v[188:191], v[36:39]
	s_waitcnt vmcnt(11)
	ds_write_b128 v117, v[80:83] offset:28672
	v_mfma_f32_16x16x32_bf16 v[20:23], v[168:171], v[188:191], v[20:23]
	v_mfma_f32_16x16x32_bf16 v[4:7], v[204:207], v[188:191], v[4:7]
	ds_write_b128 v117, v[76:79] offset:49152
	v_mfma_f32_16x16x32_bf16 v[48:51], v[200:203], v[196:199], v[48:51]
	v_mfma_f32_16x16x32_bf16 v[32:35], v[134:137], v[196:199], v[32:35]
	s_waitcnt vmcnt(10)
	ds_write_b128 v117, v[84:87] offset:53248
	v_mfma_f32_16x16x32_bf16 v[16:19], v[168:171], v[196:199], v[16:19]
	v_mfma_f32_16x16x32_bf16 v[0:3], v[204:207], v[196:199], v[0:3]
	s_waitcnt vmcnt(9)
	ds_write_b128 v117, v[88:91] offset:57344
	s_waitcnt vmcnt(8)
	ds_write_b128 v117, v[92:95] offset:61440
	s_setprio 0
	s_waitcnt lgkmcnt(0)
	s_barrier
	s_setprio 1
	ds_read_b128 v[84:87], v119 offset:49152
	ds_read_b128 v[88:91], v119 offset:51200
	ds_read_b128 v[56:59], v118 offset:16384
	ds_read_b128 v[72:75], v118 offset:18432
	ds_read_b128 v[76:79], v118 offset:20480
	ds_read_b128 v[92:95], v118 offset:22528
	v_lshl_add_u64 v[68:69], v[110:111], 0, s[26:27]
	v_lshl_add_u64 v[80:81], v[114:115], 0, s[26:27]
	s_waitcnt lgkmcnt(3)
	v_mfma_f32_16x16x32_bf16 v[64:67], v[84:87], v[56:59], v[64:67]
	ds_read_b128 v[134:137], v119 offset:53248
	v_mfma_f32_16x16x32_bf16 v[40:43], v[88:91], v[56:59], v[40:43]
	ds_read_b128 v[168:171], v119 offset:55296
	s_waitcnt lgkmcnt(1)
	v_mfma_f32_16x16x32_bf16 v[28:31], v[134:137], v[56:59], v[28:31]
	s_waitcnt lgkmcnt(0)
	v_mfma_f32_16x16x32_bf16 v[12:15], v[168:171], v[56:59], v[12:15]
	v_lshl_add_u64 v[56:57], v[100:101], 0, s[26:27]
	global_load_dwordx4 v[56:59], v[56:57], off
	ds_read_b128 v[176:179], v120 offset:16384
	v_mfma_f32_16x16x32_bf16 v[60:63], v[84:87], v[72:75], v[60:63]
	v_mfma_f32_16x16x32_bf16 v[44:47], v[88:91], v[72:75], v[44:47]
	global_load_dwordx4 v[68:71], v[68:69], off
	ds_read_b128 v[184:187], v120 offset:18432
	v_mfma_f32_16x16x32_bf16 v[24:27], v[134:137], v[72:75], v[24:27]
	v_mfma_f32_16x16x32_bf16 v[8:11], v[168:171], v[72:75], v[8:11]
	v_lshl_add_u64 v[72:73], v[112:113], 0, s[26:27]
	global_load_dwordx4 v[72:75], v[72:73], off
	ds_read_b128 v[188:191], v120 offset:20480
	v_mfma_f32_16x16x32_bf16 v[52:55], v[84:87], v[76:79], v[52:55]
	v_mfma_f32_16x16x32_bf16 v[36:39], v[88:91], v[76:79], v[36:39]
	global_load_dwordx4 v[80:83], v[80:81], off
	ds_read_b128 v[196:199], v120 offset:22528
	v_mfma_f32_16x16x32_bf16 v[20:23], v[134:137], v[76:79], v[20:23]
	v_mfma_f32_16x16x32_bf16 v[4:7], v[168:171], v[76:79], v[4:7]
	v_lshl_add_u64 v[76:77], v[102:103], 0, s[26:27]
	global_load_dwordx4 v[76:79], v[76:77], off
	ds_read_b128 v[200:203], v121 offset:49152
	v_mfma_f32_16x16x32_bf16 v[48:51], v[84:87], v[92:95], v[48:51]
	v_lshl_add_u64 v[84:85], v[104:105], 0, s[26:27]
	v_mfma_f32_16x16x32_bf16 v[32:35], v[88:91], v[92:95], v[32:35]
	global_load_dwordx4 v[84:87], v[84:85], off
	ds_read_b128 v[204:207], v121 offset:51200
	v_lshl_add_u64 v[88:89], v[106:107], 0, s[26:27]
	v_mfma_f32_16x16x32_bf16 v[16:19], v[134:137], v[92:95], v[16:19]
	v_mfma_f32_16x16x32_bf16 v[0:3], v[168:171], v[92:95], v[0:3]
	v_lshl_add_u64 v[92:93], v[108:109], 0, s[26:27]
	global_load_dwordx4 v[88:91], v[88:89], off
	ds_read_b128 v[134:137], v121 offset:53248
	s_waitcnt lgkmcnt(2)
	v_mfma_f32_16x16x32_bf16 v[64:67], v[200:203], v[176:179], v[64:67]
	s_waitcnt lgkmcnt(1)
	v_mfma_f32_16x16x32_bf16 v[40:43], v[204:207], v[176:179], v[40:43]
	global_load_dwordx4 v[92:95], v[92:93], off
	ds_read_b128 v[168:171], v121 offset:55296
	s_waitcnt lgkmcnt(1)
	v_mfma_f32_16x16x32_bf16 v[28:31], v[134:137], v[176:179], v[28:31]
	s_waitcnt lgkmcnt(0)
	v_mfma_f32_16x16x32_bf16 v[12:15], v[168:171], v[176:179], v[12:15]
	s_waitcnt vmcnt(15)
	ds_write_b128 v117, v[130:133]
	v_mfma_f32_16x16x32_bf16 v[60:63], v[200:203], v[184:187], v[60:63]
	v_mfma_f32_16x16x32_bf16 v[44:47], v[204:207], v[184:187], v[44:47]
	s_waitcnt vmcnt(14)
	ds_write_b128 v117, v[180:183] offset:4096
	v_mfma_f32_16x16x32_bf16 v[24:27], v[134:137], v[184:187], v[24:27]
	v_mfma_f32_16x16x32_bf16 v[8:11], v[168:171], v[184:187], v[8:11]
	s_waitcnt vmcnt(13)
	ds_write_b128 v117, v[138:141] offset:8192
	v_mfma_f32_16x16x32_bf16 v[52:55], v[200:203], v[188:191], v[52:55]
	v_mfma_f32_16x16x32_bf16 v[36:39], v[204:207], v[188:191], v[36:39]
	s_waitcnt vmcnt(12)
	ds_write_b128 v117, v[192:195] offset:12288
	v_mfma_f32_16x16x32_bf16 v[20:23], v[134:137], v[188:191], v[20:23]
	v_mfma_f32_16x16x32_bf16 v[4:7], v[168:171], v[188:191], v[4:7]
	s_waitcnt vmcnt(11)
	ds_write_b128 v117, v[160:163] offset:32768
	v_mfma_f32_16x16x32_bf16 v[48:51], v[200:203], v[196:199], v[48:51]
	v_mfma_f32_16x16x32_bf16 v[32:35], v[204:207], v[196:199], v[32:35]
	s_waitcnt vmcnt(10)
	ds_write_b128 v117, v[126:129] offset:36864
	v_mfma_f32_16x16x32_bf16 v[16:19], v[134:137], v[196:199], v[16:19]
	v_mfma_f32_16x16x32_bf16 v[0:3], v[168:171], v[196:199], v[0:3]
	s_waitcnt vmcnt(9)
	ds_write_b128 v117, v[164:167] offset:40960
	s_waitcnt vmcnt(8)
	ds_write_b128 v117, v[172:175] offset:45056
	s_setprio 0
	s_mov_b32 s40, s33
	s_waitcnt lgkmcnt(0)
	s_barrier
	s_cbranch_scc0 .LBB0_1101
	s_waitcnt vmcnt(1)
	v_add_u32_e32 v88, s1, v122
	s_addk_i32 s1, 0xf000
	s_ashr_i32 s1, s1, 10
	s_add_i32 s1, s1, 1
	s_and_b64 s[40:41], s[20:21], exec
	s_cselect_b32 s1, 0, s1
	s_mul_i32 s2, s1, 0x3000
	s_add_i32 s26, s1, 10
	s_add_i32 s33, s2, 0x1e000
	s_mul_hi_u32 s26, s26, 0x3000
	s_add_u32 s33, s4, s33
	s_addc_u32 s26, s5, s26
	s_add_u32 s42, s33, 0x2000
	s_addc_u32 s43, s26, 0
	s_add_i32 s1, s1, 15
	s_add_i32 s2, s2, 0x2d000
	s_mul_hi_u32 s1, s1, 0x3000
	s_add_u32 s2, s4, s2
	s_addc_u32 s1, s5, s1
	s_add_u32 s40, s2, 0x1000
	v_or_b32_e32 v96, s0, v123
	v_lshlrev_b64 v[72:73], 2, v[96:97]
	s_addc_u32 s41, s1, 0
	v_lshl_add_u64 v[56:57], s[42:43], 0, v[72:73]
	v_lshl_add_u64 v[70:71], s[12:13], 0, v[72:73]
	v_lshlrev_b32_e32 v58, 12, v88
	v_mov_b32_e32 v59, v97
	v_lshl_add_u64 v[74:75], s[40:41], 0, v[72:73]
	v_lshl_add_u64 v[68:69], v[70:71], 0, v[58:59]
	global_load_dwordx4 v[90:93], v[56:57], off
	s_nop 0
	global_load_dwordx4 v[56:59], v[68:69], off
	global_load_dwordx4 v[78:81], v[74:75], off
	v_lshl_add_u64 v[72:73], s[14:15], 0, v[72:73]
	global_load_dwordx4 v[82:85], v[72:73], off
	v_mov_b32_e32 v75, v97
	v_lshlrev_b32_e32 v74, 1, v96
	v_lshlrev_b32_e32 v89, 10, v88
	v_mov_b32_e32 v87, v97
	v_lshlrev_b32_e32 v86, 11, v88
	s_waitcnt vmcnt(4)
	v_lshl_add_u64 v[94:95], s[22:23], 0, v[74:75]
	v_or_b32_e32 v104, 0x4000, v89
	v_mov_b32_e32 v77, v97
	v_lshl_add_u64 v[74:75], v[94:95], 0, v[86:87]
	v_lshlrev_b32_e32 v76, 2, v104
	v_lshl_add_u64 v[98:99], v[70:71], 0, v[76:77]
	v_mov_b32_e32 v107, v97
	v_or_b32_e32 v106, 16, v96
	v_lshl_add_u64 v[86:87], s[22:23], 0, v[86:87]
	s_waitcnt vmcnt(2)
	v_pk_fma_f32 v[64:65], v[64:65], v[90:91], v[56:57]
	v_pk_fma_f32 v[66:67], v[66:67], v[92:93], v[58:59]
	s_waitcnt vmcnt(1)
	v_pk_add_f32 v[56:57], v[78:79], 1.0 op_sel_hi:[1,0]
	v_pk_add_f32 v[58:59], v[80:81], 1.0 op_sel_hi:[1,0]
	s_waitcnt vmcnt(0)
	v_pk_mul_f32 v[100:101], v[82:83], v[56:57]
	v_pk_mul_f32 v[102:103], v[84:85], v[58:59]
	v_pk_mul_f32 v[56:57], v[100:101], v[64:65]
	v_pk_mul_f32 v[58:59], v[102:103], v[66:67]
	v_cvt_pk_bf16_f32 v56, v56, v57
	v_cvt_pk_bf16_f32 v57, v58, v59
	global_store_dwordx4 v[68:69], v[64:67], off sc1
	global_store_dwordx2 v[74:75], v[56:57], off
	global_load_dwordx4 v[56:59], v[98:99], off
	v_mov_b32_e32 v79, v97
	v_or_b32_e32 v82, 0x8000, v89
	v_lshlrev_b32_e32 v78, 1, v104
	v_mov_b32_e32 v81, v97
	v_lshlrev_b32_e32 v80, 2, v82
	v_lshl_add_u64 v[74:75], v[94:95], 0, v[78:79]
	v_lshl_add_u64 v[104:105], v[70:71], 0, v[80:81]
	v_mov_b32_e32 v83, v97
	v_or_b32_e32 v89, 0xc000, v89
	v_lshlrev_b32_e32 v82, 1, v82
	v_mov_b32_e32 v85, v97
	v_lshlrev_b32_e32 v84, 2, v89
	v_pk_mul_f32 v[64:65], v[64:65], v[64:65]
	v_pk_mul_f32 v[66:67], v[66:67], v[66:67]
	v_add_f32_e32 v64, v64, v65
	v_add_f32_e32 v64, v66, v64
	v_add_f32_e32 v64, v67, v64
	s_waitcnt vmcnt(0)
	v_pk_fma_f32 v[56:57], v[60:61], v[90:91], v[56:57]
	v_pk_fma_f32 v[58:59], v[62:63], v[92:93], v[58:59]
	v_pk_mul_f32 v[60:61], v[100:101], v[56:57]
	v_pk_mul_f32 v[62:63], v[102:103], v[58:59]
	v_cvt_pk_bf16_f32 v60, v60, v61
	v_cvt_pk_bf16_f32 v61, v62, v63
	global_store_dwordx4 v[98:99], v[56:59], off sc1
	global_store_dwordx2 v[74:75], v[60:61], off
	global_load_dwordx4 v[60:63], v[104:105], off
	v_lshl_add_u64 v[74:75], v[94:95], 0, v[82:83]
	v_lshl_add_u64 v[98:99], v[70:71], 0, v[84:85]
	s_waitcnt vmcnt(0)
	v_pk_fma_f32 v[52:53], v[52:53], v[90:91], v[60:61]
	v_pk_fma_f32 v[54:55], v[54:55], v[92:93], v[62:63]
	v_pk_mul_f32 v[60:61], v[100:101], v[52:53]
	v_pk_mul_f32 v[62:63], v[102:103], v[54:55]
	v_cvt_pk_bf16_f32 v60, v60, v61
	v_cvt_pk_bf16_f32 v61, v62, v63
	global_store_dwordx4 v[104:105], v[52:55], off sc1
	global_store_dwordx2 v[74:75], v[60:61], off
	global_load_dwordx4 v[60:63], v[98:99], off
	v_mov_b32_e32 v75, v97
	v_lshlrev_b32_e32 v74, 1, v89
	v_lshlrev_b64 v[104:105], 2, v[106:107]
	v_lshl_add_u64 v[94:95], v[94:95], 0, v[74:75]
	v_lshl_add_u64 v[108:109], s[42:43], 0, v[104:105]
	s_waitcnt vmcnt(0)
	v_pk_fma_f32 v[48:49], v[48:49], v[90:91], v[60:61]
	v_pk_fma_f32 v[50:51], v[50:51], v[92:93], v[62:63]
	v_pk_mul_f32 v[60:61], v[100:101], v[48:49]
	v_pk_mul_f32 v[62:63], v[102:103], v[50:51]
	v_cvt_pk_bf16_f32 v60, v60, v61
	v_cvt_pk_bf16_f32 v61, v62, v63
	global_store_dwordx4 v[98:99], v[48:51], off sc1
	global_store_dwordx2 v[94:95], v[60:61], off
	global_load_dwordx4 v[90:93], v[108:109], off
	s_nop 0
	global_load_dwordx4 v[60:63], v[68:69], off offset:64
	v_lshl_add_u64 v[94:95], s[40:41], 0, v[104:105]
	global_load_dwordx4 v[98:101], v[94:95], off
	global_load_dwordx4 v[102:105], v[72:73], off offset:64
	v_mov_b32_e32 v95, v97
	v_lshlrev_b32_e32 v94, 1, v106
	v_lshl_add_u64 v[106:107], v[70:71], 0, 64
	v_lshl_add_u64 v[108:109], v[86:87], 0, v[94:95]
	v_lshl_add_u64 v[110:111], v[106:107], 0, v[76:77]
	v_lshl_add_u64 v[94:95], s[22:23], 0, v[94:95]
	s_waitcnt vmcnt(2)
	v_pk_fma_f32 v[60:61], v[40:41], v[90:91], v[60:61]
	v_pk_fma_f32 v[62:63], v[42:43], v[92:93], v[62:63]
	s_waitcnt vmcnt(1)
	v_pk_add_f32 v[40:41], v[98:99], 1.0 op_sel_hi:[1,0]
	v_pk_add_f32 v[42:43], v[100:101], 1.0 op_sel_hi:[1,0]
	s_waitcnt vmcnt(0)
	v_pk_mul_f32 v[98:99], v[102:103], v[40:41]
	v_pk_mul_f32 v[100:101], v[104:105], v[42:43]
	v_pk_mul_f32 v[40:41], v[98:99], v[60:61]
	v_pk_mul_f32 v[42:43], v[100:101], v[62:63]
	v_cvt_pk_bf16_f32 v40, v40, v41
	v_cvt_pk_bf16_f32 v41, v42, v43
	global_store_dwordx4 v[68:69], v[60:63], off offset:64 sc1
	global_store_dwordx2 v[108:109], v[40:41], off
	global_load_dwordx4 v[40:43], v[110:111], off
	v_lshl_add_u64 v[102:103], v[94:95], 0, v[78:79]
	v_lshl_add_u64 v[104:105], v[106:107], 0, v[80:81]
	v_lshl_add_u64 v[106:107], v[106:107], 0, v[84:85]
	v_mov_b32_e32 v109, v97
	v_or_b32_e32 v108, 32, v96
	v_or_b32_e32 v96, 48, v96
	v_pk_mul_f32 v[60:61], v[60:61], v[60:61]
	v_pk_mul_f32 v[62:63], v[62:63], v[62:63]
	v_add_f32_e32 v60, v60, v61
	v_add_f32_e32 v60, v62, v60
	v_add_f32_e32 v60, v63, v60
	v_add_f32_e32 v60, v64, v60
	s_waitcnt vmcnt(0)
	v_pk_fma_f32 v[40:41], v[44:45], v[90:91], v[40:41]
	v_pk_fma_f32 v[42:43], v[46:47], v[92:93], v[42:43]
	v_pk_mul_f32 v[44:45], v[98:99], v[40:41]
	v_pk_mul_f32 v[46:47], v[100:101], v[42:43]
	v_cvt_pk_bf16_f32 v44, v44, v45
	v_cvt_pk_bf16_f32 v45, v46, v47
	global_store_dwordx4 v[110:111], v[40:43], off sc1
	global_store_dwordx2 v[102:103], v[44:45], off
	global_load_dwordx4 v[44:47], v[104:105], off
	v_lshl_add_u64 v[102:103], v[94:95], 0, v[82:83]
	v_lshl_add_u64 v[94:95], v[94:95], 0, v[74:75]
	s_waitcnt vmcnt(0)
	v_pk_fma_f32 v[36:37], v[36:37], v[90:91], v[44:45]
	v_pk_fma_f32 v[38:39], v[38:39], v[92:93], v[46:47]
	v_pk_mul_f32 v[44:45], v[98:99], v[36:37]
	v_pk_mul_f32 v[46:47], v[100:101], v[38:39]
	v_cvt_pk_bf16_f32 v44, v44, v45
	v_cvt_pk_bf16_f32 v45, v46, v47
	global_store_dwordx4 v[104:105], v[36:39], off sc1
	global_store_dwordx2 v[102:103], v[44:45], off
	global_load_dwordx4 v[44:47], v[106:107], off
	v_lshlrev_b64 v[102:103], 2, v[108:109]
	v_lshl_add_u64 v[104:105], s[42:43], 0, v[102:103]
	s_waitcnt vmcnt(0)
	v_pk_fma_f32 v[32:33], v[32:33], v[90:91], v[44:45]
	v_pk_fma_f32 v[34:35], v[34:35], v[92:93], v[46:47]
	v_pk_mul_f32 v[44:45], v[98:99], v[32:33]
	v_pk_mul_f32 v[46:47], v[100:101], v[34:35]
	v_cvt_pk_bf16_f32 v44, v44, v45
	v_cvt_pk_bf16_f32 v45, v46, v47
	global_store_dwordx4 v[106:107], v[32:35], off sc1
	global_store_dwordx2 v[94:95], v[44:45], off
	global_load_dwordx4 v[44:47], v[104:105], off
	s_nop 0
	global_load_dwordx4 v[90:93], v[68:69], off offset:128
	v_lshl_add_u64 v[94:95], s[40:41], 0, v[102:103]
	global_load_dwordx4 v[98:101], v[94:95], off
	global_load_dwordx4 v[102:105], v[72:73], off offset:128
	v_mov_b32_e32 v95, v97
	v_lshlrev_b32_e32 v94, 1, v108
	v_lshl_add_u64 v[106:107], v[70:71], 0, s[36:37]
	v_lshl_add_u64 v[108:109], v[86:87], 0, v[94:95]
	v_lshl_add_u64 v[110:111], v[106:107], 0, v[76:77]
	v_lshl_add_u64 v[94:95], s[22:23], 0, v[94:95]
	s_waitcnt vmcnt(2)
	v_pk_fma_f32 v[28:29], v[28:29], v[44:45], v[90:91]
	v_pk_fma_f32 v[30:31], v[30:31], v[46:47], v[92:93]
	s_waitcnt vmcnt(1)
	v_pk_add_f32 v[90:91], v[98:99], 1.0 op_sel_hi:[1,0]
	v_pk_add_f32 v[92:93], v[100:101], 1.0 op_sel_hi:[1,0]
	s_waitcnt vmcnt(0)
	v_pk_mul_f32 v[98:99], v[102:103], v[90:91]
	v_pk_mul_f32 v[100:101], v[104:105], v[92:93]
	v_pk_mul_f32 v[90:91], v[98:99], v[28:29]
	v_pk_mul_f32 v[92:93], v[100:101], v[30:31]
	v_cvt_pk_bf16_f32 v90, v90, v91
	v_cvt_pk_bf16_f32 v91, v92, v93
	global_store_dwordx4 v[68:69], v[28:31], off offset:128 sc1
	global_store_dwordx2 v[108:109], v[90:91], off
	global_load_dwordx4 v[90:93], v[110:111], off
	v_lshl_add_u64 v[102:103], v[94:95], 0, v[78:79]
	v_lshl_add_u64 v[104:105], v[106:107], 0, v[80:81]
	v_lshl_add_u64 v[106:107], v[106:107], 0, v[84:85]
	v_pk_mul_f32 v[28:29], v[28:29], v[28:29]
	v_pk_mul_f32 v[30:31], v[30:31], v[30:31]
	v_add_f32_e32 v28, v28, v29
	v_add_f32_e32 v28, v30, v28
	v_add_f32_e32 v28, v31, v28
	v_add_f32_e32 v28, v60, v28
	s_waitcnt vmcnt(0)
	v_pk_fma_f32 v[24:25], v[24:25], v[44:45], v[90:91]
	v_pk_fma_f32 v[26:27], v[26:27], v[46:47], v[92:93]
	v_pk_mul_f32 v[90:91], v[98:99], v[24:25]
	v_pk_mul_f32 v[92:93], v[100:101], v[26:27]
	v_cvt_pk_bf16_f32 v90, v90, v91
	v_cvt_pk_bf16_f32 v91, v92, v93
	global_store_dwordx4 v[110:111], v[24:27], off sc1
	global_store_dwordx2 v[102:103], v[90:91], off
	global_load_dwordx4 v[90:93], v[104:105], off
	v_lshl_add_u64 v[102:103], v[94:95], 0, v[82:83]
	v_lshl_add_u64 v[94:95], v[94:95], 0, v[74:75]
	s_waitcnt vmcnt(0)
	v_pk_fma_f32 v[20:21], v[20:21], v[44:45], v[90:91]
	v_pk_fma_f32 v[22:23], v[22:23], v[46:47], v[92:93]
	v_pk_mul_f32 v[90:91], v[98:99], v[20:21]
	v_pk_mul_f32 v[92:93], v[100:101], v[22:23]
	v_cvt_pk_bf16_f32 v90, v90, v91
	v_cvt_pk_bf16_f32 v91, v92, v93
	global_store_dwordx4 v[104:105], v[20:23], off sc1
	global_store_dwordx2 v[102:103], v[90:91], off
	global_load_dwordx4 v[90:93], v[106:107], off
	v_lshlrev_b64 v[102:103], 2, v[96:97]
	v_lshl_add_u64 v[104:105], s[42:43], 0, v[102:103]
	v_lshlrev_b32_e32 v96, 1, v96
	s_waitcnt vmcnt(0)
	v_pk_fma_f32 v[16:17], v[16:17], v[44:45], v[90:91]
	v_pk_fma_f32 v[18:19], v[18:19], v[46:47], v[92:93]
	v_pk_mul_f32 v[44:45], v[98:99], v[16:17]
	v_pk_mul_f32 v[46:47], v[100:101], v[18:19]
	v_cvt_pk_bf16_f32 v44, v44, v45
	v_cvt_pk_bf16_f32 v45, v46, v47
	global_store_dwordx4 v[106:107], v[16:19], off sc1
	global_store_dwordx2 v[94:95], v[44:45], off
	global_load_dwordx4 v[44:47], v[104:105], off
	s_nop 0
	global_load_dwordx4 v[90:93], v[68:69], off offset:192
	v_lshl_add_u64 v[94:95], s[40:41], 0, v[102:103]
	global_load_dwordx4 v[98:101], v[94:95], off
	global_load_dwordx4 v[102:105], v[72:73], off offset:192
	v_lshl_add_u64 v[72:73], v[70:71], 0, s[38:39]
	v_lshl_add_u64 v[70:71], v[86:87], 0, v[96:97]
	v_lshl_add_u64 v[76:77], v[72:73], 0, v[76:77]
	v_lshl_add_u64 v[80:81], v[72:73], 0, v[80:81]
	v_lshl_add_u64 v[72:73], v[72:73], 0, v[84:85]
	s_waitcnt vmcnt(2)
	v_pk_fma_f32 v[12:13], v[12:13], v[44:45], v[90:91]
	s_waitcnt vmcnt(1)
	v_pk_add_f32 v[86:87], v[98:99], 1.0 op_sel_hi:[1,0]
	v_pk_add_f32 v[90:91], v[100:101], 1.0 op_sel_hi:[1,0]
	v_pk_fma_f32 v[14:15], v[14:15], v[46:47], v[92:93]
	s_waitcnt vmcnt(0)
	v_pk_mul_f32 v[86:87], v[102:103], v[86:87]
	v_pk_mul_f32 v[90:91], v[104:105], v[90:91]
	global_store_dwordx4 v[68:69], v[12:15], off offset:192 sc1
	v_pk_mul_f32 v[68:69], v[86:87], v[12:13]
	v_pk_mul_f32 v[92:93], v[90:91], v[14:15]
	v_cvt_pk_bf16_f32 v68, v68, v69
	v_cvt_pk_bf16_f32 v69, v92, v93
	global_store_dwordx2 v[70:71], v[68:69], off
	global_load_dwordx4 v[68:71], v[76:77], off
	v_lshl_add_u64 v[92:93], s[22:23], 0, v[96:97]
	v_lshl_add_u64 v[78:79], v[92:93], 0, v[78:79]
	v_pk_mul_f32 v[12:13], v[12:13], v[12:13]
	v_pk_mul_f32 v[14:15], v[14:15], v[14:15]
	v_add_f32_e32 v12, v12, v13
	v_add_f32_e32 v12, v14, v12
	v_add_f32_e32 v12, v15, v12
	v_add_f32_e32 v14, v28, v12
	ds_bpermute_b32 v15, v124, v14
	v_lshlrev_b32_e32 v96, 2, v88
	v_lshl_add_u64 v[12:13], v[92:93], 0, v[74:75]
	s_waitcnt lgkmcnt(0)
	v_add_f32_e32 v14, v14, v15
	ds_bpermute_b32 v15, v125, v14
	s_waitcnt vmcnt(0)
	v_pk_fma_f32 v[8:9], v[8:9], v[44:45], v[68:69]
	v_pk_fma_f32 v[10:11], v[10:11], v[46:47], v[70:71]
	v_pk_mul_f32 v[68:69], v[86:87], v[8:9]
	v_pk_mul_f32 v[70:71], v[90:91], v[10:11]
	v_cvt_pk_bf16_f32 v68, v68, v69
	v_cvt_pk_bf16_f32 v69, v70, v71
	global_store_dwordx4 v[76:77], v[8:11], off sc1
	global_store_dwordx2 v[78:79], v[68:69], off
	global_load_dwordx4 v[68:71], v[80:81], off
	v_lshl_add_u64 v[76:77], v[92:93], 0, v[82:83]
	s_waitcnt vmcnt(0)
	v_pk_fma_f32 v[4:5], v[4:5], v[44:45], v[68:69]
	v_pk_fma_f32 v[6:7], v[6:7], v[46:47], v[70:71]
	v_pk_mul_f32 v[68:69], v[86:87], v[4:5]
	v_pk_mul_f32 v[70:71], v[90:91], v[6:7]
	v_cvt_pk_bf16_f32 v68, v68, v69
	v_cvt_pk_bf16_f32 v69, v70, v71
	global_store_dwordx4 v[80:81], v[4:7], off sc1
	global_store_dwordx2 v[76:77], v[68:69], off
	global_load_dwordx4 v[68:71], v[72:73], off
	s_waitcnt vmcnt(0)
	v_pk_fma_f32 v[0:1], v[0:1], v[44:45], v[68:69]
	v_pk_fma_f32 v[2:3], v[2:3], v[46:47], v[70:71]
	v_pk_mul_f32 v[28:29], v[86:87], v[0:1]
	v_pk_mul_f32 v[30:31], v[90:91], v[2:3]
	v_cvt_pk_bf16_f32 v28, v28, v29
	v_cvt_pk_bf16_f32 v29, v30, v31
	global_store_dwordx4 v[72:73], v[0:3], off sc1
	global_store_dwordx2 v[12:13], v[28:29], off
	v_lshl_add_u64 v[12:13], s[24:25], 0, v[96:97]
	s_and_saveexec_b64 s[40:41], s[10:11]
	s_cbranch_execz .LBB0_1104
	s_waitcnt lgkmcnt(0)
	v_add_f32_e32 v14, v14, v15
	global_atomic_add_f32 v[12:13], v14, off

.LBB0_1181:
	s_and_b64 vcc, exec, s[10:11]
	s_cbranch_vccz .LBB0_1183
	v_cvt_pk_bf16_f32 v3, v8, s0
	ds_write_b16 v174, v3
	v_cvt_pk_bf16_f32 v3, v141, s0
	ds_write_b16 v174, v3 offset:144
	v_cvt_pk_bf16_f32 v3, v10, s0
	ds_write_b16 v174, v3 offset:288
	v_cvt_pk_bf16_f32 v3, v142, s0
	ds_write_b16 v174, v3 offset:432
	v_cvt_pk_bf16_f32 v3, v140, s0
	ds_write_b16 v174, v3 offset:2304
	v_cvt_pk_bf16_f32 v3, v9, s0
	ds_write_b16 v174, v3 offset:2448
	v_cvt_pk_bf16_f32 v3, v14, s0
	ds_write_b16 v174, v3 offset:2592
	v_cvt_pk_bf16_f32 v3, v143, s0
	ds_write_b16 v174, v3 offset:2736
	v_cvt_pk_bf16_f32 v3, v16, s0
	ds_write_b16 v174, v3 offset:4608
	v_cvt_pk_bf16_f32 v3, v157, s0
	ds_write_b16 v174, v3 offset:4752
	v_cvt_pk_bf16_f32 v3, v18, s0
	ds_write_b16 v174, v3 offset:4896
	v_cvt_pk_bf16_f32 v3, v12, s0
	ds_write_b16 v174, v3 offset:5040
	v_cvt_pk_bf16_f32 v3, v156, s0
	ds_write_b16 v174, v3 offset:6912
	v_cvt_pk_bf16_f32 v3, v17, s0
	ds_write_b16 v174, v3 offset:7056
	v_cvt_pk_bf16_f32 v3, v22, s0
	ds_write_b16 v174, v3 offset:7200
	v_cvt_pk_bf16_f32 v3, v13, s0
	ds_write_b16 v174, v3 offset:7344
	v_cvt_pk_bf16_f32 v3, v24, s0
	ds_write_b16 v174, v3 offset:8
	v_cvt_pk_bf16_f32 v3, v21, s0
	ds_write_b16 v174, v3 offset:152
	v_cvt_pk_bf16_f32 v3, v26, s0
	ds_write_b16 v174, v3 offset:296
	v_cvt_pk_bf16_f32 v3, v152, s0
	ds_write_b16 v174, v3 offset:440
	v_cvt_pk_bf16_f32 v3, v20, s0
	ds_write_b16 v174, v3 offset:2312
	v_cvt_pk_bf16_f32 v3, v25, s0
	ds_write_b16 v174, v3 offset:2456
	v_cvt_pk_bf16_f32 v3, v30, s0
	ds_write_b16 v174, v3 offset:2600
	v_cvt_pk_bf16_f32 v3, v153, s0
	ds_write_b16 v174, v3 offset:2744
	v_cvt_pk_bf16_f32 v3, v32, s0
	ds_write_b16 v174, v3 offset:4616
	v_cvt_pk_bf16_f32 v3, v163, s0
	ds_write_b16 v174, v3 offset:4760
	v_cvt_pk_bf16_f32 v3, v34, s0
	ds_write_b16 v174, v3 offset:4904
	v_cvt_pk_bf16_f32 v3, v28, s0
	ds_write_b16 v174, v3 offset:5048
	v_cvt_pk_bf16_f32 v3, v162, s0
	ds_write_b16 v174, v3 offset:6920
	v_cvt_pk_bf16_f32 v3, v33, s0
	ds_write_b16 v174, v3 offset:7064
	v_cvt_pk_bf16_f32 v3, v38, s0
	ds_write_b16 v174, v3 offset:7208
	v_cvt_pk_bf16_f32 v3, v29, s0
	ds_write_b16 v174, v3 offset:7352
	v_cvt_pk_bf16_f32 v3, v40, s0
	ds_write_b16 v174, v3 offset:64
	v_cvt_pk_bf16_f32 v3, v161, s0
	ds_write_b16 v174, v3 offset:208
	v_cvt_pk_bf16_f32 v3, v42, s0
	ds_write_b16 v174, v3 offset:352
	v_cvt_pk_bf16_f32 v3, v36, s0
	ds_write_b16 v174, v3 offset:496
	v_cvt_pk_bf16_f32 v3, v160, s0
	ds_write_b16 v174, v3 offset:2368
	v_cvt_pk_bf16_f32 v3, v41, s0
	ds_write_b16 v174, v3 offset:2512
	v_cvt_pk_bf16_f32 v3, v46, s0
	ds_write_b16 v174, v3 offset:2656
	v_cvt_pk_bf16_f32 v3, v37, s0
	ds_write_b16 v174, v3 offset:2800
	v_cvt_pk_bf16_f32 v3, v48, s0
	ds_write_b16 v174, v3 offset:4672
	v_cvt_pk_bf16_f32 v3, v167, s0
	ds_write_b16 v174, v3 offset:4816
	v_cvt_pk_bf16_f32 v3, v50, s0
	ds_write_b16 v174, v3 offset:4960
	v_cvt_pk_bf16_f32 v3, v44, s0
	ds_write_b16 v174, v3 offset:5104
	v_cvt_pk_bf16_f32 v3, v166, s0
	ds_write_b16 v174, v3 offset:6976
	v_cvt_pk_bf16_f32 v3, v49, s0
	ds_write_b16 v174, v3 offset:7120
	v_cvt_pk_bf16_f32 v3, v54, s0
	ds_write_b16 v174, v3 offset:7264
	v_cvt_pk_bf16_f32 v3, v45, s0
	ds_write_b16 v174, v3 offset:7408
	v_cvt_pk_bf16_f32 v3, v56, s0
	ds_write_b16 v174, v3 offset:72
	v_cvt_pk_bf16_f32 v3, v53, s0
	ds_write_b16 v174, v3 offset:216
	v_cvt_pk_bf16_f32 v3, v58, s0
	ds_write_b16 v174, v3 offset:360
	v_cvt_pk_bf16_f32 v3, v164, s0
	ds_write_b16 v174, v3 offset:504
	v_cvt_pk_bf16_f32 v3, v52, s0
	ds_write_b16 v174, v3 offset:2376
	v_cvt_pk_bf16_f32 v3, v57, s0
	ds_write_b16 v174, v3 offset:2520
	v_cvt_pk_bf16_f32 v3, v2, s0
	ds_write_b16 v174, v3 offset:2664
	v_cvt_pk_bf16_f32 v3, v165, s0
	ds_write_b16 v174, v3 offset:2808
	v_cvt_pk_bf16_f32 v3, v60, s0
	ds_write_b16 v174, v3 offset:4680
	v_cvt_pk_bf16_f32 v3, v1, s0
	ds_write_b16 v174, v3 offset:4824
	v_cvt_pk_bf16_f32 v3, v62, s0
	ds_write_b16 v174, v3 offset:4968
	v_cvt_pk_bf16_f32 v3, v168, s0
	ds_write_b16 v174, v3 offset:5112
	v_cvt_pk_bf16_f32 v3, v0, s0
	ds_write_b16 v174, v3 offset:6984
	v_cvt_pk_bf16_f32 v3, v61, s0
	ds_write_b16 v174, v3 offset:7128
	v_cvt_pk_bf16_f32 v3, v6, s0
	ds_write_b16 v174, v3 offset:7272
	v_cvt_pk_bf16_f32 v3, v169, s0
	ds_write_b16 v174, v3 offset:7416
	v_add_u32_e32 v3, 0xfffffb00, v130
	s_waitcnt lgkmcnt(0)
	s_lshl_b32 s36, s46, 1
	ds_read_b128 v[64:67], v184
	v_or_b32_e32 v7, v3, v175
	v_lshl_add_u64 v[4:5], v[136:137], 0, s[36:37]
	v_lshlrev_b32_e32 v68, 14, v7
	v_mov_b32_e32 v69, v131
	v_lshl_add_u64 v[72:73], v[4:5], 0, v[68:69]
	ds_read_b128 v[68:71], v184 offset:1152
	v_or_b32_e32 v7, v3, v176
	s_waitcnt lgkmcnt(1)
	global_store_dwordx4 v[72:73], v[64:67], off sc1
	v_mov_b32_e32 v63, v168
	v_mov_b32_e32 v59, v164
	v_lshlrev_b32_e32 v64, 14, v7
	v_mov_b32_e32 v65, v131
	v_lshl_add_u64 v[64:65], v[4:5], 0, v[64:65]
	s_waitcnt lgkmcnt(0)
	global_store_dwordx4 v[64:65], v[68:71], off sc1
	ds_read_b128 v[64:67], v184 offset:2304
	v_or_b32_e32 v7, v3, v177
	v_lshlrev_b32_e32 v68, 14, v7
	v_mov_b32_e32 v69, v131
	v_lshl_add_u64 v[72:73], v[4:5], 0, v[68:69]
	ds_read_b128 v[68:71], v184 offset:3456
	v_or_b32_e32 v7, v3, v178
	s_waitcnt lgkmcnt(1)
	global_store_dwordx4 v[72:73], v[64:67], off sc1
	v_mov_b32_e32 v55, v45
	v_mov_b32_e32 v51, v44
	v_lshlrev_b32_e32 v64, 14, v7
	v_mov_b32_e32 v65, v131
	v_lshl_add_u64 v[64:65], v[4:5], 0, v[64:65]
	s_waitcnt lgkmcnt(0)
	global_store_dwordx4 v[64:65], v[68:71], off sc1
	ds_read_b128 v[64:67], v184 offset:4608
	v_or_b32_e32 v7, v3, v179
	v_lshlrev_b32_e32 v68, 14, v7
	v_mov_b32_e32 v69, v131
	v_lshl_add_u64 v[72:73], v[4:5], 0, v[68:69]
	ds_read_b128 v[68:71], v184 offset:5760
	v_or_b32_e32 v7, v3, v180
	s_waitcnt lgkmcnt(1)
	global_store_dwordx4 v[72:73], v[64:67], off sc1
	v_mov_b32_e32 v47, v37
	v_mov_b32_e32 v43, v36
	v_lshlrev_b32_e32 v64, 14, v7
	v_mov_b32_e32 v65, v131
	v_lshl_add_u64 v[64:65], v[4:5], 0, v[64:65]
	s_waitcnt lgkmcnt(0)
	global_store_dwordx4 v[64:65], v[68:71], off sc1
	ds_read_b128 v[64:67], v184 offset:6912
	v_or_b32_e32 v7, v3, v181
	v_lshlrev_b32_e32 v68, 14, v7
	v_mov_b32_e32 v69, v131
	v_lshl_add_u64 v[72:73], v[4:5], 0, v[68:69]
	ds_read_b128 v[68:71], v184 offset:8064
	v_or_b32_e32 v3, v3, v182
	s_waitcnt lgkmcnt(1)
	global_store_dwordx4 v[72:73], v[64:67], off sc1
	v_mov_b32_e32 v7, v169
	v_mov_b32_e32 v39, v29
	v_lshlrev_b32_e32 v64, 14, v3
	v_mov_b32_e32 v65, v131
	v_lshl_add_u64 v[4:5], v[4:5], 0, v[64:65]
	v_mov_b32_e32 v3, v165
	v_mov_b32_e32 v35, v28
	v_mov_b32_e32 v31, v153
	v_mov_b32_e32 v27, v152
	v_mov_b32_e32 v23, v13
	v_mov_b32_e32 v19, v12
	v_mov_b32_e32 v15, v143
	v_mov_b32_e32 v11, v142
	s_waitcnt lgkmcnt(0)
	global_store_dwordx4 v[4:5], v[68:71], off sc1
	v_mov_b32_e32 v4, v0
	v_mov_b32_e32 v5, v61
	v_mov_b32_e32 v61, v1
	v_mov_b32_e32 v0, v52
	v_mov_b32_e32 v1, v57
	v_mov_b32_e32 v57, v53
	v_mov_b32_e32 v52, v166
	v_mov_b32_e32 v53, v49
	v_mov_b32_e32 v49, v167
	v_mov_b32_e32 v44, v160
	v_mov_b32_e32 v45, v41
	v_mov_b32_e32 v41, v161
	v_mov_b32_e32 v36, v162
	v_mov_b32_e32 v37, v33
	v_mov_b32_e32 v33, v163
	v_mov_b32_e32 v28, v20
	v_mov_b32_e32 v29, v25
	v_mov_b32_e32 v25, v21
	v_mov_b32_e32 v20, v156
	v_mov_b32_e32 v21, v17
	v_mov_b32_e32 v17, v157
	v_mov_b32_e32 v12, v140
	v_mov_b32_e32 v13, v9
	v_mov_b32_e32 v9, v141
	v_mov_b64_e32 v[66:67], v[10:11]
	v_mov_b64_e32 v[70:71], v[14:15]
	v_mov_b64_e32 v[74:75], v[18:19]
	v_mov_b64_e32 v[78:79], v[22:23]
	v_mov_b64_e32 v[82:83], v[26:27]
	v_mov_b64_e32 v[86:87], v[30:31]
	v_mov_b64_e32 v[90:91], v[34:35]
	v_mov_b64_e32 v[94:95], v[38:39]
	v_mov_b64_e32 v[98:99], v[42:43]
	v_mov_b64_e32 v[102:103], v[46:47]
	v_mov_b64_e32 v[106:107], v[50:51]
	v_mov_b64_e32 v[110:111], v[54:55]
	v_mov_b64_e32 v[114:115], v[58:59]
	v_mov_b64_e32 v[118:119], v[2:3]
	v_mov_b64_e32 v[122:123], v[62:63]
	v_mov_b64_e32 v[126:127], v[6:7]
	v_mov_b64_e32 v[64:65], v[8:9]
	v_mov_b64_e32 v[68:69], v[12:13]
	v_mov_b64_e32 v[72:73], v[16:17]
	v_mov_b64_e32 v[76:77], v[20:21]
	v_mov_b64_e32 v[80:81], v[24:25]
	v_mov_b64_e32 v[84:85], v[28:29]
	v_mov_b64_e32 v[88:89], v[32:33]
	v_mov_b64_e32 v[92:93], v[36:37]
	v_mov_b64_e32 v[96:97], v[40:41]
	v_mov_b64_e32 v[100:101], v[44:45]
	v_mov_b64_e32 v[104:105], v[48:49]
	v_mov_b64_e32 v[108:109], v[52:53]
	v_mov_b64_e32 v[112:113], v[56:57]
	v_mov_b64_e32 v[116:117], v[0:1]
	v_mov_b64_e32 v[120:121], v[60:61]
	v_mov_b64_e32 v[124:125], v[4:5]

.LBB0_1345:
	s_add_i32 s25, s28, 2
	s_cmp_lt_u32 s28, 14
	s_cselect_b32 s30, s24, 0x700
	s_min_u32 s18, s28, 12
	s_lshl_b32 s18, s18, 7
	s_addk_i32 s24, 0x100
	s_ashr_i32 s31, s30, 31
	s_addk_i32 s18, 0x180
	s_cmp_gt_u32 s28, 13
	s_setprio 1
	ds_read_b128 v[124:127], v119 offset:32768
	ds_read_b128 v[132:135], v119 offset:34816
	ds_read_b128 v[128:131], v118
	ds_read_b128 v[136:139], v118 offset:2048
	ds_read_b128 v[140:143], v118 offset:4096
	ds_read_b128 v[152:155], v118 offset:6144
	v_add_u32_e32 v99, s30, v96
	v_add_u32_e32 v146, 0x10000, v99
	s_waitcnt lgkmcnt(3)
	v_mfma_f32_16x16x32_bf16 v[8:11], v[124:127], v[128:131], v[8:11]
	ds_read_b128 v[156:159], v119 offset:36864
	v_mfma_f32_16x16x32_bf16 v[4:7], v[132:135], v[128:131], v[4:7]
	ds_read_b128 v[160:163], v119 offset:38912
	s_waitcnt lgkmcnt(1)
	v_mfma_f32_16x16x32_bf16 v[12:15], v[156:159], v[128:131], v[12:15]
	s_waitcnt lgkmcnt(0)
	v_mfma_f32_16x16x32_bf16 v[0:3], v[160:163], v[128:131], v[0:3]
	v_lshl_add_u64 v[128:129], v[100:101], 0, s[30:31]
	global_load_dwordx4 v[128:131], v[128:129], off
	ds_read_b128 v[164:167], v120
	v_mfma_f32_16x16x32_bf16 v[44:47], v[124:127], v[136:139], v[44:47]
	v_mfma_f32_16x16x32_bf16 v[36:39], v[132:135], v[136:139], v[36:39]
	global_load_dwordx4 v[168:171], v146, s[10:11]
	ds_read_b128 v[172:175], v120 offset:2048
	v_mfma_f32_16x16x32_bf16 v[20:23], v[156:159], v[136:139], v[20:23]
	v_mfma_f32_16x16x32_bf16 v[16:19], v[160:163], v[136:139], v[16:19]
	v_add_u32_e32 v136, 0x20000, v99
	v_add_u32_e32 v99, 0x30000, v99
	global_load_dwordx4 v[136:139], v136, s[10:11]
	ds_read_b128 v[176:179], v120 offset:4096
	v_mfma_f32_16x16x32_bf16 v[52:55], v[124:127], v[140:143], v[52:55]
	v_mfma_f32_16x16x32_bf16 v[48:51], v[132:135], v[140:143], v[48:51]
	global_load_dwordx4 v[180:183], v99, s[10:11]
	v_add_u32_e32 v99, s30, v98
	ds_read_b128 v[184:187], v120 offset:6144
	v_mfma_f32_16x16x32_bf16 v[32:35], v[156:159], v[140:143], v[32:35]
	v_add_u32_e32 v146, 0x20000, v99
	v_mfma_f32_16x16x32_bf16 v[24:27], v[160:163], v[140:143], v[24:27]
	global_load_dwordx4 v[140:143], v99, s[8:9]
	ds_read_b128 v[188:191], v121 offset:32768
	v_mfma_f32_16x16x32_bf16 v[60:63], v[124:127], v[152:155], v[60:63]
	v_add_u32_e32 v124, 0x10000, v99
	v_add_u32_e32 v99, 0x30000, v99
	v_mfma_f32_16x16x32_bf16 v[56:59], v[132:135], v[152:155], v[56:59]
	global_load_dwordx4 v[124:127], v124, s[8:9]
	ds_read_b128 v[132:135], v121 offset:34816
	v_mfma_f32_16x16x32_bf16 v[40:43], v[156:159], v[152:155], v[40:43]
	v_mfma_f32_16x16x32_bf16 v[28:31], v[160:163], v[152:155], v[28:31]
	global_load_dwordx4 v[152:155], v146, s[8:9]
	ds_read_b128 v[156:159], v121 offset:36864
	s_waitcnt lgkmcnt(2)
	v_mfma_f32_16x16x32_bf16 v[8:11], v[188:191], v[164:167], v[8:11]
	s_waitcnt lgkmcnt(1)
	v_mfma_f32_16x16x32_bf16 v[4:7], v[132:135], v[164:167], v[4:7]
	global_load_dwordx4 v[160:163], v99, s[8:9]
	ds_read_b128 v[192:195], v121 offset:38912
	s_waitcnt lgkmcnt(1)
	v_mfma_f32_16x16x32_bf16 v[12:15], v[156:159], v[164:167], v[12:15]
	s_waitcnt lgkmcnt(0)
	v_mfma_f32_16x16x32_bf16 v[0:3], v[192:195], v[164:167], v[0:3]
	s_waitcnt vmcnt(14)
	ds_write_b128 v117, v[64:67] offset:16384
	v_mfma_f32_16x16x32_bf16 v[44:47], v[188:191], v[172:175], v[44:47]
	v_mfma_f32_16x16x32_bf16 v[36:39], v[132:135], v[172:175], v[36:39]
	s_waitcnt vmcnt(13)
	ds_write_b128 v117, v[68:71] offset:20480
	v_mfma_f32_16x16x32_bf16 v[20:23], v[156:159], v[172:175], v[20:23]
	v_mfma_f32_16x16x32_bf16 v[16:19], v[192:195], v[172:175], v[16:19]
	s_waitcnt vmcnt(12)
	ds_write_b128 v117, v[72:75] offset:24576
	v_mfma_f32_16x16x32_bf16 v[52:55], v[188:191], v[176:179], v[52:55]
	v_mfma_f32_16x16x32_bf16 v[48:51], v[132:135], v[176:179], v[48:51]
	s_waitcnt vmcnt(11)
	ds_write_b128 v117, v[80:83] offset:28672
	v_mfma_f32_16x16x32_bf16 v[32:35], v[156:159], v[176:179], v[32:35]
	v_mfma_f32_16x16x32_bf16 v[24:27], v[192:195], v[176:179], v[24:27]
	ds_write_b128 v117, v[76:79] offset:49152
	v_mfma_f32_16x16x32_bf16 v[60:63], v[188:191], v[184:187], v[60:63]
	v_mfma_f32_16x16x32_bf16 v[56:59], v[132:135], v[184:187], v[56:59]
	s_waitcnt vmcnt(10)
	ds_write_b128 v117, v[84:87] offset:53248
	v_mfma_f32_16x16x32_bf16 v[40:43], v[156:159], v[184:187], v[40:43]
	v_mfma_f32_16x16x32_bf16 v[28:31], v[192:195], v[184:187], v[28:31]
	s_waitcnt vmcnt(9)
	ds_write_b128 v117, v[88:91] offset:57344
	s_waitcnt vmcnt(8)
	ds_write_b128 v117, v[92:95] offset:61440
	s_setprio 0
	s_waitcnt lgkmcnt(0)
	s_barrier
	s_setprio 1
	ds_read_b128 v[84:87], v119 offset:49152
	ds_read_b128 v[88:91], v119 offset:51200
	ds_read_b128 v[64:67], v118 offset:16384
	ds_read_b128 v[72:75], v118 offset:18432
	ds_read_b128 v[76:79], v118 offset:20480
	ds_read_b128 v[92:95], v118 offset:22528
	v_lshl_add_u64 v[68:69], v[110:111], 0, s[18:19]
	v_lshl_add_u64 v[80:81], v[114:115], 0, s[18:19]
	s_waitcnt lgkmcnt(3)
	v_mfma_f32_16x16x32_bf16 v[8:11], v[84:87], v[64:67], v[8:11]
	ds_read_b128 v[132:135], v119 offset:53248
	v_mfma_f32_16x16x32_bf16 v[4:7], v[88:91], v[64:67], v[4:7]
	ds_read_b128 v[156:159], v119 offset:55296
	s_waitcnt lgkmcnt(1)
	v_mfma_f32_16x16x32_bf16 v[12:15], v[132:135], v[64:67], v[12:15]
	s_waitcnt lgkmcnt(0)
	v_mfma_f32_16x16x32_bf16 v[0:3], v[156:159], v[64:67], v[0:3]
	v_lshl_add_u64 v[64:65], v[100:101], 0, s[18:19]
	global_load_dwordx4 v[64:67], v[64:65], off
	ds_read_b128 v[164:167], v120 offset:16384
	v_mfma_f32_16x16x32_bf16 v[44:47], v[84:87], v[72:75], v[44:47]
	v_mfma_f32_16x16x32_bf16 v[36:39], v[88:91], v[72:75], v[36:39]
	global_load_dwordx4 v[68:71], v[68:69], off
	ds_read_b128 v[172:175], v120 offset:18432
	v_mfma_f32_16x16x32_bf16 v[20:23], v[132:135], v[72:75], v[20:23]
	v_mfma_f32_16x16x32_bf16 v[16:19], v[156:159], v[72:75], v[16:19]
	v_lshl_add_u64 v[72:73], v[112:113], 0, s[18:19]
	global_load_dwordx4 v[72:75], v[72:73], off
	ds_read_b128 v[176:179], v120 offset:20480
	v_mfma_f32_16x16x32_bf16 v[52:55], v[84:87], v[76:79], v[52:55]
	v_mfma_f32_16x16x32_bf16 v[48:51], v[88:91], v[76:79], v[48:51]
	global_load_dwordx4 v[80:83], v[80:81], off
	ds_read_b128 v[184:187], v120 offset:22528
	v_mfma_f32_16x16x32_bf16 v[32:35], v[132:135], v[76:79], v[32:35]
	v_mfma_f32_16x16x32_bf16 v[24:27], v[156:159], v[76:79], v[24:27]
	v_lshl_add_u64 v[76:77], v[102:103], 0, s[18:19]
	global_load_dwordx4 v[76:79], v[76:77], off
	ds_read_b128 v[188:191], v121 offset:49152
	v_mfma_f32_16x16x32_bf16 v[60:63], v[84:87], v[92:95], v[60:63]
	v_lshl_add_u64 v[84:85], v[104:105], 0, s[18:19]
	v_mfma_f32_16x16x32_bf16 v[56:59], v[88:91], v[92:95], v[56:59]
	global_load_dwordx4 v[84:87], v[84:85], off
	ds_read_b128 v[192:195], v121 offset:51200
	v_lshl_add_u64 v[88:89], v[106:107], 0, s[18:19]
	v_mfma_f32_16x16x32_bf16 v[40:43], v[132:135], v[92:95], v[40:43]
	v_mfma_f32_16x16x32_bf16 v[28:31], v[156:159], v[92:95], v[28:31]
	v_lshl_add_u64 v[92:93], v[108:109], 0, s[18:19]
	global_load_dwordx4 v[88:91], v[88:89], off
	ds_read_b128 v[132:135], v121 offset:53248
	s_waitcnt lgkmcnt(2)
	v_mfma_f32_16x16x32_bf16 v[8:11], v[188:191], v[164:167], v[8:11]
	s_waitcnt lgkmcnt(1)
	v_mfma_f32_16x16x32_bf16 v[4:7], v[192:195], v[164:167], v[4:7]
	global_load_dwordx4 v[92:95], v[92:93], off
	ds_read_b128 v[156:159], v121 offset:55296
	s_waitcnt lgkmcnt(1)
	v_mfma_f32_16x16x32_bf16 v[12:15], v[132:135], v[164:167], v[12:15]
	s_waitcnt lgkmcnt(0)
	v_mfma_f32_16x16x32_bf16 v[0:3], v[156:159], v[164:167], v[0:3]
	s_waitcnt vmcnt(15)
	ds_write_b128 v117, v[128:131]
	v_mfma_f32_16x16x32_bf16 v[44:47], v[188:191], v[172:175], v[44:47]
	v_mfma_f32_16x16x32_bf16 v[36:39], v[192:195], v[172:175], v[36:39]
	s_waitcnt vmcnt(14)
	ds_write_b128 v117, v[168:171] offset:4096
	v_mfma_f32_16x16x32_bf16 v[20:23], v[132:135], v[172:175], v[20:23]
	v_mfma_f32_16x16x32_bf16 v[16:19], v[156:159], v[172:175], v[16:19]
	s_waitcnt vmcnt(13)
	ds_write_b128 v117, v[136:139] offset:8192
	v_mfma_f32_16x16x32_bf16 v[52:55], v[188:191], v[176:179], v[52:55]
	v_mfma_f32_16x16x32_bf16 v[48:51], v[192:195], v[176:179], v[48:51]
	s_waitcnt vmcnt(12)
	ds_write_b128 v117, v[180:183] offset:12288
	v_mfma_f32_16x16x32_bf16 v[32:35], v[132:135], v[176:179], v[32:35]
	v_mfma_f32_16x16x32_bf16 v[24:27], v[156:159], v[176:179], v[24:27]
	s_waitcnt vmcnt(11)
	ds_write_b128 v117, v[140:143] offset:32768
	v_mfma_f32_16x16x32_bf16 v[60:63], v[188:191], v[184:187], v[60:63]
	v_mfma_f32_16x16x32_bf16 v[56:59], v[192:195], v[184:187], v[56:59]
	s_waitcnt vmcnt(10)
	ds_write_b128 v117, v[124:127] offset:36864
	v_mfma_f32_16x16x32_bf16 v[40:43], v[132:135], v[184:187], v[40:43]
	v_mfma_f32_16x16x32_bf16 v[28:31], v[156:159], v[184:187], v[28:31]
	s_waitcnt vmcnt(9)
	ds_write_b128 v117, v[152:155] offset:40960
	s_waitcnt vmcnt(8)
	ds_write_b128 v117, v[160:163] offset:45056
	s_setprio 0
	s_mov_b32 s28, s25
	s_waitcnt lgkmcnt(0)
	s_barrier
	s_cbranch_scc0 .LBB0_1345
	s_add_i32 s18, s26, 0xfffff000
	s_ashr_i32 s18, s18, 10
	s_add_i32 s18, s18, 16
	s_and_b64 s[24:25], s[2:3], exec
	s_cselect_b32 s18, 15, s18
	s_mul_hi_u32 s24, s18, 0x3000
	s_mulk_i32 s18, 0x3000
	s_add_u32 s18, s6, s18
	v_or_b32_e32 v96, s27, v123
	s_addc_u32 s25, s7, s24
	s_waitcnt vmcnt(7)
	v_lshlrev_b64 v[64:65], 2, v[96:97]
	s_add_u32 s24, s18, 0xf442000
	s_waitcnt vmcnt(0)
	v_lshl_add_u64 v[94:95], s[6:7], 0, v[64:65]
	v_add_lshl_u32 v78, s26, v122, 12
	s_addc_u32 s25, s25, 0
	v_mov_b32_e32 v79, v97
	v_or_b32_e32 v114, 0x10000, v78
	v_mov_b32_e32 v115, v97
	v_or_b32_e32 v160, 0x20000, v78
	v_mov_b32_e32 v161, v97
	v_or_b32_e32 v164, 0x30000, v78
	v_mov_b32_e32 v165, v97
	v_or_b32_e32 v86, 16, v96
	v_mov_b32_e32 v87, v97
	v_lshl_add_u64 v[102:103], v[94:95], 0, 64
	v_or_b32_e32 v110, 32, v96
	v_mov_b32_e32 v111, v97
	v_lshl_add_u64 v[136:137], v[94:95], 0, s[20:21]
	v_or_b32_e32 v96, 48, v96
	v_lshl_add_u64 v[74:75], s[24:25], 0, v[64:65]
	v_lshl_add_u64 v[64:65], v[94:95], 0, v[78:79]
	v_lshl_add_u64 v[146:147], v[94:95], 0, v[114:115]
	v_lshl_add_u64 v[168:169], v[94:95], 0, v[160:161]
	v_lshl_add_u64 v[170:171], v[94:95], 0, v[164:165]
	v_lshl_add_u64 v[90:91], v[86:87], 2, s[24:25]
	v_lshl_add_u64 v[174:175], v[102:103], 0, v[160:161]
	v_lshl_add_u64 v[110:111], v[110:111], 2, s[24:25]
	v_lshl_add_u64 v[178:179], v[136:137], 0, v[114:115]
	v_lshl_add_u64 v[180:181], v[136:137], 0, v[160:161]
	v_lshl_add_u64 v[182:183], v[136:137], 0, v[164:165]
	v_lshl_add_u64 v[140:141], v[96:97], 2, s[24:25]
	v_lshl_add_u64 v[94:95], v[94:95], 0, s[22:23]
	global_load_dwordx4 v[66:69], v[74:75], off
	global_load_dwordx4 v[70:73], v[64:65], off
	v_lshl_add_u64 v[172:173], v[102:103], 0, v[114:115]
	global_load_dwordx4 v[74:77], v[146:147], off
	global_load_dwordx4 v[78:81], v[168:169], off
	global_load_dwordx4 v[82:85], v[170:171], off
	global_load_dwordx4 v[86:89], v[64:65], off offset:64
	s_nop 0
	global_load_dwordx4 v[90:93], v[90:91], off
	s_nop 0
	global_load_dwordx4 v[98:101], v[172:173], off
	v_lshl_add_u64 v[176:177], v[102:103], 0, v[164:165]
	global_load_dwordx4 v[102:105], v[174:175], off
	global_load_dwordx4 v[106:109], v[176:177], off
	s_nop 0
	global_load_dwordx4 v[110:113], v[110:111], off
	s_nop 0
	global_load_dwordx4 v[124:127], v[64:65], off offset:128
	global_load_dwordx4 v[128:131], v[178:179], off
	global_load_dwordx4 v[132:135], v[180:181], off
	global_load_dwordx4 v[136:139], v[182:183], off
	s_nop 0
	global_load_dwordx4 v[140:143], v[140:141], off
	s_nop 0
	global_load_dwordx4 v[152:155], v[64:65], off offset:192
	v_lshl_add_u64 v[114:115], v[94:95], 0, v[114:115]
	global_load_dwordx4 v[156:159], v[114:115], off
	v_lshl_add_u64 v[184:185], v[94:95], 0, v[160:161]
	global_load_dwordx4 v[160:163], v[184:185], off
	v_lshl_add_u64 v[94:95], v[94:95], 0, v[164:165]
	global_load_dwordx4 v[164:167], v[94:95], off
	s_add_i32 s97, s97, s96
	s_cmp_gt_u32 s97, 63
	s_waitcnt vmcnt(18)
	v_pk_fma_f32 v[8:9], v[8:9], v[66:67], v[70:71]
	v_pk_fma_f32 v[10:11], v[10:11], v[68:69], v[72:73]
	s_waitcnt vmcnt(17)
	v_pk_fma_f32 v[44:45], v[44:45], v[66:67], v[74:75]
	v_pk_fma_f32 v[46:47], v[46:47], v[68:69], v[76:77]
	s_waitcnt vmcnt(13)
	v_pk_fma_f32 v[4:5], v[4:5], v[90:91], v[86:87]
	v_pk_fma_f32 v[6:7], v[6:7], v[92:93], v[88:89]
	v_pk_fma_f32 v[52:53], v[52:53], v[66:67], v[78:79]
	v_pk_fma_f32 v[54:55], v[54:55], v[68:69], v[80:81]
	v_pk_fma_f32 v[60:61], v[60:61], v[66:67], v[82:83]
	v_pk_fma_f32 v[62:63], v[62:63], v[68:69], v[84:85]
	s_waitcnt vmcnt(12)
	v_pk_fma_f32 v[36:37], v[36:37], v[90:91], v[98:99]
	v_pk_fma_f32 v[38:39], v[38:39], v[92:93], v[100:101]
	s_waitcnt vmcnt(3)
	v_pk_fma_f32 v[0:1], v[0:1], v[140:141], v[152:153]
	v_pk_fma_f32 v[2:3], v[2:3], v[142:143], v[154:155]
	v_pk_fma_f32 v[48:49], v[48:49], v[90:91], v[102:103]
	v_pk_fma_f32 v[50:51], v[50:51], v[92:93], v[104:105]
	v_pk_fma_f32 v[56:57], v[56:57], v[90:91], v[106:107]
	v_pk_fma_f32 v[58:59], v[58:59], v[92:93], v[108:109]
	v_pk_fma_f32 v[12:13], v[12:13], v[110:111], v[124:125]
	v_pk_fma_f32 v[14:15], v[14:15], v[112:113], v[126:127]
	global_store_dwordx4 v[64:65], v[8:11], off sc1
	global_store_dwordx4 v[146:147], v[44:47], off sc1
	global_store_dwordx4 v[168:169], v[52:55], off sc1
	global_store_dwordx4 v[170:171], v[60:63], off sc1
	global_store_dwordx4 v[64:65], v[4:7], off offset:64 sc1
	global_store_dwordx4 v[172:173], v[36:39], off sc1
	global_store_dwordx4 v[174:175], v[48:51], off sc1
	global_store_dwordx4 v[176:177], v[56:59], off sc1
	global_store_dwordx4 v[64:65], v[12:15], off offset:128 sc1
	v_pk_fma_f32 v[4:5], v[20:21], v[110:111], v[128:129]
	v_pk_fma_f32 v[6:7], v[22:23], v[112:113], v[130:131]
	global_store_dwordx4 v[64:65], v[0:3], off offset:192 sc1
	global_store_dwordx4 v[178:179], v[4:7], off sc1
	s_waitcnt vmcnt(13)
	v_pk_fma_f32 v[0:1], v[16:17], v[140:141], v[156:157]
	v_pk_fma_f32 v[2:3], v[18:19], v[142:143], v[158:159]
	v_pk_fma_f32 v[4:5], v[32:33], v[110:111], v[132:133]
	v_pk_fma_f32 v[6:7], v[34:35], v[112:113], v[134:135]
	global_store_dwordx4 v[114:115], v[0:3], off sc1
	global_store_dwordx4 v[180:181], v[4:7], off sc1
	s_waitcnt vmcnt(14)
	v_pk_fma_f32 v[0:1], v[24:25], v[140:141], v[160:161]
	v_pk_fma_f32 v[2:3], v[26:27], v[142:143], v[162:163]
	v_pk_fma_f32 v[4:5], v[40:41], v[110:111], v[136:137]
	v_pk_fma_f32 v[6:7], v[42:43], v[112:113], v[138:139]
	global_store_dwordx4 v[184:185], v[0:3], off sc1
	global_store_dwordx4 v[182:183], v[4:7], off sc1
	s_waitcnt vmcnt(15)
	v_pk_fma_f32 v[0:1], v[28:29], v[140:141], v[164:165]
	v_pk_fma_f32 v[2:3], v[30:31], v[142:143], v[166:167]
	global_store_dwordx4 v[94:95], v[0:3], off sc1
	s_cbranch_scc0 .LBB0_1344
